# static s_setprio 1 for younger wave half (waves 4-7) in GEMM K-loops, per-segment setprio removed; on top of MFMA order + SGPR-base LDS-DMA
# baseline (speedup 1.0000x reference)
;     __device__ __forceinline__ bool next(int i, Unit& u) const { if (i > 0 || c >= nitems) return false; u.pm = 64; u.pn = c % npn; u.k0 = (c / npn) * kslice; return true; }
; template <class Epi, class Sched, bool ALIGN_EPI = false, bool SP2 = false>
; __device__ __forceinline__ void gemm_phase(PG8_LAS unsigned char* lds, const Gemm g, const Sched& S, const Epi& E) {
;     ...
;         const bool has_next = S.next(ui + 1, nxt);
;         const char* nA = has_next ? (const char*)g.A + (size_t)nxt.pm * tstep + (size_t)nxt.k0 * 2 : cA; const char* nB = has_next ? (const char*)g.Bt + (size_t)nxt.pn * tstep + (size_t)nxt.k0 * 2 : cB;
;     ...
; #pragma unroll
;         for (int a = 0; a < 2; ++a)
; #pragma unroll
;             for (int b = 0; b < 2; ++b)
; #pragma unroll
;                 for (int m = 0; m < 4; ++m)
; #pragma unroll
;                     for (int n = 0; n < 2; ++n) acc[a][b][m][n] = (f32x4){0.f, 0.f, 0.f, 0.f};
;         cur = nxt; cA = nA; cB = nB; ++ui;
.LBB0_191:
	s_ashr_i32 s19, s18, 31
	s_lshl_b64 s[26:27], s[18:19], 20
	s_add_u32 s26, s3, s26
	s_addc_u32 s27, s33, s27
	s_and_b64 s[34:35], s[4:5], exec
	s_cselect_b32 s19, s27, s67
	s_cselect_b32 s50, s26, s66
	s_ashr_i32 s17, s16, 31
	s_lshl_b64 s[34:35], s[16:17], 20
	s_add_u32 s34, s6, s34
	s_addc_u32 s35, s7, s35
	s_and_b64 s[52:53], s[4:5], exec
	s_cselect_b32 s17, s35, s69
	s_cselect_b32 s51, s34, s68
	s_add_u32 s66, s66, 0x80080
	s_addc_u32 s67, s67, 0
	s_add_u32 s52, s68, 0x100
	v_mov_b32_e32 v0, 0
	s_addc_u32 s53, s69, 0
	s_mov_b32 s54, -2
	v_mov_b32_e32 v1, v0
	v_mov_b32_e32 v2, v0
	v_mov_b32_e32 v3, v0
	v_mov_b32_e32 v8, v0
	v_mov_b32_e32 v9, v0
	v_mov_b32_e32 v10, v0
	v_mov_b32_e32 v11, v0
	v_mov_b32_e32 v16, v0
	v_mov_b32_e32 v17, v0
	v_mov_b32_e32 v18, v0
	v_mov_b32_e32 v19, v0
	v_mov_b32_e32 v24, v0
	v_mov_b32_e32 v25, v0
	v_mov_b32_e32 v26, v0
	v_mov_b32_e32 v27, v0
	v_mov_b32_e32 v32, v0
	v_mov_b32_e32 v33, v0
	v_mov_b32_e32 v34, v0
	v_mov_b32_e32 v35, v0
	v_mov_b32_e32 v40, v0
	v_mov_b32_e32 v41, v0
	v_mov_b32_e32 v42, v0
	v_mov_b32_e32 v43, v0
	v_mov_b32_e32 v48, v0
	v_mov_b32_e32 v49, v0
	v_mov_b32_e32 v50, v0
	v_mov_b32_e32 v51, v0
	v_mov_b32_e32 v56, v0
	v_mov_b32_e32 v57, v0
	v_mov_b32_e32 v58, v0
	v_mov_b32_e32 v59, v0
	v_mov_b32_e32 v4, v0
	v_mov_b32_e32 v5, v0
	v_mov_b32_e32 v6, v0
	v_mov_b32_e32 v7, v0
	v_mov_b32_e32 v12, v0
	v_mov_b32_e32 v13, v0
	v_mov_b32_e32 v14, v0
	v_mov_b32_e32 v15, v0
	v_mov_b32_e32 v20, v0
	v_mov_b32_e32 v21, v0
	v_mov_b32_e32 v22, v0
	v_mov_b32_e32 v23, v0
	v_mov_b32_e32 v28, v0
	v_mov_b32_e32 v29, v0
	v_mov_b32_e32 v30, v0
	v_mov_b32_e32 v31, v0
	v_mov_b32_e32 v36, v0
	v_mov_b32_e32 v37, v0
	v_mov_b32_e32 v38, v0
	v_mov_b32_e32 v39, v0
	v_mov_b32_e32 v44, v0
	v_mov_b32_e32 v45, v0
	v_mov_b32_e32 v46, v0
	v_mov_b32_e32 v47, v0
	v_mov_b32_e32 v52, v0
	v_mov_b32_e32 v53, v0
	v_mov_b32_e32 v54, v0
	v_mov_b32_e32 v55, v0
	v_mov_b32_e32 v60, v0
	v_mov_b32_e32 v61, v0
	v_mov_b32_e32 v62, v0
	v_mov_b32_e32 v63, v0
	v_mov_b32_e32 v64, v0
	v_mov_b32_e32 v65, v0
	v_mov_b32_e32 v66, v0
	v_mov_b32_e32 v67, v0
	v_mov_b32_e32 v72, v0
	v_mov_b32_e32 v73, v0
	v_mov_b32_e32 v74, v0
	v_mov_b32_e32 v75, v0
	v_mov_b32_e32 v80, v0
	v_mov_b32_e32 v81, v0
	v_mov_b32_e32 v82, v0
	v_mov_b32_e32 v83, v0
	v_mov_b32_e32 v88, v0
	v_mov_b32_e32 v89, v0
	v_mov_b32_e32 v90, v0
	v_mov_b32_e32 v91, v0
	v_mov_b32_e32 v96, v0
	v_mov_b32_e32 v97, v0
	v_mov_b32_e32 v98, v0
	v_mov_b32_e32 v99, v0
	v_mov_b32_e32 v104, v0
	v_mov_b32_e32 v105, v0
	v_mov_b32_e32 v106, v0
	v_mov_b32_e32 v107, v0
	v_mov_b32_e32 v112, v0
	v_mov_b32_e32 v113, v0
	v_mov_b32_e32 v114, v0
	v_mov_b32_e32 v115, v0
	v_mov_b32_e32 v120, v0
	v_mov_b32_e32 v121, v0
	v_mov_b32_e32 v122, v0
	v_mov_b32_e32 v123, v0
	v_mov_b32_e32 v68, v0
	v_mov_b32_e32 v69, v0
	v_mov_b32_e32 v70, v0
	v_mov_b32_e32 v71, v0
	v_mov_b32_e32 v76, v0
	v_mov_b32_e32 v77, v0
	v_mov_b32_e32 v78, v0
	v_mov_b32_e32 v79, v0
	v_mov_b32_e32 v84, v0
	v_mov_b32_e32 v85, v0
	v_mov_b32_e32 v86, v0
	v_mov_b32_e32 v87, v0
	v_mov_b32_e32 v92, v0
	v_mov_b32_e32 v93, v0
	v_mov_b32_e32 v94, v0
	v_mov_b32_e32 v95, v0
	v_mov_b32_e32 v100, v0
	v_mov_b32_e32 v101, v0
	v_mov_b32_e32 v102, v0
	v_mov_b32_e32 v103, v0
	v_mov_b32_e32 v108, v0
	v_mov_b32_e32 v109, v0
	v_mov_b32_e32 v110, v0
	v_mov_b32_e32 v111, v0
	v_mov_b32_e32 v116, v0
	v_mov_b32_e32 v117, v0
	v_mov_b32_e32 v118, v0
	v_mov_b32_e32 v119, v0
	v_mov_b32_e32 v124, v0
	v_mov_b32_e32 v125, v0
	v_mov_b32_e32 v126, v0
	v_mov_b32_e32 v127, v0
	s_and_b64 vcc, exec, s[14:15]
	s_cbranch_vccnz .Lsp_skip_6
	s_setprio 1
.Lsp_skip_6:
.LBB0_192:
	ds_read_b128 v[162:165], v158
	ds_read_b128 v[166:169], v158 offset:1024
	ds_read_b128 v[170:173], v158 offset:2048
	ds_read_b128 v[174:177], v158 offset:3072
	ds_read_b128 v[188:191], v159
	ds_read_b128 v[196:199], v159 offset:1024
	ds_read_b128 v[200:203], v159 offset:2048
	ds_read_b128 v[204:207], v159 offset:3072
	s_add_u32 s55, s66, 0xfff80080
	s_addc_u32 s56, s67, -1
	s_cmp_eq_u32 s54, 28
	s_cselect_b32 s71, s19, s56
	s_cselect_b32 s70, s50, s55
	s_cselect_b32 s69, s17, s53
	s_cselect_b32 s68, s51, s52
	s_add_i32 m0, s37, 0xc000
	ds_read_b128 v[208:211], v161
	ds_read_b128 v[212:215], v161 offset:1024
	ds_read_b128 v[216:219], v161 offset:2048
	ds_read_b128 v[220:223], v161 offset:3072
	ds_read_b128 v[224:227], v161 offset:4096
	ds_read_b128 v[228:231], v161 offset:5120
	ds_read_b128 v[232:235], v161 offset:6144
	ds_read_b128 v[236:239], v161 offset:7168
	global_load_lds_dwordx4 v128, s[66:67]
	s_add_i32 m0, s37, 0xe000
	s_nop 0
	global_load_lds_dwordx4 v130, s[66:67]
	s_waitcnt vmcnt(8)
	s_waitcnt lgkmcnt(0)
	s_barrier
; #define PG8_STAGE(bufoff, gbase, voff) do { _Pragma("unroll") for (int _i = 0; _i < 2; ++_i) \
;         __builtin_amdgcn_global_load_lds((const unsigned*)((const char*)(gbase) + (voff)[_i]), (PG8_LAS unsigned*)(lds + (bufoff) + ldsw + _i * 8192), 16, 0, 0); } while (0)
; #define PG8_LDA(dst, b, h) do { _Pragma("unroll") for (int m = 0; m < 4; ++m) _Pragma("unroll") for (int k = 0; k < 2; ++k) dst[m][k] = *(const PG8_LAS bf16x8*)(lds + PG8_SA(b, h) + aoff + m * 2048 + k * 1024); } while (0)
; #define PG8_LDB(dst, b, h) do { _Pragma("unroll") for (int n = 0; n < 2; ++n) _Pragma("unroll") for (int k = 0; k < 2; ++k) dst[n][k] = *(const PG8_LAS bf16x8*)(lds + PG8_SB(b, h) + boff + n * 2048 + k * 1024); } while (0)
; #define PG8_MMA(ai, bj, At, Bt) do { __builtin_amdgcn_s_setprio(1); _Pragma("unroll") for (int m = 0; m < 4; ++m) _Pragma("unroll") for (int n = 0; n < 2; ++n) _Pragma("unroll") for (int k = 0; k < 2; ++k) \
;         acc[ai][bj][m][n] = __builtin_amdgcn_mfma_f32_16x16x32_bf16(Bt[n][k], At[m][k], acc[ai][bj][m][n], 0, 0, 0); __builtin_amdgcn_s_setprio(0); } while (0)
; #define PG8_WAIT_V(n) asm volatile("s_waitcnt vmcnt(" #n ")" ::: "memory")
; #define PG8_WAIT_L(n) asm volatile("s_waitcnt lgkmcnt(" #n ")" ::: "memory")
; #define PG8_BAR __builtin_amdgcn_s_barrier()
; #define PG8_SCHED __builtin_amdgcn_sched_barrier(0)
; template <class Epi, class Sched, bool ALIGN_EPI = false, bool SP2 = false>
; __device__ __forceinline__ void gemm_phase(PG8_LAS unsigned char* lds, const Gemm g, const Sched& S, const Epi& E) {
;     ...
;             PG8_LDB(B0, 0, 0); PG8_LDB(B1, 0, 1); PG8_SCHED; PG8_LDA(At, 0, 0); PG8_STAGE(PG8_SA(1, 1), a1 + hstep, voffA);
;             PG8_WAIT_V(8); PG8_WAIT_L(0); PG8_BAR; PG8_MMA(0, 0, At, B0); PG8_MMA(0, 1, At, B1); PG8_BAR; PG8_SCHED;
;             PG8_LDA(At, 0, 1); PG8_STAGE(PG8_SB(0, 0), b2, voffB); PG8_STAGE(PG8_SB(0, 1), b2 + hstep, voffB); PG8_STAGE(PG8_SA(0, 0), a2, voffA);
;             PG8_WAIT_V(8); PG8_WAIT_L(0); PG8_BAR; PG8_MMA(1, 0, At, B0); PG8_MMA(1, 1, At, B1); PG8_BAR; PG8_SCHED;
	s_waitcnt lgkmcnt(0)
	v_mfma_f32_16x16x32_bf16 v[124:127], v[162:165], v[208:211], v[124:127]
	v_mfma_f32_16x16x32_bf16 v[124:127], v[166:169], v[212:215], v[124:127]
	v_mfma_f32_16x16x32_bf16 v[116:119], v[174:177], v[212:215], v[116:119]
	v_mfma_f32_16x16x32_bf16 v[116:119], v[170:173], v[208:211], v[116:119]
	v_mfma_f32_16x16x32_bf16 v[100:103], v[170:173], v[216:219], v[100:103]
	v_mfma_f32_16x16x32_bf16 v[100:103], v[174:177], v[220:223], v[100:103]
	v_mfma_f32_16x16x32_bf16 v[108:111], v[166:169], v[220:223], v[108:111]
	v_mfma_f32_16x16x32_bf16 v[108:111], v[162:165], v[216:219], v[108:111]
	v_mfma_f32_16x16x32_bf16 v[92:95], v[162:165], v[224:227], v[92:95]
	v_mfma_f32_16x16x32_bf16 v[92:95], v[166:169], v[228:231], v[92:95]
	v_mfma_f32_16x16x32_bf16 v[84:87], v[174:177], v[228:231], v[84:87]
	v_mfma_f32_16x16x32_bf16 v[84:87], v[170:173], v[224:227], v[84:87]
	v_mfma_f32_16x16x32_bf16 v[68:71], v[170:173], v[232:235], v[68:71]
	v_mfma_f32_16x16x32_bf16 v[68:71], v[174:177], v[236:239], v[68:71]
	v_mfma_f32_16x16x32_bf16 v[76:79], v[166:169], v[236:239], v[76:79]
	v_mfma_f32_16x16x32_bf16 v[76:79], v[162:165], v[232:235], v[76:79]
	v_mfma_f32_16x16x32_bf16 v[120:123], v[188:191], v[208:211], v[120:123]
	v_mfma_f32_16x16x32_bf16 v[120:123], v[196:199], v[212:215], v[120:123]
	v_mfma_f32_16x16x32_bf16 v[112:115], v[204:207], v[212:215], v[112:115]
	v_mfma_f32_16x16x32_bf16 v[112:115], v[200:203], v[208:211], v[112:115]
	v_mfma_f32_16x16x32_bf16 v[96:99], v[200:203], v[216:219], v[96:99]
	v_mfma_f32_16x16x32_bf16 v[96:99], v[204:207], v[220:223], v[96:99]
	v_mfma_f32_16x16x32_bf16 v[104:107], v[196:199], v[220:223], v[104:107]
	v_mfma_f32_16x16x32_bf16 v[104:107], v[188:191], v[216:219], v[104:107]
	v_mfma_f32_16x16x32_bf16 v[88:91], v[188:191], v[224:227], v[88:91]
	v_mfma_f32_16x16x32_bf16 v[88:91], v[196:199], v[228:231], v[88:91]
	v_mfma_f32_16x16x32_bf16 v[80:83], v[204:207], v[228:231], v[80:83]
	v_mfma_f32_16x16x32_bf16 v[80:83], v[200:203], v[224:227], v[80:83]
	v_mfma_f32_16x16x32_bf16 v[64:67], v[200:203], v[232:235], v[64:67]
	v_mfma_f32_16x16x32_bf16 v[64:67], v[204:207], v[236:239], v[64:67]
	v_mfma_f32_16x16x32_bf16 v[72:75], v[196:199], v[236:239], v[72:75]
	v_mfma_f32_16x16x32_bf16 v[72:75], v[188:191], v[232:235], v[72:75]
	s_barrier
	s_add_u32 s98, s68, 0x80
	s_addc_u32 s99, s69, 0
	s_add_u32 s100, s70, 0x80
	s_addc_u32 s101, s71, 0
	s_add_i32 s55, s46, s36
	s_mov_b32 m0, s55
	ds_read_b128 v[208:211], v161 offset:16384
	ds_read_b128 v[212:215], v161 offset:17408
	ds_read_b128 v[216:219], v161 offset:18432
	ds_read_b128 v[220:223], v161 offset:19456
	ds_read_b128 v[224:227], v161 offset:20480
	ds_read_b128 v[228:231], v161 offset:21504
	ds_read_b128 v[232:235], v161 offset:22528
	ds_read_b128 v[236:239], v161 offset:23552
	global_load_lds_dwordx4 v152, s[68:69]
	s_add_i32 m0, s55, 0x2000
	s_add_u32 s56, s68, 0x80000
	s_addc_u32 s57, s69, 0
	s_add_i32 s55, s47, s36
	global_load_lds_dwordx4 v156, s[68:69]
	s_mov_b32 m0, s55
	s_nop 0
	global_load_lds_dwordx4 v152, s[56:57]
	s_add_i32 m0, s55, 0x2000
	s_nop 0
	global_load_lds_dwordx4 v156, s[56:57]
	s_mov_b32 m0, s37
	s_nop 0
	global_load_lds_dwordx4 v150, s[70:71]
	s_mov_b32 m0, s38
	s_nop 0
	global_load_lds_dwordx4 v154, s[70:71]
	s_waitcnt vmcnt(8)
	s_waitcnt lgkmcnt(0)
	s_barrier
	s_waitcnt lgkmcnt(0)
	v_mfma_f32_16x16x32_bf16 v[60:63], v[162:165], v[208:211], v[60:63]
	v_mfma_f32_16x16x32_bf16 v[60:63], v[166:169], v[212:215], v[60:63]
	v_mfma_f32_16x16x32_bf16 v[52:55], v[174:177], v[212:215], v[52:55]
	v_mfma_f32_16x16x32_bf16 v[52:55], v[170:173], v[208:211], v[52:55]
	v_mfma_f32_16x16x32_bf16 v[36:39], v[170:173], v[216:219], v[36:39]
	v_mfma_f32_16x16x32_bf16 v[36:39], v[174:177], v[220:223], v[36:39]
	v_mfma_f32_16x16x32_bf16 v[44:47], v[166:169], v[220:223], v[44:47]
	v_mfma_f32_16x16x32_bf16 v[44:47], v[162:165], v[216:219], v[44:47]
	v_mfma_f32_16x16x32_bf16 v[28:31], v[162:165], v[224:227], v[28:31]
	v_mfma_f32_16x16x32_bf16 v[28:31], v[166:169], v[228:231], v[28:31]
	v_mfma_f32_16x16x32_bf16 v[20:23], v[174:177], v[228:231], v[20:23]
	v_mfma_f32_16x16x32_bf16 v[20:23], v[170:173], v[224:227], v[20:23]
	v_mfma_f32_16x16x32_bf16 v[4:7], v[170:173], v[232:235], v[4:7]
	v_mfma_f32_16x16x32_bf16 v[4:7], v[174:177], v[236:239], v[4:7]
	v_mfma_f32_16x16x32_bf16 v[12:15], v[166:169], v[236:239], v[12:15]
	v_mfma_f32_16x16x32_bf16 v[12:15], v[162:165], v[232:235], v[12:15]
	v_mfma_f32_16x16x32_bf16 v[56:59], v[188:191], v[208:211], v[56:59]
	v_mfma_f32_16x16x32_bf16 v[56:59], v[196:199], v[212:215], v[56:59]
	v_mfma_f32_16x16x32_bf16 v[48:51], v[204:207], v[212:215], v[48:51]
	v_mfma_f32_16x16x32_bf16 v[48:51], v[200:203], v[208:211], v[48:51]
	v_mfma_f32_16x16x32_bf16 v[32:35], v[200:203], v[216:219], v[32:35]
	v_mfma_f32_16x16x32_bf16 v[32:35], v[204:207], v[220:223], v[32:35]
	v_mfma_f32_16x16x32_bf16 v[40:43], v[196:199], v[220:223], v[40:43]
	v_mfma_f32_16x16x32_bf16 v[40:43], v[188:191], v[216:219], v[40:43]
	v_mfma_f32_16x16x32_bf16 v[24:27], v[188:191], v[224:227], v[24:27]
	v_mfma_f32_16x16x32_bf16 v[24:27], v[196:199], v[228:231], v[24:27]
	v_mfma_f32_16x16x32_bf16 v[16:19], v[204:207], v[228:231], v[16:19]
	v_mfma_f32_16x16x32_bf16 v[16:19], v[200:203], v[224:227], v[16:19]
	v_mfma_f32_16x16x32_bf16 v[0:3], v[200:203], v[232:235], v[0:3]
	v_mfma_f32_16x16x32_bf16 v[0:3], v[204:207], v[236:239], v[0:3]
	v_mfma_f32_16x16x32_bf16 v[8:11], v[196:199], v[236:239], v[8:11]
	v_mfma_f32_16x16x32_bf16 v[8:11], v[188:191], v[232:235], v[8:11]
	s_barrier
; #define PG8_STAGE(bufoff, gbase, voff) do { _Pragma("unroll") for (int _i = 0; _i < 2; ++_i) \
;         __builtin_amdgcn_global_load_lds((const unsigned*)((const char*)(gbase) + (voff)[_i]), (PG8_LAS unsigned*)(lds + (bufoff) + ldsw + _i * 8192), 16, 0, 0); } while (0)
; #define PG8_LDA(dst, b, h) do { _Pragma("unroll") for (int m = 0; m < 4; ++m) _Pragma("unroll") for (int k = 0; k < 2; ++k) dst[m][k] = *(const PG8_LAS bf16x8*)(lds + PG8_SA(b, h) + aoff + m * 2048 + k * 1024); } while (0)
; #define PG8_LDB(dst, b, h) do { _Pragma("unroll") for (int n = 0; n < 2; ++n) _Pragma("unroll") for (int k = 0; k < 2; ++k) dst[n][k] = *(const PG8_LAS bf16x8*)(lds + PG8_SB(b, h) + boff + n * 2048 + k * 1024); } while (0)
; #define PG8_MMA(ai, bj, At, Bt) do { __builtin_amdgcn_s_setprio(1); _Pragma("unroll") for (int m = 0; m < 4; ++m) _Pragma("unroll") for (int n = 0; n < 2; ++n) _Pragma("unroll") for (int k = 0; k < 2; ++k) \
;         acc[ai][bj][m][n] = __builtin_amdgcn_mfma_f32_16x16x32_bf16(Bt[n][k], At[m][k], acc[ai][bj][m][n], 0, 0, 0); __builtin_amdgcn_s_setprio(0); } while (0)
; #define PG8_WAIT_V(n) asm volatile("s_waitcnt vmcnt(" #n ")" ::: "memory")
; #define PG8_WAIT_L(n) asm volatile("s_waitcnt lgkmcnt(" #n ")" ::: "memory")
; #define PG8_BAR __builtin_amdgcn_s_barrier()
; #define PG8_SCHED __builtin_amdgcn_sched_barrier(0)
; template <class Epi, class Sched, bool ALIGN_EPI = false, bool SP2 = false>
; __device__ __forceinline__ void gemm_phase(PG8_LAS unsigned char* lds, const Gemm g, const Sched& S, const Epi& E) {
;     ...
;             PG8_LDB(B0, 1, 0); PG8_LDB(B1, 1, 1); PG8_SCHED; PG8_LDA(At, 1, 0); PG8_STAGE(PG8_SA(0, 1), a2 + hstep, voffA);
;             PG8_WAIT_V(8); PG8_WAIT_L(0); PG8_BAR; PG8_MMA(0, 0, At, B0); PG8_MMA(0, 1, At, B1); PG8_BAR; PG8_SCHED;
;             PG8_LDA(At, 1, 1); PG8_STAGE(PG8_SB(1, 0), b3, voffB); PG8_STAGE(PG8_SB(1, 1), b3 + hstep, voffB); PG8_STAGE(PG8_SA(1, 0), a3, voffA);
;             PG8_WAIT_V(8); PG8_WAIT_L(0); PG8_BAR; PG8_MMA(1, 0, At, B0); PG8_MMA(1, 1, At, B1); PG8_BAR; PG8_SCHED;
;     ...
;         if constexpr (ALIGN_EPI) { if (wr == 0) PG8_BAR; }
	s_add_i32 s55, 0, 0x18000
	s_add_i32 s58, 0, 0x1c000
	v_add_u32_e32 v174, s55, v148
	v_add_u32_e32 v183, s58, v148
	ds_read_b128 v[162:165], v174
	ds_read_b128 v[166:169], v174 offset:1024
	ds_read_b128 v[170:173], v174 offset:2048
	ds_read_b128 v[174:177], v174 offset:3072
	ds_read_b128 v[188:191], v183
	ds_read_b128 v[196:199], v183 offset:1024
	ds_read_b128 v[200:203], v183 offset:2048
	ds_read_b128 v[204:207], v183 offset:3072
	s_add_u32 s56, s70, 0x80000
	s_addc_u32 s57, s71, 0
	s_mov_b32 m0, s39
	ds_read_b128 v[208:211], v161 offset:32768
	ds_read_b128 v[212:215], v161 offset:33792
	ds_read_b128 v[216:219], v161 offset:34816
	ds_read_b128 v[220:223], v161 offset:35840
	ds_read_b128 v[224:227], v161 offset:36864
	ds_read_b128 v[228:231], v161 offset:37888
	ds_read_b128 v[232:235], v161 offset:38912
	ds_read_b128 v[236:239], v161 offset:39936
	global_load_lds_dwordx4 v150, s[56:57]
	s_mov_b32 m0, s40
	s_nop 0
	global_load_lds_dwordx4 v154, s[56:57]
	s_waitcnt vmcnt(8)
	s_waitcnt lgkmcnt(0)
	s_barrier
	s_waitcnt lgkmcnt(0)
	v_mfma_f32_16x16x32_bf16 v[124:127], v[162:165], v[208:211], v[124:127]
	v_mfma_f32_16x16x32_bf16 v[124:127], v[166:169], v[212:215], v[124:127]
	v_mfma_f32_16x16x32_bf16 v[116:119], v[174:177], v[212:215], v[116:119]
	v_mfma_f32_16x16x32_bf16 v[116:119], v[170:173], v[208:211], v[116:119]
	v_mfma_f32_16x16x32_bf16 v[100:103], v[170:173], v[216:219], v[100:103]
	v_mfma_f32_16x16x32_bf16 v[100:103], v[174:177], v[220:223], v[100:103]
	v_mfma_f32_16x16x32_bf16 v[108:111], v[166:169], v[220:223], v[108:111]
	v_mfma_f32_16x16x32_bf16 v[108:111], v[162:165], v[216:219], v[108:111]
	v_mfma_f32_16x16x32_bf16 v[92:95], v[162:165], v[224:227], v[92:95]
	v_mfma_f32_16x16x32_bf16 v[92:95], v[166:169], v[228:231], v[92:95]
	v_mfma_f32_16x16x32_bf16 v[84:87], v[174:177], v[228:231], v[84:87]
	v_mfma_f32_16x16x32_bf16 v[84:87], v[170:173], v[224:227], v[84:87]
	v_mfma_f32_16x16x32_bf16 v[68:71], v[170:173], v[232:235], v[68:71]
	v_mfma_f32_16x16x32_bf16 v[68:71], v[174:177], v[236:239], v[68:71]
	v_mfma_f32_16x16x32_bf16 v[76:79], v[166:169], v[236:239], v[76:79]
	v_mfma_f32_16x16x32_bf16 v[76:79], v[162:165], v[232:235], v[76:79]
	v_mfma_f32_16x16x32_bf16 v[120:123], v[188:191], v[208:211], v[120:123]
	v_mfma_f32_16x16x32_bf16 v[120:123], v[196:199], v[212:215], v[120:123]
	v_mfma_f32_16x16x32_bf16 v[112:115], v[204:207], v[212:215], v[112:115]
	v_mfma_f32_16x16x32_bf16 v[112:115], v[200:203], v[208:211], v[112:115]
	v_mfma_f32_16x16x32_bf16 v[96:99], v[200:203], v[216:219], v[96:99]
	v_mfma_f32_16x16x32_bf16 v[96:99], v[204:207], v[220:223], v[96:99]
	v_mfma_f32_16x16x32_bf16 v[104:107], v[196:199], v[220:223], v[104:107]
	v_mfma_f32_16x16x32_bf16 v[104:107], v[188:191], v[216:219], v[104:107]
	v_mfma_f32_16x16x32_bf16 v[88:91], v[188:191], v[224:227], v[88:91]
	v_mfma_f32_16x16x32_bf16 v[88:91], v[196:199], v[228:231], v[88:91]
	v_mfma_f32_16x16x32_bf16 v[80:83], v[204:207], v[228:231], v[80:83]
	v_mfma_f32_16x16x32_bf16 v[80:83], v[200:203], v[224:227], v[80:83]
	v_mfma_f32_16x16x32_bf16 v[64:67], v[200:203], v[232:235], v[64:67]
	v_mfma_f32_16x16x32_bf16 v[64:67], v[204:207], v[236:239], v[64:67]
	v_mfma_f32_16x16x32_bf16 v[72:75], v[196:199], v[236:239], v[72:75]
	v_mfma_f32_16x16x32_bf16 v[72:75], v[188:191], v[232:235], v[72:75]
	s_barrier
	s_add_i32 s55, s55, s36
	s_mov_b32 m0, s55
	ds_read_b128 v[208:211], v161 offset:49152
	ds_read_b128 v[212:215], v161 offset:50176
	ds_read_b128 v[216:219], v161 offset:51200
	ds_read_b128 v[220:223], v161 offset:52224
	ds_read_b128 v[224:227], v161 offset:53248
	ds_read_b128 v[228:231], v161 offset:54272
	ds_read_b128 v[232:235], v161 offset:55296
	ds_read_b128 v[236:239], v161 offset:56320
	global_load_lds_dwordx4 v152, s[98:99]
	s_add_i32 m0, s55, 0x2000
	s_add_u32 s56, s68, 0x80080
	s_addc_u32 s57, s69, 0
	s_add_i32 s55, s58, s36
	global_load_lds_dwordx4 v156, s[98:99]
	s_mov_b32 m0, s55
	s_nop 0
	global_load_lds_dwordx4 v152, s[56:57]
	s_add_i32 m0, s55, 0x2000
	s_nop 0
	global_load_lds_dwordx4 v156, s[56:57]
	s_mov_b32 m0, s42
	s_nop 0
	global_load_lds_dwordx4 v150, s[100:101]
	s_mov_b32 m0, s43
	s_nop 0
	global_load_lds_dwordx4 v154, s[100:101]
	s_waitcnt vmcnt(8)
	s_waitcnt lgkmcnt(0)
	s_barrier
	s_waitcnt lgkmcnt(0)
	v_mfma_f32_16x16x32_bf16 v[60:63], v[162:165], v[208:211], v[60:63]
	v_mfma_f32_16x16x32_bf16 v[60:63], v[166:169], v[212:215], v[60:63]
	v_mfma_f32_16x16x32_bf16 v[52:55], v[174:177], v[212:215], v[52:55]
	v_mfma_f32_16x16x32_bf16 v[52:55], v[170:173], v[208:211], v[52:55]
	v_mfma_f32_16x16x32_bf16 v[36:39], v[170:173], v[216:219], v[36:39]
	v_mfma_f32_16x16x32_bf16 v[36:39], v[174:177], v[220:223], v[36:39]
	v_mfma_f32_16x16x32_bf16 v[44:47], v[166:169], v[220:223], v[44:47]
	v_mfma_f32_16x16x32_bf16 v[44:47], v[162:165], v[216:219], v[44:47]
	v_mfma_f32_16x16x32_bf16 v[28:31], v[162:165], v[224:227], v[28:31]
	v_mfma_f32_16x16x32_bf16 v[28:31], v[166:169], v[228:231], v[28:31]
	v_mfma_f32_16x16x32_bf16 v[20:23], v[174:177], v[228:231], v[20:23]
	v_mfma_f32_16x16x32_bf16 v[20:23], v[170:173], v[224:227], v[20:23]
	v_mfma_f32_16x16x32_bf16 v[4:7], v[170:173], v[232:235], v[4:7]
	v_mfma_f32_16x16x32_bf16 v[4:7], v[174:177], v[236:239], v[4:7]
	v_mfma_f32_16x16x32_bf16 v[12:15], v[166:169], v[236:239], v[12:15]
	v_mfma_f32_16x16x32_bf16 v[12:15], v[162:165], v[232:235], v[12:15]
	v_mfma_f32_16x16x32_bf16 v[56:59], v[188:191], v[208:211], v[56:59]
	v_mfma_f32_16x16x32_bf16 v[56:59], v[196:199], v[212:215], v[56:59]
	v_mfma_f32_16x16x32_bf16 v[48:51], v[204:207], v[212:215], v[48:51]
	v_mfma_f32_16x16x32_bf16 v[48:51], v[200:203], v[208:211], v[48:51]
	v_mfma_f32_16x16x32_bf16 v[32:35], v[200:203], v[216:219], v[32:35]
	v_mfma_f32_16x16x32_bf16 v[32:35], v[204:207], v[220:223], v[32:35]
	v_mfma_f32_16x16x32_bf16 v[40:43], v[196:199], v[220:223], v[40:43]
	v_mfma_f32_16x16x32_bf16 v[40:43], v[188:191], v[216:219], v[40:43]
	v_mfma_f32_16x16x32_bf16 v[24:27], v[188:191], v[224:227], v[24:27]
	v_mfma_f32_16x16x32_bf16 v[24:27], v[196:199], v[228:231], v[24:27]
	v_mfma_f32_16x16x32_bf16 v[16:19], v[204:207], v[228:231], v[16:19]
	v_mfma_f32_16x16x32_bf16 v[16:19], v[200:203], v[224:227], v[16:19]
	v_mfma_f32_16x16x32_bf16 v[0:3], v[200:203], v[232:235], v[0:3]
	v_mfma_f32_16x16x32_bf16 v[0:3], v[204:207], v[236:239], v[0:3]
	v_mfma_f32_16x16x32_bf16 v[8:11], v[196:199], v[236:239], v[8:11]
	v_mfma_f32_16x16x32_bf16 v[8:11], v[188:191], v[232:235], v[8:11]
	s_barrier
	s_add_i32 s54, s54, 2
	s_add_u32 s66, s66, 0x100
	s_addc_u32 s67, s67, 0
	s_add_u32 s52, s52, 0x100
	s_addc_u32 s53, s53, 0
	s_cmp_gt_u32 s54, 29
	s_cbranch_scc0 .LBB0_192
	s_setprio 0
	s_and_b64 vcc, exec, s[14:15]
	s_cbranch_vccz .LBB0_195
	s_barrier

; #define PG8_STAGE(bufoff, gbase, voff) do { _Pragma("unroll") for (int _i = 0; _i < 2; ++_i) \
;         __builtin_amdgcn_global_load_lds((const unsigned*)((const char*)(gbase) + (voff)[_i]), (PG8_LAS unsigned*)(lds + (bufoff) + ldsw + _i * 8192), 16, 0, 0); } while (0)
; #define PG8_LDA(dst, b, h) do { _Pragma("unroll") for (int m = 0; m < 4; ++m) _Pragma("unroll") for (int k = 0; k < 2; ++k) dst[m][k] = *(const PG8_LAS bf16x8*)(lds + PG8_SA(b, h) + aoff + m * 2048 + k * 1024); } while (0)
; #define PG8_LDB(dst, b, h) do { _Pragma("unroll") for (int n = 0; n < 2; ++n) _Pragma("unroll") for (int k = 0; k < 2; ++k) dst[n][k] = *(const PG8_LAS bf16x8*)(lds + PG8_SB(b, h) + boff + n * 2048 + k * 1024); } while (0)
; #define PG8_MMA(ai, bj, At, Bt) do { __builtin_amdgcn_s_setprio(1); _Pragma("unroll") for (int m = 0; m < 4; ++m) _Pragma("unroll") for (int n = 0; n < 2; ++n) _Pragma("unroll") for (int k = 0; k < 2; ++k) \
;         acc[ai][bj][m][n] = __builtin_amdgcn_mfma_f32_16x16x32_bf16(Bt[n][k], At[m][k], acc[ai][bj][m][n], 0, 0, 0); __builtin_amdgcn_s_setprio(0); } while (0)
; #define PG8_WAIT_V(n) asm volatile("s_waitcnt vmcnt(" #n ")" ::: "memory")
; #define PG8_WAIT_L(n) asm volatile("s_waitcnt lgkmcnt(" #n ")" ::: "memory")
; #define PG8_BAR __builtin_amdgcn_s_barrier()
; #define PG8_SCHED __builtin_amdgcn_sched_barrier(0)
; template <class Epi, class Sched, bool ALIGN_EPI = false, bool SP2 = false>
; __device__ __forceinline__ void gemm_phase(PG8_LAS unsigned char* lds, const Gemm g, const Sched& S, const Epi& E) {
;     ...
;             PG8_LDB(B0, 0, 0); PG8_LDB(B1, 0, 1); PG8_SCHED; PG8_LDA(At, 0, 0); PG8_STAGE(PG8_SA(1, 1), a1 + hstep, voffA);
;             PG8_WAIT_V(8); PG8_WAIT_L(0); PG8_BAR; PG8_MMA(0, 0, At, B0); PG8_MMA(0, 1, At, B1); PG8_BAR; PG8_SCHED;
;     ...
;         for (int a = 0; a < 2; ++a)
; #pragma unroll
;             for (int b = 0; b < 2; ++b)
; #pragma unroll
;                 for (int m = 0; m < 4; ++m)
; #pragma unroll
;                     for (int n = 0; n < 2; ++n) acc[a][b][m][n] = (f32x4){0.f, 0.f, 0.f, 0.f};
;         cur = nxt; cA = nA; cB = nB; ++ui;
.LBB0_307:
	s_add_u32 s10, s14, 0x160080
	s_addc_u32 s11, s15, 0
	s_add_u32 s17, s12, 0x100
	v_mov_b32_e32 v0, 0
	s_addc_u32 s39, s13, 0
	s_mov_b32 s40, -2
	s_waitcnt lgkmcnt(0)
	v_mov_b32_e32 v1, v0
	v_mov_b32_e32 v2, v0
	v_mov_b32_e32 v3, v0
	v_mov_b32_e32 v4, v0
	v_mov_b32_e32 v5, v0
	v_mov_b32_e32 v6, v0
	v_mov_b32_e32 v7, v0
	v_mov_b32_e32 v16, v0
	v_mov_b32_e32 v17, v0
	v_mov_b32_e32 v18, v0
	v_mov_b32_e32 v19, v0
	v_mov_b32_e32 v20, v0
	v_mov_b32_e32 v21, v0
	v_mov_b32_e32 v22, v0
	v_mov_b32_e32 v23, v0
	v_mov_b32_e32 v32, v0
	v_mov_b32_e32 v33, v0
	v_mov_b32_e32 v34, v0
	v_mov_b32_e32 v35, v0
	v_mov_b32_e32 v36, v0
	v_mov_b32_e32 v37, v0
	v_mov_b32_e32 v38, v0
	v_mov_b32_e32 v39, v0
	v_mov_b32_e32 v48, v0
	v_mov_b32_e32 v49, v0
	v_mov_b32_e32 v50, v0
	v_mov_b32_e32 v51, v0
	v_mov_b32_e32 v52, v0
	v_mov_b32_e32 v53, v0
	v_mov_b32_e32 v54, v0
	v_mov_b32_e32 v55, v0
	v_mov_b32_e32 v8, v0
	v_mov_b32_e32 v9, v0
	v_mov_b32_e32 v10, v0
	v_mov_b32_e32 v11, v0
	v_mov_b32_e32 v12, v0
	v_mov_b32_e32 v13, v0
	v_mov_b32_e32 v14, v0
	v_mov_b32_e32 v15, v0
	v_mov_b32_e32 v24, v0
	v_mov_b32_e32 v25, v0
	v_mov_b32_e32 v26, v0
	v_mov_b32_e32 v27, v0
	v_mov_b32_e32 v28, v0
	v_mov_b32_e32 v29, v0
	v_mov_b32_e32 v30, v0
	v_mov_b32_e32 v31, v0
	v_mov_b32_e32 v40, v0
	v_mov_b32_e32 v41, v0
	v_mov_b32_e32 v42, v0
	v_mov_b32_e32 v43, v0
	v_mov_b32_e32 v44, v0
	v_mov_b32_e32 v45, v0
	v_mov_b32_e32 v46, v0
	v_mov_b32_e32 v47, v0
	v_mov_b32_e32 v56, v0
	v_mov_b32_e32 v57, v0
	v_mov_b32_e32 v58, v0
	v_mov_b32_e32 v59, v0
	v_mov_b32_e32 v60, v0
	v_mov_b32_e32 v61, v0
	v_mov_b32_e32 v62, v0
	v_mov_b32_e32 v63, v0
	v_mov_b32_e32 v64, v0
	v_mov_b32_e32 v65, v0
	v_mov_b32_e32 v66, v0
	v_mov_b32_e32 v67, v0
	v_mov_b32_e32 v68, v0
	v_mov_b32_e32 v69, v0
	v_mov_b32_e32 v70, v0
	v_mov_b32_e32 v71, v0
	v_mov_b32_e32 v80, v0
	v_mov_b32_e32 v81, v0
	v_mov_b32_e32 v82, v0
	v_mov_b32_e32 v83, v0
	v_mov_b32_e32 v84, v0
	v_mov_b32_e32 v85, v0
	v_mov_b32_e32 v86, v0
	v_mov_b32_e32 v87, v0
	v_mov_b32_e32 v96, v0
	v_mov_b32_e32 v97, v0
	v_mov_b32_e32 v98, v0
	v_mov_b32_e32 v99, v0
	v_mov_b32_e32 v100, v0
	v_mov_b32_e32 v101, v0
	v_mov_b32_e32 v102, v0
	v_mov_b32_e32 v103, v0
	v_mov_b32_e32 v112, v0
	v_mov_b32_e32 v113, v0
	v_mov_b32_e32 v114, v0
	v_mov_b32_e32 v115, v0
	v_mov_b32_e32 v116, v0
	v_mov_b32_e32 v117, v0
	v_mov_b32_e32 v118, v0
	v_mov_b32_e32 v119, v0
	v_mov_b32_e32 v72, v0
	v_mov_b32_e32 v73, v0
	v_mov_b32_e32 v74, v0
	v_mov_b32_e32 v75, v0
	v_mov_b32_e32 v76, v0
	v_mov_b32_e32 v77, v0
	v_mov_b32_e32 v78, v0
	v_mov_b32_e32 v79, v0
	v_mov_b32_e32 v88, v0
	v_mov_b32_e32 v89, v0
	v_mov_b32_e32 v90, v0
	v_mov_b32_e32 v91, v0
	v_mov_b32_e32 v92, v0
	v_mov_b32_e32 v93, v0
	v_mov_b32_e32 v94, v0
	v_mov_b32_e32 v95, v0
	v_mov_b32_e32 v104, v0
	v_mov_b32_e32 v105, v0
	v_mov_b32_e32 v106, v0
	v_mov_b32_e32 v107, v0
	v_mov_b32_e32 v108, v0
	v_mov_b32_e32 v109, v0
	v_mov_b32_e32 v110, v0
	v_mov_b32_e32 v111, v0
	v_mov_b32_e32 v120, v0
	v_mov_b32_e32 v121, v0
	v_mov_b32_e32 v122, v0
	v_mov_b32_e32 v123, v0
	v_mov_b32_e32 v124, v0
	v_mov_b32_e32 v125, v0
	v_mov_b32_e32 v126, v0
	v_mov_b32_e32 v127, v0
	s_and_b64 vcc, exec, s[74:75]
	s_cbranch_vccnz .Lsp_skip_5
	s_setprio 1
.Lsp_skip_5:
.LBB0_308:
	ds_read_b128 v[128:131], v155
	ds_read_b128 v[132:135], v155 offset:1024
	ds_read_b128 v[170:173], v155 offset:2048
	ds_read_b128 v[174:177], v155 offset:3072
	ds_read_b128 v[196:199], v157
	ds_read_b128 v[200:203], v157 offset:1024
	ds_read_b128 v[204:207], v157 offset:2048
	ds_read_b128 v[208:211], v157 offset:3072
	s_add_u32 s12, s10, 0xffea0080
	s_addc_u32 s13, s11, -1
	s_cmpk_eq_i32 s40, 0x54
	s_cselect_b32 s15, s77, s13
	s_cselect_b32 s14, s76, s12
	s_cselect_b32 s13, s79, s39
	s_cselect_b32 s12, s78, s17
	s_add_i32 m0, s54, 0xc000
	ds_read_b128 v[212:215], v161
	ds_read_b128 v[216:219], v161 offset:1024
	ds_read_b128 v[220:223], v161 offset:2048
	ds_read_b128 v[224:227], v161 offset:3072
	ds_read_b128 v[228:231], v161 offset:4096
	ds_read_b128 v[232:235], v161 offset:5120
	ds_read_b128 v[236:239], v161 offset:6144
	ds_read_b128 v[240:243], v161 offset:7168
	global_load_lds_dwordx4 v162, s[10:11]
	s_add_i32 m0, s54, 0xe000
	s_nop 0
	global_load_lds_dwordx4 v164, s[10:11]
	s_waitcnt vmcnt(8)
	s_waitcnt lgkmcnt(0)
	s_barrier
	s_waitcnt lgkmcnt(0)
	v_mfma_f32_16x16x32_bf16 v[124:127], v[128:131], v[212:215], v[124:127]
	v_mfma_f32_16x16x32_bf16 v[124:127], v[132:135], v[216:219], v[124:127]
	v_mfma_f32_16x16x32_bf16 v[120:123], v[174:177], v[216:219], v[120:123]
	v_mfma_f32_16x16x32_bf16 v[120:123], v[170:173], v[212:215], v[120:123]
	v_mfma_f32_16x16x32_bf16 v[104:107], v[170:173], v[220:223], v[104:107]
	v_mfma_f32_16x16x32_bf16 v[104:107], v[174:177], v[224:227], v[104:107]
	v_mfma_f32_16x16x32_bf16 v[108:111], v[132:135], v[224:227], v[108:111]
	v_mfma_f32_16x16x32_bf16 v[108:111], v[128:131], v[220:223], v[108:111]
	v_mfma_f32_16x16x32_bf16 v[92:95], v[128:131], v[228:231], v[92:95]
	v_mfma_f32_16x16x32_bf16 v[92:95], v[132:135], v[232:235], v[92:95]
	v_mfma_f32_16x16x32_bf16 v[88:91], v[174:177], v[232:235], v[88:91]
	v_mfma_f32_16x16x32_bf16 v[88:91], v[170:173], v[228:231], v[88:91]
	v_mfma_f32_16x16x32_bf16 v[72:75], v[170:173], v[236:239], v[72:75]
	v_mfma_f32_16x16x32_bf16 v[72:75], v[174:177], v[240:243], v[72:75]
	v_mfma_f32_16x16x32_bf16 v[76:79], v[132:135], v[240:243], v[76:79]
	v_mfma_f32_16x16x32_bf16 v[76:79], v[128:131], v[236:239], v[76:79]
	v_mfma_f32_16x16x32_bf16 v[116:119], v[196:199], v[212:215], v[116:119]
	v_mfma_f32_16x16x32_bf16 v[116:119], v[200:203], v[216:219], v[116:119]
	v_mfma_f32_16x16x32_bf16 v[112:115], v[208:211], v[216:219], v[112:115]
	v_mfma_f32_16x16x32_bf16 v[112:115], v[204:207], v[212:215], v[112:115]
	v_mfma_f32_16x16x32_bf16 v[96:99], v[204:207], v[220:223], v[96:99]
	v_mfma_f32_16x16x32_bf16 v[96:99], v[208:211], v[224:227], v[96:99]
	v_mfma_f32_16x16x32_bf16 v[100:103], v[200:203], v[224:227], v[100:103]
	v_mfma_f32_16x16x32_bf16 v[100:103], v[196:199], v[220:223], v[100:103]
	v_mfma_f32_16x16x32_bf16 v[84:87], v[196:199], v[228:231], v[84:87]
	v_mfma_f32_16x16x32_bf16 v[84:87], v[200:203], v[232:235], v[84:87]
	v_mfma_f32_16x16x32_bf16 v[80:83], v[208:211], v[232:235], v[80:83]
	v_mfma_f32_16x16x32_bf16 v[80:83], v[204:207], v[228:231], v[80:83]
	v_mfma_f32_16x16x32_bf16 v[64:67], v[204:207], v[236:239], v[64:67]
	v_mfma_f32_16x16x32_bf16 v[64:67], v[208:211], v[240:243], v[64:67]
	v_mfma_f32_16x16x32_bf16 v[68:71], v[200:203], v[240:243], v[68:71]
	v_mfma_f32_16x16x32_bf16 v[68:71], v[196:199], v[236:239], v[68:71]
	s_barrier
; #define PG8_STAGE(bufoff, gbase, voff) do { _Pragma("unroll") for (int _i = 0; _i < 2; ++_i) \
;         __builtin_amdgcn_global_load_lds((const unsigned*)((const char*)(gbase) + (voff)[_i]), (PG8_LAS unsigned*)(lds + (bufoff) + ldsw + _i * 8192), 16, 0, 0); } while (0)
; #define PG8_LDA(dst, b, h) do { _Pragma("unroll") for (int m = 0; m < 4; ++m) _Pragma("unroll") for (int k = 0; k < 2; ++k) dst[m][k] = *(const PG8_LAS bf16x8*)(lds + PG8_SA(b, h) + aoff + m * 2048 + k * 1024); } while (0)
; #define PG8_LDB(dst, b, h) do { _Pragma("unroll") for (int n = 0; n < 2; ++n) _Pragma("unroll") for (int k = 0; k < 2; ++k) dst[n][k] = *(const PG8_LAS bf16x8*)(lds + PG8_SB(b, h) + boff + n * 2048 + k * 1024); } while (0)
; #define PG8_MMA(ai, bj, At, Bt) do { __builtin_amdgcn_s_setprio(1); _Pragma("unroll") for (int m = 0; m < 4; ++m) _Pragma("unroll") for (int n = 0; n < 2; ++n) _Pragma("unroll") for (int k = 0; k < 2; ++k) \
;         acc[ai][bj][m][n] = __builtin_amdgcn_mfma_f32_16x16x32_bf16(Bt[n][k], At[m][k], acc[ai][bj][m][n], 0, 0, 0); __builtin_amdgcn_s_setprio(0); } while (0)
; #define PG8_WAIT_V(n) asm volatile("s_waitcnt vmcnt(" #n ")" ::: "memory")
; #define PG8_WAIT_L(n) asm volatile("s_waitcnt lgkmcnt(" #n ")" ::: "memory")
; #define PG8_BAR __builtin_amdgcn_s_barrier()
; #define PG8_SCHED __builtin_amdgcn_sched_barrier(0)
; template <class Epi, class Sched, bool ALIGN_EPI = false, bool SP2 = false>
; __device__ __forceinline__ void gemm_phase(PG8_LAS unsigned char* lds, const Gemm g, const Sched& S, const Epi& E) {
;     ...
;             PG8_LDA(At, 0, 1); PG8_STAGE(PG8_SB(0, 0), b2, voffB); PG8_STAGE(PG8_SB(0, 1), b2 + hstep, voffB); PG8_STAGE(PG8_SA(0, 0), a2, voffA);
;             PG8_WAIT_V(8); PG8_WAIT_L(0); PG8_BAR; PG8_MMA(1, 0, At, B0); PG8_MMA(1, 1, At, B1); PG8_BAR; PG8_SCHED;
;             PG8_LDB(B0, 1, 0); PG8_LDB(B1, 1, 1); PG8_SCHED; PG8_LDA(At, 1, 0); PG8_STAGE(PG8_SA(0, 1), a2 + hstep, voffA);
;             PG8_WAIT_V(8); PG8_WAIT_L(0); PG8_BAR; PG8_MMA(0, 0, At, B0); PG8_MMA(0, 1, At, B1); PG8_BAR; PG8_SCHED;
	s_add_u32 s98, s12, 0x80
	s_addc_u32 s99, s13, 0
	s_add_u32 s100, s14, 0x80
	s_addc_u32 s101, s15, 0
	s_add_i32 s41, s92, s53
	s_mov_b32 m0, s41
	ds_read_b128 v[212:215], v161 offset:16384
	ds_read_b128 v[216:219], v161 offset:17408
	ds_read_b128 v[220:223], v161 offset:18432
	ds_read_b128 v[224:227], v161 offset:19456
	ds_read_b128 v[228:231], v161 offset:20480
	ds_read_b128 v[232:235], v161 offset:21504
	ds_read_b128 v[236:239], v161 offset:22528
	ds_read_b128 v[240:243], v161 offset:23552
	global_load_lds_dwordx4 v144, s[12:13]
	s_add_i32 m0, s41, 0x2000
	s_add_u32 s42, s12, 0x160000
	s_addc_u32 s43, s13, 0
	s_add_i32 s41, s93, s53
	global_load_lds_dwordx4 v148, s[12:13]
	s_mov_b32 m0, s41
	s_nop 0
	global_load_lds_dwordx4 v144, s[42:43]
	s_add_i32 m0, s41, 0x2000
	s_nop 0
	global_load_lds_dwordx4 v148, s[42:43]
	s_mov_b32 m0, s54
	s_nop 0
	global_load_lds_dwordx4 v142, s[14:15]
	s_mov_b32 m0, s55
	s_nop 0
	global_load_lds_dwordx4 v146, s[14:15]
	s_waitcnt vmcnt(8)
	s_waitcnt lgkmcnt(0)
	s_barrier
	s_waitcnt lgkmcnt(0)
	v_mfma_f32_16x16x32_bf16 v[60:63], v[128:131], v[212:215], v[60:63]
	v_mfma_f32_16x16x32_bf16 v[60:63], v[132:135], v[216:219], v[60:63]
	v_mfma_f32_16x16x32_bf16 v[56:59], v[174:177], v[216:219], v[56:59]
	v_mfma_f32_16x16x32_bf16 v[56:59], v[170:173], v[212:215], v[56:59]
	v_mfma_f32_16x16x32_bf16 v[40:43], v[170:173], v[220:223], v[40:43]
	v_mfma_f32_16x16x32_bf16 v[40:43], v[174:177], v[224:227], v[40:43]
	v_mfma_f32_16x16x32_bf16 v[44:47], v[132:135], v[224:227], v[44:47]
	v_mfma_f32_16x16x32_bf16 v[44:47], v[128:131], v[220:223], v[44:47]
	v_mfma_f32_16x16x32_bf16 v[28:31], v[128:131], v[228:231], v[28:31]
	v_mfma_f32_16x16x32_bf16 v[28:31], v[132:135], v[232:235], v[28:31]
	v_mfma_f32_16x16x32_bf16 v[24:27], v[174:177], v[232:235], v[24:27]
	v_mfma_f32_16x16x32_bf16 v[24:27], v[170:173], v[228:231], v[24:27]
	v_mfma_f32_16x16x32_bf16 v[8:11], v[170:173], v[236:239], v[8:11]
	v_mfma_f32_16x16x32_bf16 v[8:11], v[174:177], v[240:243], v[8:11]
	v_mfma_f32_16x16x32_bf16 v[12:15], v[132:135], v[240:243], v[12:15]
	v_mfma_f32_16x16x32_bf16 v[12:15], v[128:131], v[236:239], v[12:15]
	v_mfma_f32_16x16x32_bf16 v[52:55], v[196:199], v[212:215], v[52:55]
	v_mfma_f32_16x16x32_bf16 v[52:55], v[200:203], v[216:219], v[52:55]
	v_mfma_f32_16x16x32_bf16 v[48:51], v[208:211], v[216:219], v[48:51]
	v_mfma_f32_16x16x32_bf16 v[48:51], v[204:207], v[212:215], v[48:51]
	v_mfma_f32_16x16x32_bf16 v[32:35], v[204:207], v[220:223], v[32:35]
	v_mfma_f32_16x16x32_bf16 v[32:35], v[208:211], v[224:227], v[32:35]
	v_mfma_f32_16x16x32_bf16 v[36:39], v[200:203], v[224:227], v[36:39]
	v_mfma_f32_16x16x32_bf16 v[36:39], v[196:199], v[220:223], v[36:39]
	v_mfma_f32_16x16x32_bf16 v[20:23], v[196:199], v[228:231], v[20:23]
	v_mfma_f32_16x16x32_bf16 v[20:23], v[200:203], v[232:235], v[20:23]
	v_mfma_f32_16x16x32_bf16 v[16:19], v[208:211], v[232:235], v[16:19]
	v_mfma_f32_16x16x32_bf16 v[16:19], v[204:207], v[228:231], v[16:19]
	v_mfma_f32_16x16x32_bf16 v[0:3], v[204:207], v[236:239], v[0:3]
	v_mfma_f32_16x16x32_bf16 v[0:3], v[208:211], v[240:243], v[0:3]
	v_mfma_f32_16x16x32_bf16 v[4:7], v[200:203], v[240:243], v[4:7]
	v_mfma_f32_16x16x32_bf16 v[4:7], v[196:199], v[236:239], v[4:7]
	s_barrier
	s_add_i32 s41, 0, 0x18000
	v_add_u32_e32 v158, s41, v151
	s_add_i32 s42, 0, 0x1c000
	ds_read_b128 v[128:131], v158
	ds_read_b128 v[132:135], v158 offset:1024
	ds_read_b128 v[170:173], v158 offset:2048
	ds_read_b128 v[174:177], v158 offset:3072
	v_add_u32_e32 v158, s42, v151
	ds_read_b128 v[196:199], v158
	ds_read_b128 v[200:203], v158 offset:1024
	ds_read_b128 v[204:207], v158 offset:2048
	ds_read_b128 v[208:211], v158 offset:3072
	s_add_u32 s14, s14, 0x160000
	s_addc_u32 s15, s15, 0
	s_mov_b32 m0, s56
	ds_read_b128 v[212:215], v161 offset:32768
	ds_read_b128 v[216:219], v161 offset:33792
	ds_read_b128 v[220:223], v161 offset:34816
	ds_read_b128 v[224:227], v161 offset:35840
	ds_read_b128 v[228:231], v161 offset:36864
	ds_read_b128 v[232:235], v161 offset:37888
	ds_read_b128 v[236:239], v161 offset:38912
	ds_read_b128 v[240:243], v161 offset:39936
	global_load_lds_dwordx4 v142, s[14:15]
	s_mov_b32 m0, s57
	s_nop 0
	global_load_lds_dwordx4 v146, s[14:15]
	s_waitcnt vmcnt(8)
	s_waitcnt lgkmcnt(0)
	s_barrier
; #define PG8_STAGE(bufoff, gbase, voff) do { _Pragma("unroll") for (int _i = 0; _i < 2; ++_i) \
;         __builtin_amdgcn_global_load_lds((const unsigned*)((const char*)(gbase) + (voff)[_i]), (PG8_LAS unsigned*)(lds + (bufoff) + ldsw + _i * 8192), 16, 0, 0); } while (0)
; #define PG8_LDA(dst, b, h) do { _Pragma("unroll") for (int m = 0; m < 4; ++m) _Pragma("unroll") for (int k = 0; k < 2; ++k) dst[m][k] = *(const PG8_LAS bf16x8*)(lds + PG8_SA(b, h) + aoff + m * 2048 + k * 1024); } while (0)
; #define PG8_MMA(ai, bj, At, Bt) do { __builtin_amdgcn_s_setprio(1); _Pragma("unroll") for (int m = 0; m < 4; ++m) _Pragma("unroll") for (int n = 0; n < 2; ++n) _Pragma("unroll") for (int k = 0; k < 2; ++k) \
;         acc[ai][bj][m][n] = __builtin_amdgcn_mfma_f32_16x16x32_bf16(Bt[n][k], At[m][k], acc[ai][bj][m][n], 0, 0, 0); __builtin_amdgcn_s_setprio(0); } while (0)
; #define PG8_WAIT_V(n) asm volatile("s_waitcnt vmcnt(" #n ")" ::: "memory")
; #define PG8_WAIT_L(n) asm volatile("s_waitcnt lgkmcnt(" #n ")" ::: "memory")
; #define PG8_BAR __builtin_amdgcn_s_barrier()
; #define PG8_SCHED __builtin_amdgcn_sched_barrier(0)
; template <class Epi, class Sched, bool ALIGN_EPI = false, bool SP2 = false>
; __device__ __forceinline__ void gemm_phase(PG8_LAS unsigned char* lds, const Gemm g, const Sched& S, const Epi& E) {
;     ...
;             PG8_WAIT_V(8); PG8_WAIT_L(0); PG8_BAR; PG8_MMA(0, 0, At, B0); PG8_MMA(0, 1, At, B1); PG8_BAR; PG8_SCHED;
;             PG8_LDA(At, 1, 1); PG8_STAGE(PG8_SB(1, 0), b3, voffB); PG8_STAGE(PG8_SB(1, 1), b3 + hstep, voffB); PG8_STAGE(PG8_SA(1, 0), a3, voffA);
;             PG8_WAIT_V(8); PG8_WAIT_L(0); PG8_BAR; PG8_MMA(1, 0, At, B0); PG8_MMA(1, 1, At, B1); PG8_BAR; PG8_SCHED;
	s_waitcnt lgkmcnt(0)
	v_mfma_f32_16x16x32_bf16 v[124:127], v[128:131], v[212:215], v[124:127]
	v_mfma_f32_16x16x32_bf16 v[124:127], v[132:135], v[216:219], v[124:127]
	v_mfma_f32_16x16x32_bf16 v[120:123], v[174:177], v[216:219], v[120:123]
	v_mfma_f32_16x16x32_bf16 v[120:123], v[170:173], v[212:215], v[120:123]
	v_mfma_f32_16x16x32_bf16 v[104:107], v[170:173], v[220:223], v[104:107]
	v_mfma_f32_16x16x32_bf16 v[104:107], v[174:177], v[224:227], v[104:107]
	v_mfma_f32_16x16x32_bf16 v[108:111], v[132:135], v[224:227], v[108:111]
	v_mfma_f32_16x16x32_bf16 v[108:111], v[128:131], v[220:223], v[108:111]
	v_mfma_f32_16x16x32_bf16 v[92:95], v[128:131], v[228:231], v[92:95]
	v_mfma_f32_16x16x32_bf16 v[92:95], v[132:135], v[232:235], v[92:95]
	v_mfma_f32_16x16x32_bf16 v[88:91], v[174:177], v[232:235], v[88:91]
	v_mfma_f32_16x16x32_bf16 v[88:91], v[170:173], v[228:231], v[88:91]
	v_mfma_f32_16x16x32_bf16 v[72:75], v[170:173], v[236:239], v[72:75]
	v_mfma_f32_16x16x32_bf16 v[72:75], v[174:177], v[240:243], v[72:75]
	v_mfma_f32_16x16x32_bf16 v[76:79], v[132:135], v[240:243], v[76:79]
	v_mfma_f32_16x16x32_bf16 v[76:79], v[128:131], v[236:239], v[76:79]
	v_mfma_f32_16x16x32_bf16 v[116:119], v[196:199], v[212:215], v[116:119]
	v_mfma_f32_16x16x32_bf16 v[116:119], v[200:203], v[216:219], v[116:119]
	v_mfma_f32_16x16x32_bf16 v[112:115], v[208:211], v[216:219], v[112:115]
	v_mfma_f32_16x16x32_bf16 v[112:115], v[204:207], v[212:215], v[112:115]
	v_mfma_f32_16x16x32_bf16 v[96:99], v[204:207], v[220:223], v[96:99]
	v_mfma_f32_16x16x32_bf16 v[96:99], v[208:211], v[224:227], v[96:99]
	v_mfma_f32_16x16x32_bf16 v[100:103], v[200:203], v[224:227], v[100:103]
	v_mfma_f32_16x16x32_bf16 v[100:103], v[196:199], v[220:223], v[100:103]
	v_mfma_f32_16x16x32_bf16 v[84:87], v[196:199], v[228:231], v[84:87]
	v_mfma_f32_16x16x32_bf16 v[84:87], v[200:203], v[232:235], v[84:87]
	v_mfma_f32_16x16x32_bf16 v[80:83], v[208:211], v[232:235], v[80:83]
	v_mfma_f32_16x16x32_bf16 v[80:83], v[204:207], v[228:231], v[80:83]
	v_mfma_f32_16x16x32_bf16 v[64:67], v[204:207], v[236:239], v[64:67]
	v_mfma_f32_16x16x32_bf16 v[64:67], v[208:211], v[240:243], v[64:67]
	v_mfma_f32_16x16x32_bf16 v[68:71], v[200:203], v[240:243], v[68:71]
	v_mfma_f32_16x16x32_bf16 v[68:71], v[196:199], v[236:239], v[68:71]
	s_barrier
	s_add_i32 s14, s41, s53
	s_mov_b32 m0, s14
	ds_read_b128 v[212:215], v161 offset:49152
	ds_read_b128 v[216:219], v161 offset:50176
	ds_read_b128 v[220:223], v161 offset:51200
	ds_read_b128 v[224:227], v161 offset:52224
	ds_read_b128 v[228:231], v161 offset:53248
	ds_read_b128 v[232:235], v161 offset:54272
	ds_read_b128 v[236:239], v161 offset:55296
	ds_read_b128 v[240:243], v161 offset:56320
	global_load_lds_dwordx4 v144, s[98:99]
	s_add_i32 m0, s14, 0x2000
	s_add_u32 s12, s12, 0x160080
	s_addc_u32 s13, s13, 0
	s_add_i32 s14, s42, s53
	global_load_lds_dwordx4 v148, s[98:99]
	s_mov_b32 m0, s14
	s_nop 0
	global_load_lds_dwordx4 v144, s[12:13]
	s_add_i32 m0, s14, 0x2000
	s_nop 0
	global_load_lds_dwordx4 v148, s[12:13]
	s_mov_b32 m0, s84
	s_nop 0
	global_load_lds_dwordx4 v142, s[100:101]
	s_mov_b32 m0, s85
	s_nop 0
	global_load_lds_dwordx4 v146, s[100:101]
	s_waitcnt vmcnt(8)
	s_waitcnt lgkmcnt(0)
	s_barrier
	s_waitcnt lgkmcnt(0)
	v_mfma_f32_16x16x32_bf16 v[60:63], v[128:131], v[212:215], v[60:63]
	v_mfma_f32_16x16x32_bf16 v[60:63], v[132:135], v[216:219], v[60:63]
	v_mfma_f32_16x16x32_bf16 v[56:59], v[174:177], v[216:219], v[56:59]
	v_mfma_f32_16x16x32_bf16 v[56:59], v[170:173], v[212:215], v[56:59]
	v_mfma_f32_16x16x32_bf16 v[40:43], v[170:173], v[220:223], v[40:43]
	v_mfma_f32_16x16x32_bf16 v[40:43], v[174:177], v[224:227], v[40:43]
	v_mfma_f32_16x16x32_bf16 v[44:47], v[132:135], v[224:227], v[44:47]
	v_mfma_f32_16x16x32_bf16 v[44:47], v[128:131], v[220:223], v[44:47]
	v_mfma_f32_16x16x32_bf16 v[28:31], v[128:131], v[228:231], v[28:31]
	v_mfma_f32_16x16x32_bf16 v[28:31], v[132:135], v[232:235], v[28:31]
	v_mfma_f32_16x16x32_bf16 v[24:27], v[174:177], v[232:235], v[24:27]
	v_mfma_f32_16x16x32_bf16 v[24:27], v[170:173], v[228:231], v[24:27]
	v_mfma_f32_16x16x32_bf16 v[8:11], v[170:173], v[236:239], v[8:11]
	v_mfma_f32_16x16x32_bf16 v[8:11], v[174:177], v[240:243], v[8:11]
	v_mfma_f32_16x16x32_bf16 v[12:15], v[132:135], v[240:243], v[12:15]
	v_mfma_f32_16x16x32_bf16 v[12:15], v[128:131], v[236:239], v[12:15]
	v_mfma_f32_16x16x32_bf16 v[52:55], v[196:199], v[212:215], v[52:55]
	v_mfma_f32_16x16x32_bf16 v[52:55], v[200:203], v[216:219], v[52:55]
	v_mfma_f32_16x16x32_bf16 v[48:51], v[208:211], v[216:219], v[48:51]
	v_mfma_f32_16x16x32_bf16 v[48:51], v[204:207], v[212:215], v[48:51]
	v_mfma_f32_16x16x32_bf16 v[32:35], v[204:207], v[220:223], v[32:35]
	v_mfma_f32_16x16x32_bf16 v[32:35], v[208:211], v[224:227], v[32:35]
	v_mfma_f32_16x16x32_bf16 v[36:39], v[200:203], v[224:227], v[36:39]
	v_mfma_f32_16x16x32_bf16 v[36:39], v[196:199], v[220:223], v[36:39]
	v_mfma_f32_16x16x32_bf16 v[20:23], v[196:199], v[228:231], v[20:23]
	v_mfma_f32_16x16x32_bf16 v[20:23], v[200:203], v[232:235], v[20:23]
	v_mfma_f32_16x16x32_bf16 v[16:19], v[208:211], v[232:235], v[16:19]
	v_mfma_f32_16x16x32_bf16 v[16:19], v[204:207], v[228:231], v[16:19]
	v_mfma_f32_16x16x32_bf16 v[0:3], v[204:207], v[236:239], v[0:3]
	v_mfma_f32_16x16x32_bf16 v[0:3], v[208:211], v[240:243], v[0:3]
	v_mfma_f32_16x16x32_bf16 v[4:7], v[200:203], v[240:243], v[4:7]
	v_mfma_f32_16x16x32_bf16 v[4:7], v[196:199], v[236:239], v[4:7]
	s_barrier
	s_add_i32 s40, s40, 2
	s_add_u32 s10, s10, 0x100
	s_addc_u32 s11, s11, 0
	s_add_u32 s17, s17, 0x100
	s_addc_u32 s39, s39, 0
	s_cmpk_gt_u32 s40, 0x55
	s_cbranch_scc0 .LBB0_308
	s_setprio 0
	s_and_b64 vcc, exec, s[74:75]
	s_cbranch_vccz .LBB0_311
	s_barrier

;     __device__ __forceinline__ bool next(int i, Unit& u) const { if (i > 0 || c >= nitems) return false; u.pm = 64; u.pn = c % npn; u.k0 = (c / npn) * kslice; return true; }
; #define PG8_STAGE(bufoff, gbase, voff) do { _Pragma("unroll") for (int _i = 0; _i < 2; ++_i) \
;         __builtin_amdgcn_global_load_lds((const unsigned*)((const char*)(gbase) + (voff)[_i]), (PG8_LAS unsigned*)(lds + (bufoff) + ldsw + _i * 8192), 16, 0, 0); } while (0)
; #define PG8_LDA(dst, b, h) do { _Pragma("unroll") for (int m = 0; m < 4; ++m) _Pragma("unroll") for (int k = 0; k < 2; ++k) dst[m][k] = *(const PG8_LAS bf16x8*)(lds + PG8_SA(b, h) + aoff + m * 2048 + k * 1024); } while (0)
; #define PG8_LDB(dst, b, h) do { _Pragma("unroll") for (int n = 0; n < 2; ++n) _Pragma("unroll") for (int k = 0; k < 2; ++k) dst[n][k] = *(const PG8_LAS bf16x8*)(lds + PG8_SB(b, h) + boff + n * 2048 + k * 1024); } while (0)
; #define PG8_SCHED __builtin_amdgcn_sched_barrier(0)
; template <class Epi, class Sched, bool ALIGN_EPI = false, bool SP2 = false>
; __device__ __forceinline__ void gemm_phase(PG8_LAS unsigned char* lds, const Gemm g, const Sched& S, const Epi& E) {
;     ...
;         const bool has_next = S.next(ui + 1, nxt);
;         const char* nA = has_next ? (const char*)g.A + (size_t)nxt.pm * tstep + (size_t)nxt.k0 * 2 : cA; const char* nB = has_next ? (const char*)g.Bt + (size_t)nxt.pn * tstep + (size_t)nxt.k0 * 2 : cB;
;         for (int t = 0; t < nt; t += 2) {
;             const bool last = (t == nt - 2);
;             const char* a1 = cA + (size_t)(t + 1) * kstep;
;             const char* a2 = last ? nA : cA + (size_t)(t + 2) * kstep; const char* b2 = last ? nB : cB + (size_t)(t + 2) * kstep;
;             const char* a3 = a2 + kstep; const char* b3 = b2 + kstep;
;             if (last && has_next) S.a_ready(nxt);
;             if constexpr (SP2) {
;             PG8_LDB(B0, 0, 0); PG8_LDB(B1, 0, 1); PG8_SCHED; PG8_LDA(At, 0, 0); PG8_STAGE(PG8_SA(1, 1), a1 + hstep, voffA);
;     ...
;         for (int a = 0; a < 2; ++a)
; #pragma unroll
;             for (int b = 0; b < 2; ++b)
; #pragma unroll
;                 for (int m = 0; m < 4; ++m)
; #pragma unroll
;                     for (int n = 0; n < 2; ++n) acc[a][b][m][n] = (f32x4){0.f, 0.f, 0.f, 0.f};
.LBB0_622:
	s_ashr_i32 s71, s70, 31
	s_lshl_b64 s[36:37], s[70:71], 20
	s_add_u32 s72, s33, s36
	s_addc_u32 s73, s82, s37
	s_and_b64 s[36:37], s[8:9], exec
	s_cselect_b32 s36, s73, s11
	s_cselect_b32 s37, s72, s10
	s_ashr_i32 s69, s68, 31
	s_lshl_b64 s[38:39], s[68:69], 20
	s_add_u32 s74, s83, s38
	s_addc_u32 s75, s84, s39
	s_and_b64 s[38:39], s[8:9], exec
	s_cselect_b32 s38, s75, s77
	s_cselect_b32 s39, s74, s76
	s_add_u32 s10, s10, 0x80080
	s_addc_u32 s11, s11, 0
	s_add_u32 s40, s76, 0x100
	v_mov_b32_e32 v0, 0
	s_addc_u32 s41, s77, 0
	s_mov_b32 s42, -2
	v_mov_b32_e32 v1, v0
	v_mov_b32_e32 v2, v0
	v_mov_b32_e32 v3, v0
	v_mov_b32_e32 v8, v0
	v_mov_b32_e32 v9, v0
	v_mov_b32_e32 v10, v0
	v_mov_b32_e32 v11, v0
	v_mov_b32_e32 v16, v0
	v_mov_b32_e32 v17, v0
	v_mov_b32_e32 v18, v0
	v_mov_b32_e32 v19, v0
	v_mov_b32_e32 v20, v0
	v_mov_b32_e32 v21, v0
	v_mov_b32_e32 v22, v0
	v_mov_b32_e32 v23, v0
	v_mov_b32_e32 v32, v0
	v_mov_b32_e32 v33, v0
	v_mov_b32_e32 v34, v0
	v_mov_b32_e32 v35, v0
	v_mov_b32_e32 v36, v0
	v_mov_b32_e32 v37, v0
	v_mov_b32_e32 v38, v0
	v_mov_b32_e32 v39, v0
	v_mov_b32_e32 v48, v0
	v_mov_b32_e32 v49, v0
	v_mov_b32_e32 v50, v0
	v_mov_b32_e32 v51, v0
	v_mov_b32_e32 v52, v0
	v_mov_b32_e32 v53, v0
	v_mov_b32_e32 v54, v0
	v_mov_b32_e32 v55, v0
	v_mov_b32_e32 v4, v0
	v_mov_b32_e32 v5, v0
	v_mov_b32_e32 v6, v0
	v_mov_b32_e32 v7, v0
	v_mov_b32_e32 v12, v0
	v_mov_b32_e32 v13, v0
	v_mov_b32_e32 v14, v0
	v_mov_b32_e32 v15, v0
	v_mov_b32_e32 v24, v0
	v_mov_b32_e32 v25, v0
	v_mov_b32_e32 v26, v0
	v_mov_b32_e32 v27, v0
	v_mov_b32_e32 v28, v0
	v_mov_b32_e32 v29, v0
	v_mov_b32_e32 v30, v0
	v_mov_b32_e32 v31, v0
	v_mov_b32_e32 v40, v0
	v_mov_b32_e32 v41, v0
	v_mov_b32_e32 v42, v0
	v_mov_b32_e32 v43, v0
	v_mov_b32_e32 v44, v0
	v_mov_b32_e32 v45, v0
	v_mov_b32_e32 v46, v0
	v_mov_b32_e32 v47, v0
	v_mov_b32_e32 v56, v0
	v_mov_b32_e32 v57, v0
	v_mov_b32_e32 v58, v0
	v_mov_b32_e32 v59, v0
	v_mov_b32_e32 v60, v0
	v_mov_b32_e32 v61, v0
	v_mov_b32_e32 v62, v0
	v_mov_b32_e32 v63, v0
	v_mov_b32_e32 v64, v0
	v_mov_b32_e32 v65, v0
	v_mov_b32_e32 v66, v0
	v_mov_b32_e32 v67, v0
	v_mov_b32_e32 v68, v0
	v_mov_b32_e32 v69, v0
	v_mov_b32_e32 v70, v0
	v_mov_b32_e32 v71, v0
	v_mov_b32_e32 v80, v0
	v_mov_b32_e32 v81, v0
	v_mov_b32_e32 v82, v0
	v_mov_b32_e32 v83, v0
	v_mov_b32_e32 v84, v0
	v_mov_b32_e32 v85, v0
	v_mov_b32_e32 v86, v0
	v_mov_b32_e32 v87, v0
	v_mov_b32_e32 v96, v0
	v_mov_b32_e32 v97, v0
	v_mov_b32_e32 v98, v0
	v_mov_b32_e32 v99, v0
	v_mov_b32_e32 v100, v0
	v_mov_b32_e32 v101, v0
	v_mov_b32_e32 v102, v0
	v_mov_b32_e32 v103, v0
	v_mov_b32_e32 v112, v0
	v_mov_b32_e32 v113, v0
	v_mov_b32_e32 v114, v0
	v_mov_b32_e32 v115, v0
	v_mov_b32_e32 v116, v0
	v_mov_b32_e32 v117, v0
	v_mov_b32_e32 v118, v0
	v_mov_b32_e32 v119, v0
	v_mov_b32_e32 v72, v0
	v_mov_b32_e32 v73, v0
	v_mov_b32_e32 v74, v0
	v_mov_b32_e32 v75, v0
	v_mov_b32_e32 v76, v0
	v_mov_b32_e32 v77, v0
	v_mov_b32_e32 v78, v0
	v_mov_b32_e32 v79, v0
	v_mov_b32_e32 v88, v0
	v_mov_b32_e32 v89, v0
	v_mov_b32_e32 v90, v0
	v_mov_b32_e32 v91, v0
	v_mov_b32_e32 v92, v0
	v_mov_b32_e32 v93, v0
	v_mov_b32_e32 v94, v0
	v_mov_b32_e32 v95, v0
	v_mov_b32_e32 v104, v0
	v_mov_b32_e32 v105, v0
	v_mov_b32_e32 v106, v0
	v_mov_b32_e32 v107, v0
	v_mov_b32_e32 v108, v0
	v_mov_b32_e32 v109, v0
	v_mov_b32_e32 v110, v0
	v_mov_b32_e32 v111, v0
	v_mov_b32_e32 v120, v0
	v_mov_b32_e32 v121, v0
	v_mov_b32_e32 v122, v0
	v_mov_b32_e32 v123, v0
	v_mov_b32_e32 v124, v0
	v_mov_b32_e32 v125, v0
	v_mov_b32_e32 v126, v0
	v_mov_b32_e32 v127, v0
	s_and_b64 vcc, exec, s[66:67]
	s_cbranch_vccnz .Lsp_skip_4
	s_setprio 1
.Lsp_skip_4:
.LBB0_623:
	ds_read_b128 v[162:165], v147
	ds_read_b128 v[166:169], v147 offset:1024
	ds_read_b128 v[172:175], v147 offset:2048
	ds_read_b128 v[196:199], v147 offset:3072
	ds_read_b128 v[200:203], v149
	ds_read_b128 v[204:207], v149 offset:1024
	ds_read_b128 v[208:211], v149 offset:2048
	ds_read_b128 v[212:215], v149 offset:3072
	s_add_u32 s43, s10, 0xfff80080
	s_addc_u32 s44, s11, -1
	s_cmp_eq_u32 s42, 28
	s_cselect_b32 s79, s36, s44
	s_cselect_b32 s78, s37, s43
	s_cselect_b32 s77, s38, s41
	s_cselect_b32 s76, s39, s40
	s_add_i32 m0, s86, 0xc000
	ds_read_b128 v[216:219], v159
	ds_read_b128 v[220:223], v159 offset:1024
	ds_read_b128 v[224:227], v159 offset:2048
	ds_read_b128 v[228:231], v159 offset:3072
	ds_read_b128 v[232:235], v159 offset:4096
	ds_read_b128 v[236:239], v159 offset:5120
	ds_read_b128 v[240:243], v159 offset:6144
	ds_read_b128 v[244:247], v159 offset:7168
	global_load_lds_dwordx4 v132, s[10:11]
	s_add_i32 m0, s86, 0xe000
	s_nop 0
	global_load_lds_dwordx4 v134, s[10:11]
	s_waitcnt vmcnt(8)
	s_waitcnt lgkmcnt(0)
	s_barrier
; #define PG8_STAGE(bufoff, gbase, voff) do { _Pragma("unroll") for (int _i = 0; _i < 2; ++_i) \
;         __builtin_amdgcn_global_load_lds((const unsigned*)((const char*)(gbase) + (voff)[_i]), (PG8_LAS unsigned*)(lds + (bufoff) + ldsw + _i * 8192), 16, 0, 0); } while (0)
; #define PG8_LDA(dst, b, h) do { _Pragma("unroll") for (int m = 0; m < 4; ++m) _Pragma("unroll") for (int k = 0; k < 2; ++k) dst[m][k] = *(const PG8_LAS bf16x8*)(lds + PG8_SA(b, h) + aoff + m * 2048 + k * 1024); } while (0)
; #define PG8_MMA(ai, bj, At, Bt) do { __builtin_amdgcn_s_setprio(1); _Pragma("unroll") for (int m = 0; m < 4; ++m) _Pragma("unroll") for (int n = 0; n < 2; ++n) _Pragma("unroll") for (int k = 0; k < 2; ++k) \
;         acc[ai][bj][m][n] = __builtin_amdgcn_mfma_f32_16x16x32_bf16(Bt[n][k], At[m][k], acc[ai][bj][m][n], 0, 0, 0); __builtin_amdgcn_s_setprio(0); } while (0)
; #define PG8_WAIT_V(n) asm volatile("s_waitcnt vmcnt(" #n ")" ::: "memory")
; #define PG8_WAIT_L(n) asm volatile("s_waitcnt lgkmcnt(" #n ")" ::: "memory")
; #define PG8_BAR __builtin_amdgcn_s_barrier()
; #define PG8_SCHED __builtin_amdgcn_sched_barrier(0)
; template <class Epi, class Sched, bool ALIGN_EPI = false, bool SP2 = false>
; __device__ __forceinline__ void gemm_phase(PG8_LAS unsigned char* lds, const Gemm g, const Sched& S, const Epi& E) {
;     ...
;             PG8_WAIT_V(8); PG8_WAIT_L(0); PG8_BAR; PG8_MMA(0, 0, At, B0); PG8_MMA(0, 1, At, B1); PG8_BAR; PG8_SCHED;
;             PG8_LDA(At, 0, 1); PG8_STAGE(PG8_SB(0, 0), b2, voffB); PG8_STAGE(PG8_SB(0, 1), b2 + hstep, voffB); PG8_STAGE(PG8_SA(0, 0), a2, voffA);
;             PG8_WAIT_V(8); PG8_WAIT_L(0); PG8_BAR; PG8_MMA(1, 0, At, B0); PG8_MMA(1, 1, At, B1); PG8_BAR; PG8_SCHED;
	s_waitcnt lgkmcnt(0)
	v_mfma_f32_16x16x32_bf16 v[124:127], v[162:165], v[216:219], v[124:127]
	v_mfma_f32_16x16x32_bf16 v[124:127], v[166:169], v[220:223], v[124:127]
	v_mfma_f32_16x16x32_bf16 v[120:123], v[196:199], v[220:223], v[120:123]
	v_mfma_f32_16x16x32_bf16 v[120:123], v[172:175], v[216:219], v[120:123]
	v_mfma_f32_16x16x32_bf16 v[104:107], v[172:175], v[224:227], v[104:107]
	v_mfma_f32_16x16x32_bf16 v[104:107], v[196:199], v[228:231], v[104:107]
	v_mfma_f32_16x16x32_bf16 v[108:111], v[166:169], v[228:231], v[108:111]
	v_mfma_f32_16x16x32_bf16 v[108:111], v[162:165], v[224:227], v[108:111]
	v_mfma_f32_16x16x32_bf16 v[92:95], v[162:165], v[232:235], v[92:95]
	v_mfma_f32_16x16x32_bf16 v[92:95], v[166:169], v[236:239], v[92:95]
	v_mfma_f32_16x16x32_bf16 v[88:91], v[196:199], v[236:239], v[88:91]
	v_mfma_f32_16x16x32_bf16 v[88:91], v[172:175], v[232:235], v[88:91]
	v_mfma_f32_16x16x32_bf16 v[72:75], v[172:175], v[240:243], v[72:75]
	v_mfma_f32_16x16x32_bf16 v[72:75], v[196:199], v[244:247], v[72:75]
	v_mfma_f32_16x16x32_bf16 v[76:79], v[166:169], v[244:247], v[76:79]
	v_mfma_f32_16x16x32_bf16 v[76:79], v[162:165], v[240:243], v[76:79]
	v_mfma_f32_16x16x32_bf16 v[116:119], v[200:203], v[216:219], v[116:119]
	v_mfma_f32_16x16x32_bf16 v[116:119], v[204:207], v[220:223], v[116:119]
	v_mfma_f32_16x16x32_bf16 v[112:115], v[212:215], v[220:223], v[112:115]
	v_mfma_f32_16x16x32_bf16 v[112:115], v[208:211], v[216:219], v[112:115]
	v_mfma_f32_16x16x32_bf16 v[96:99], v[208:211], v[224:227], v[96:99]
	v_mfma_f32_16x16x32_bf16 v[96:99], v[212:215], v[228:231], v[96:99]
	v_mfma_f32_16x16x32_bf16 v[100:103], v[204:207], v[228:231], v[100:103]
	v_mfma_f32_16x16x32_bf16 v[100:103], v[200:203], v[224:227], v[100:103]
	v_mfma_f32_16x16x32_bf16 v[84:87], v[200:203], v[232:235], v[84:87]
	v_mfma_f32_16x16x32_bf16 v[84:87], v[204:207], v[236:239], v[84:87]
	v_mfma_f32_16x16x32_bf16 v[80:83], v[212:215], v[236:239], v[80:83]
	v_mfma_f32_16x16x32_bf16 v[80:83], v[208:211], v[232:235], v[80:83]
	v_mfma_f32_16x16x32_bf16 v[64:67], v[208:211], v[240:243], v[64:67]
	v_mfma_f32_16x16x32_bf16 v[64:67], v[212:215], v[244:247], v[64:67]
	v_mfma_f32_16x16x32_bf16 v[68:71], v[204:207], v[244:247], v[68:71]
	v_mfma_f32_16x16x32_bf16 v[68:71], v[200:203], v[240:243], v[68:71]
	s_barrier
	s_add_u32 s98, s76, 0x80
	s_addc_u32 s99, s77, 0
	s_add_u32 s100, s78, 0x80
	s_addc_u32 s101, s79, 0
	s_add_i32 s43, s3, s85
	s_mov_b32 m0, s43
	ds_read_b128 v[216:219], v159 offset:16384
	ds_read_b128 v[220:223], v159 offset:17408
	ds_read_b128 v[224:227], v159 offset:18432
	ds_read_b128 v[228:231], v159 offset:19456
	ds_read_b128 v[232:235], v159 offset:20480
	ds_read_b128 v[236:239], v159 offset:21504
	ds_read_b128 v[240:243], v159 offset:22528
	ds_read_b128 v[244:247], v159 offset:23552
	global_load_lds_dwordx4 v152, s[76:77]
	s_add_i32 m0, s43, 0x2000
	s_add_u32 s44, s76, 0x80000
	s_addc_u32 s45, s77, 0
	s_add_i32 s43, s52, s85
	global_load_lds_dwordx4 v156, s[76:77]
	s_mov_b32 m0, s43
	s_nop 0
	global_load_lds_dwordx4 v152, s[44:45]
	s_add_i32 m0, s43, 0x2000
	s_nop 0
	global_load_lds_dwordx4 v156, s[44:45]
	s_mov_b32 m0, s86
	s_nop 0
	global_load_lds_dwordx4 v150, s[78:79]
	s_mov_b32 m0, s87
	s_nop 0
	global_load_lds_dwordx4 v154, s[78:79]
	s_waitcnt vmcnt(8)
	s_waitcnt lgkmcnt(0)
	s_barrier
	s_waitcnt lgkmcnt(0)
	v_mfma_f32_16x16x32_bf16 v[60:63], v[162:165], v[216:219], v[60:63]
	v_mfma_f32_16x16x32_bf16 v[60:63], v[166:169], v[220:223], v[60:63]
	v_mfma_f32_16x16x32_bf16 v[56:59], v[196:199], v[220:223], v[56:59]
	v_mfma_f32_16x16x32_bf16 v[56:59], v[172:175], v[216:219], v[56:59]
	v_mfma_f32_16x16x32_bf16 v[40:43], v[172:175], v[224:227], v[40:43]
	v_mfma_f32_16x16x32_bf16 v[40:43], v[196:199], v[228:231], v[40:43]
	v_mfma_f32_16x16x32_bf16 v[44:47], v[166:169], v[228:231], v[44:47]
	v_mfma_f32_16x16x32_bf16 v[44:47], v[162:165], v[224:227], v[44:47]
	v_mfma_f32_16x16x32_bf16 v[28:31], v[162:165], v[232:235], v[28:31]
	v_mfma_f32_16x16x32_bf16 v[28:31], v[166:169], v[236:239], v[28:31]
	v_mfma_f32_16x16x32_bf16 v[24:27], v[196:199], v[236:239], v[24:27]
	v_mfma_f32_16x16x32_bf16 v[24:27], v[172:175], v[232:235], v[24:27]
	v_mfma_f32_16x16x32_bf16 v[4:7], v[172:175], v[240:243], v[4:7]
	v_mfma_f32_16x16x32_bf16 v[4:7], v[196:199], v[244:247], v[4:7]
	v_mfma_f32_16x16x32_bf16 v[12:15], v[166:169], v[244:247], v[12:15]
	v_mfma_f32_16x16x32_bf16 v[12:15], v[162:165], v[240:243], v[12:15]
	v_mfma_f32_16x16x32_bf16 v[52:55], v[200:203], v[216:219], v[52:55]
	v_mfma_f32_16x16x32_bf16 v[52:55], v[204:207], v[220:223], v[52:55]
	v_mfma_f32_16x16x32_bf16 v[48:51], v[212:215], v[220:223], v[48:51]
	v_mfma_f32_16x16x32_bf16 v[48:51], v[208:211], v[216:219], v[48:51]
	v_mfma_f32_16x16x32_bf16 v[32:35], v[208:211], v[224:227], v[32:35]
	v_mfma_f32_16x16x32_bf16 v[32:35], v[212:215], v[228:231], v[32:35]
	v_mfma_f32_16x16x32_bf16 v[36:39], v[204:207], v[228:231], v[36:39]
	v_mfma_f32_16x16x32_bf16 v[36:39], v[200:203], v[224:227], v[36:39]
	v_mfma_f32_16x16x32_bf16 v[20:23], v[200:203], v[232:235], v[20:23]
	v_mfma_f32_16x16x32_bf16 v[20:23], v[204:207], v[236:239], v[20:23]
	v_mfma_f32_16x16x32_bf16 v[16:19], v[212:215], v[236:239], v[16:19]
	v_mfma_f32_16x16x32_bf16 v[16:19], v[208:211], v[232:235], v[16:19]
	v_mfma_f32_16x16x32_bf16 v[0:3], v[208:211], v[240:243], v[0:3]
	v_mfma_f32_16x16x32_bf16 v[0:3], v[212:215], v[244:247], v[0:3]
	v_mfma_f32_16x16x32_bf16 v[8:11], v[204:207], v[244:247], v[8:11]
	v_mfma_f32_16x16x32_bf16 v[8:11], v[200:203], v[240:243], v[8:11]
	s_barrier
; #define PG8_STAGE(bufoff, gbase, voff) do { _Pragma("unroll") for (int _i = 0; _i < 2; ++_i) \
;         __builtin_amdgcn_global_load_lds((const unsigned*)((const char*)(gbase) + (voff)[_i]), (PG8_LAS unsigned*)(lds + (bufoff) + ldsw + _i * 8192), 16, 0, 0); } while (0)
; #define PG8_LDA(dst, b, h) do { _Pragma("unroll") for (int m = 0; m < 4; ++m) _Pragma("unroll") for (int k = 0; k < 2; ++k) dst[m][k] = *(const PG8_LAS bf16x8*)(lds + PG8_SA(b, h) + aoff + m * 2048 + k * 1024); } while (0)
; #define PG8_LDB(dst, b, h) do { _Pragma("unroll") for (int n = 0; n < 2; ++n) _Pragma("unroll") for (int k = 0; k < 2; ++k) dst[n][k] = *(const PG8_LAS bf16x8*)(lds + PG8_SB(b, h) + boff + n * 2048 + k * 1024); } while (0)
; #define PG8_MMA(ai, bj, At, Bt) do { __builtin_amdgcn_s_setprio(1); _Pragma("unroll") for (int m = 0; m < 4; ++m) _Pragma("unroll") for (int n = 0; n < 2; ++n) _Pragma("unroll") for (int k = 0; k < 2; ++k) \
;         acc[ai][bj][m][n] = __builtin_amdgcn_mfma_f32_16x16x32_bf16(Bt[n][k], At[m][k], acc[ai][bj][m][n], 0, 0, 0); __builtin_amdgcn_s_setprio(0); } while (0)
; #define PG8_WAIT_V(n) asm volatile("s_waitcnt vmcnt(" #n ")" ::: "memory")
; #define PG8_WAIT_L(n) asm volatile("s_waitcnt lgkmcnt(" #n ")" ::: "memory")
; #define PG8_BAR __builtin_amdgcn_s_barrier()
; #define PG8_SCHED __builtin_amdgcn_sched_barrier(0)
;     __device__ __forceinline__ void operator()(const f32x4 (&acc)[2][2][4][2], const Unit& u, int wr, int wc, int fr, int fq) const {
;         const int row0 = u.pm * BM + wr * 64 + fr, pn = u.pn, cw = wc * 32 + 8 * fq;
;         if (pn >= 10) {
; template <class Epi, class Sched, bool ALIGN_EPI = false, bool SP2 = false>
; __device__ __forceinline__ void gemm_phase(PG8_LAS unsigned char* lds, const Gemm g, const Sched& S, const Epi& E) {
;     ...
;             PG8_LDB(B0, 1, 0); PG8_LDB(B1, 1, 1); PG8_SCHED; PG8_LDA(At, 1, 0); PG8_STAGE(PG8_SA(0, 1), a2 + hstep, voffA);
;             PG8_WAIT_V(8); PG8_WAIT_L(0); PG8_BAR; PG8_MMA(0, 0, At, B0); PG8_MMA(0, 1, At, B1); PG8_BAR; PG8_SCHED;
;             PG8_LDA(At, 1, 1); PG8_STAGE(PG8_SB(1, 0), b3, voffB); PG8_STAGE(PG8_SB(1, 1), b3 + hstep, voffB); PG8_STAGE(PG8_SA(1, 0), a3, voffA);
;             PG8_WAIT_V(8); PG8_WAIT_L(0); PG8_BAR; PG8_MMA(1, 0, At, B0); PG8_MMA(1, 1, At, B1); PG8_BAR; PG8_SCHED;
;     ...
;         if constexpr (ALIGN_EPI) { if (wr == 0) PG8_BAR; }
	s_add_i32 s43, 0, 0x18000
	v_add_u32_e32 v128, s43, v145
	s_add_i32 s46, 0, 0x1c000
	ds_read_b128 v[162:165], v128
	ds_read_b128 v[166:169], v128 offset:1024
	ds_read_b128 v[172:175], v128 offset:2048
	ds_read_b128 v[196:199], v128 offset:3072
	v_add_u32_e32 v128, s46, v145
	ds_read_b128 v[200:203], v128
	ds_read_b128 v[204:207], v128 offset:1024
	ds_read_b128 v[208:211], v128 offset:2048
	ds_read_b128 v[212:215], v128 offset:3072
	s_add_u32 s44, s78, 0x80000
	s_addc_u32 s45, s79, 0
	s_mov_b32 m0, s91
	ds_read_b128 v[216:219], v159 offset:32768
	ds_read_b128 v[220:223], v159 offset:33792
	ds_read_b128 v[224:227], v159 offset:34816
	ds_read_b128 v[228:231], v159 offset:35840
	ds_read_b128 v[232:235], v159 offset:36864
	ds_read_b128 v[236:239], v159 offset:37888
	ds_read_b128 v[240:243], v159 offset:38912
	ds_read_b128 v[244:247], v159 offset:39936
	global_load_lds_dwordx4 v150, s[44:45]
	s_mov_b32 m0, s92
	s_nop 0
	global_load_lds_dwordx4 v154, s[44:45]
	s_waitcnt vmcnt(8)
	s_waitcnt lgkmcnt(0)
	s_barrier
	s_waitcnt lgkmcnt(0)
	v_mfma_f32_16x16x32_bf16 v[124:127], v[162:165], v[216:219], v[124:127]
	v_mfma_f32_16x16x32_bf16 v[124:127], v[166:169], v[220:223], v[124:127]
	v_mfma_f32_16x16x32_bf16 v[120:123], v[196:199], v[220:223], v[120:123]
	v_mfma_f32_16x16x32_bf16 v[120:123], v[172:175], v[216:219], v[120:123]
	v_mfma_f32_16x16x32_bf16 v[104:107], v[172:175], v[224:227], v[104:107]
	v_mfma_f32_16x16x32_bf16 v[104:107], v[196:199], v[228:231], v[104:107]
	v_mfma_f32_16x16x32_bf16 v[108:111], v[166:169], v[228:231], v[108:111]
	v_mfma_f32_16x16x32_bf16 v[108:111], v[162:165], v[224:227], v[108:111]
	v_mfma_f32_16x16x32_bf16 v[92:95], v[162:165], v[232:235], v[92:95]
	v_mfma_f32_16x16x32_bf16 v[92:95], v[166:169], v[236:239], v[92:95]
	v_mfma_f32_16x16x32_bf16 v[88:91], v[196:199], v[236:239], v[88:91]
	v_mfma_f32_16x16x32_bf16 v[88:91], v[172:175], v[232:235], v[88:91]
	v_mfma_f32_16x16x32_bf16 v[72:75], v[172:175], v[240:243], v[72:75]
	v_mfma_f32_16x16x32_bf16 v[72:75], v[196:199], v[244:247], v[72:75]
	v_mfma_f32_16x16x32_bf16 v[76:79], v[166:169], v[244:247], v[76:79]
	v_mfma_f32_16x16x32_bf16 v[76:79], v[162:165], v[240:243], v[76:79]
	v_mfma_f32_16x16x32_bf16 v[116:119], v[200:203], v[216:219], v[116:119]
	v_mfma_f32_16x16x32_bf16 v[116:119], v[204:207], v[220:223], v[116:119]
	v_mfma_f32_16x16x32_bf16 v[112:115], v[212:215], v[220:223], v[112:115]
	v_mfma_f32_16x16x32_bf16 v[112:115], v[208:211], v[216:219], v[112:115]
	v_mfma_f32_16x16x32_bf16 v[96:99], v[208:211], v[224:227], v[96:99]
	v_mfma_f32_16x16x32_bf16 v[96:99], v[212:215], v[228:231], v[96:99]
	v_mfma_f32_16x16x32_bf16 v[100:103], v[204:207], v[228:231], v[100:103]
	v_mfma_f32_16x16x32_bf16 v[100:103], v[200:203], v[224:227], v[100:103]
	v_mfma_f32_16x16x32_bf16 v[84:87], v[200:203], v[232:235], v[84:87]
	v_mfma_f32_16x16x32_bf16 v[84:87], v[204:207], v[236:239], v[84:87]
	v_mfma_f32_16x16x32_bf16 v[80:83], v[212:215], v[236:239], v[80:83]
	v_mfma_f32_16x16x32_bf16 v[80:83], v[208:211], v[232:235], v[80:83]
	v_mfma_f32_16x16x32_bf16 v[64:67], v[208:211], v[240:243], v[64:67]
	v_mfma_f32_16x16x32_bf16 v[64:67], v[212:215], v[244:247], v[64:67]
	v_mfma_f32_16x16x32_bf16 v[68:71], v[204:207], v[244:247], v[68:71]
	v_mfma_f32_16x16x32_bf16 v[68:71], v[200:203], v[240:243], v[68:71]
	s_barrier
	s_add_i32 s43, s43, s85
	s_mov_b32 m0, s43
	ds_read_b128 v[216:219], v159 offset:49152
	ds_read_b128 v[220:223], v159 offset:50176
	ds_read_b128 v[224:227], v159 offset:51200
	ds_read_b128 v[228:231], v159 offset:52224
	ds_read_b128 v[232:235], v159 offset:53248
	ds_read_b128 v[236:239], v159 offset:54272
	ds_read_b128 v[240:243], v159 offset:55296
	ds_read_b128 v[244:247], v159 offset:56320
	global_load_lds_dwordx4 v152, s[98:99]
	s_add_i32 m0, s43, 0x2000
	s_add_u32 s44, s76, 0x80080
	s_addc_u32 s45, s77, 0
	s_add_i32 s43, s46, s85
	global_load_lds_dwordx4 v156, s[98:99]
	s_mov_b32 m0, s43
	s_nop 0
	global_load_lds_dwordx4 v152, s[44:45]
	s_add_i32 m0, s43, 0x2000
	s_nop 0
	global_load_lds_dwordx4 v156, s[44:45]
	s_mov_b32 m0, s93
	s_nop 0
	global_load_lds_dwordx4 v150, s[100:101]
	s_mov_b32 m0, s94
	s_nop 0
	global_load_lds_dwordx4 v154, s[100:101]
	s_waitcnt vmcnt(8)
	s_waitcnt lgkmcnt(0)
	s_barrier
	s_waitcnt lgkmcnt(0)
	v_mfma_f32_16x16x32_bf16 v[60:63], v[162:165], v[216:219], v[60:63]
	v_mfma_f32_16x16x32_bf16 v[60:63], v[166:169], v[220:223], v[60:63]
	v_mfma_f32_16x16x32_bf16 v[56:59], v[196:199], v[220:223], v[56:59]
	v_mfma_f32_16x16x32_bf16 v[56:59], v[172:175], v[216:219], v[56:59]
	v_mfma_f32_16x16x32_bf16 v[40:43], v[172:175], v[224:227], v[40:43]
	v_mfma_f32_16x16x32_bf16 v[40:43], v[196:199], v[228:231], v[40:43]
	v_mfma_f32_16x16x32_bf16 v[44:47], v[166:169], v[228:231], v[44:47]
	v_mfma_f32_16x16x32_bf16 v[44:47], v[162:165], v[224:227], v[44:47]
	v_mfma_f32_16x16x32_bf16 v[28:31], v[162:165], v[232:235], v[28:31]
	v_mfma_f32_16x16x32_bf16 v[28:31], v[166:169], v[236:239], v[28:31]
	v_mfma_f32_16x16x32_bf16 v[24:27], v[196:199], v[236:239], v[24:27]
	v_mfma_f32_16x16x32_bf16 v[24:27], v[172:175], v[232:235], v[24:27]
	v_mfma_f32_16x16x32_bf16 v[4:7], v[172:175], v[240:243], v[4:7]
	v_mfma_f32_16x16x32_bf16 v[4:7], v[196:199], v[244:247], v[4:7]
	v_mfma_f32_16x16x32_bf16 v[12:15], v[166:169], v[244:247], v[12:15]
	v_mfma_f32_16x16x32_bf16 v[12:15], v[162:165], v[240:243], v[12:15]
	v_mfma_f32_16x16x32_bf16 v[52:55], v[200:203], v[216:219], v[52:55]
	v_mfma_f32_16x16x32_bf16 v[52:55], v[204:207], v[220:223], v[52:55]
	v_mfma_f32_16x16x32_bf16 v[48:51], v[212:215], v[220:223], v[48:51]
	v_mfma_f32_16x16x32_bf16 v[48:51], v[208:211], v[216:219], v[48:51]
	v_mfma_f32_16x16x32_bf16 v[32:35], v[208:211], v[224:227], v[32:35]
	v_mfma_f32_16x16x32_bf16 v[32:35], v[212:215], v[228:231], v[32:35]
	v_mfma_f32_16x16x32_bf16 v[36:39], v[204:207], v[228:231], v[36:39]
	v_mfma_f32_16x16x32_bf16 v[36:39], v[200:203], v[224:227], v[36:39]
	v_mfma_f32_16x16x32_bf16 v[20:23], v[200:203], v[232:235], v[20:23]
	v_mfma_f32_16x16x32_bf16 v[20:23], v[204:207], v[236:239], v[20:23]
	v_mfma_f32_16x16x32_bf16 v[16:19], v[212:215], v[236:239], v[16:19]
	v_mfma_f32_16x16x32_bf16 v[16:19], v[208:211], v[232:235], v[16:19]
	v_mfma_f32_16x16x32_bf16 v[0:3], v[208:211], v[240:243], v[0:3]
	v_mfma_f32_16x16x32_bf16 v[0:3], v[212:215], v[244:247], v[0:3]
	v_mfma_f32_16x16x32_bf16 v[8:11], v[204:207], v[244:247], v[8:11]
	v_mfma_f32_16x16x32_bf16 v[8:11], v[200:203], v[240:243], v[8:11]
	s_barrier
	s_add_i32 s42, s42, 2
	s_add_u32 s10, s10, 0x100
	s_addc_u32 s11, s11, 0
	s_add_u32 s40, s40, 0x100
	s_addc_u32 s41, s41, 0
	s_cmp_gt_u32 s42, 29
	s_cbranch_scc0 .LBB0_623
	s_setprio 0
	s_and_b64 vcc, exec, s[66:67]
	s_cbranch_vccz .LBB0_628
	s_barrier
	v_lshl_add_u32 v162, s4, 8, v143
	s_cmp_lt_i32 s55, 10
	s_mov_b64 s[10:11], -1
	s_cbranch_scc1 .LBB0_629

;     __device__ __forceinline__ bool next(int i, Unit& u) const { if (i > 0 || c >= nitems) return false; u.pm = 64; u.pn = c % npn; u.k0 = (c / npn) * kslice; return true; }
; #define PG8_STAGE(bufoff, gbase, voff) do { _Pragma("unroll") for (int _i = 0; _i < 2; ++_i) \
;         __builtin_amdgcn_global_load_lds((const unsigned*)((const char*)(gbase) + (voff)[_i]), (PG8_LAS unsigned*)(lds + (bufoff) + ldsw + _i * 8192), 16, 0, 0); } while (0)
; #define PG8_LDA(dst, b, h) do { _Pragma("unroll") for (int m = 0; m < 4; ++m) _Pragma("unroll") for (int k = 0; k < 2; ++k) dst[m][k] = *(const PG8_LAS bf16x8*)(lds + PG8_SA(b, h) + aoff + m * 2048 + k * 1024); } while (0)
; #define PG8_LDB(dst, b, h) do { _Pragma("unroll") for (int n = 0; n < 2; ++n) _Pragma("unroll") for (int k = 0; k < 2; ++k) dst[n][k] = *(const PG8_LAS bf16x8*)(lds + PG8_SB(b, h) + boff + n * 2048 + k * 1024); } while (0)
; #define PG8_SCHED __builtin_amdgcn_sched_barrier(0)
; template <class Epi, class Sched, bool ALIGN_EPI = false, bool SP2 = false>
; __device__ __forceinline__ void gemm_phase(PG8_LAS unsigned char* lds, const Gemm g, const Sched& S, const Epi& E) {
;     ...
;         const bool has_next = S.next(ui + 1, nxt);
;         const char* nA = has_next ? (const char*)g.A + (size_t)nxt.pm * tstep + (size_t)nxt.k0 * 2 : cA; const char* nB = has_next ? (const char*)g.Bt + (size_t)nxt.pn * tstep + (size_t)nxt.k0 * 2 : cB;
;         for (int t = 0; t < nt; t += 2) {
;             const bool last = (t == nt - 2);
;             const char* a1 = cA + (size_t)(t + 1) * kstep;
;             const char* a2 = last ? nA : cA + (size_t)(t + 2) * kstep; const char* b2 = last ? nB : cB + (size_t)(t + 2) * kstep;
;             const char* a3 = a2 + kstep; const char* b3 = b2 + kstep;
;             if (last && has_next) S.a_ready(nxt);
;             if constexpr (SP2) {
;             PG8_LDB(B0, 0, 0); PG8_LDB(B1, 0, 1); PG8_SCHED; PG8_LDA(At, 0, 0); PG8_STAGE(PG8_SA(1, 1), a1 + hstep, voffA);
;     ...
;         for (int a = 0; a < 2; ++a)
; #pragma unroll
;             for (int b = 0; b < 2; ++b)
; #pragma unroll
;                 for (int m = 0; m < 4; ++m)
; #pragma unroll
;                     for (int n = 0; n < 2; ++n) acc[a][b][m][n] = (f32x4){0.f, 0.f, 0.f, 0.f};
.LBB0_1055:
	s_ashr_i32 s27, s26, 31
	s_lshl_b64 s[28:29], s[26:27], 20
	s_add_u32 s28, s33, s28
	s_addc_u32 s29, s44, s29
	s_and_b64 s[30:31], s[10:11], exec
	s_cselect_b32 s27, s29, s39
	s_cselect_b32 s35, s28, s38
	s_ashr_i32 s25, s24, 31
	s_lshl_b64 s[30:31], s[24:25], 20
	s_add_u32 s30, s2, s30
	s_addc_u32 s31, s3, s31
	s_and_b64 s[42:43], s[10:11], exec
	s_cselect_b32 s25, s31, s41
	s_cselect_b32 s37, s30, s40
	s_add_u32 s38, s38, 0x80080
	s_addc_u32 s39, s39, 0
	s_add_u32 s63, s40, 0x100
	v_mov_b32_e32 v0, 0
	s_addc_u32 s64, s41, 0
	s_mov_b32 s65, -2
	s_waitcnt lgkmcnt(0)
	v_mov_b32_e32 v1, v0
	v_mov_b32_e32 v2, v0
	v_mov_b32_e32 v3, v0
	v_mov_b32_e32 v4, v0
	v_mov_b32_e32 v5, v0
	v_mov_b32_e32 v6, v0
	v_mov_b32_e32 v7, v0
	v_mov_b32_e32 v16, v0
	v_mov_b32_e32 v17, v0
	v_mov_b32_e32 v18, v0
	v_mov_b32_e32 v19, v0
	v_mov_b32_e32 v20, v0
	v_mov_b32_e32 v21, v0
	v_mov_b32_e32 v22, v0
	v_mov_b32_e32 v23, v0
	v_mov_b32_e32 v32, v0
	v_mov_b32_e32 v33, v0
	v_mov_b32_e32 v34, v0
	v_mov_b32_e32 v35, v0
	v_mov_b32_e32 v36, v0
	v_mov_b32_e32 v37, v0
	v_mov_b32_e32 v38, v0
	v_mov_b32_e32 v39, v0
	v_mov_b32_e32 v48, v0
	v_mov_b32_e32 v49, v0
	v_mov_b32_e32 v50, v0
	v_mov_b32_e32 v51, v0
	v_mov_b32_e32 v52, v0
	v_mov_b32_e32 v53, v0
	v_mov_b32_e32 v54, v0
	v_mov_b32_e32 v55, v0
	v_mov_b32_e32 v8, v0
	v_mov_b32_e32 v9, v0
	v_mov_b32_e32 v10, v0
	v_mov_b32_e32 v11, v0
	v_mov_b32_e32 v12, v0
	v_mov_b32_e32 v13, v0
	v_mov_b32_e32 v14, v0
	v_mov_b32_e32 v15, v0
	v_mov_b32_e32 v24, v0
	v_mov_b32_e32 v25, v0
	v_mov_b32_e32 v26, v0
	v_mov_b32_e32 v27, v0
	v_mov_b32_e32 v28, v0
	v_mov_b32_e32 v29, v0
	v_mov_b32_e32 v30, v0
	v_mov_b32_e32 v31, v0
	v_mov_b32_e32 v40, v0
	v_mov_b32_e32 v41, v0
	v_mov_b32_e32 v42, v0
	v_mov_b32_e32 v43, v0
	v_mov_b32_e32 v44, v0
	v_mov_b32_e32 v45, v0
	v_mov_b32_e32 v46, v0
	v_mov_b32_e32 v47, v0
	v_mov_b32_e32 v56, v0
	v_mov_b32_e32 v57, v0
	v_mov_b32_e32 v58, v0
	v_mov_b32_e32 v59, v0
	v_mov_b32_e32 v60, v0
	v_mov_b32_e32 v61, v0
	v_mov_b32_e32 v62, v0
	v_mov_b32_e32 v63, v0
	v_mov_b32_e32 v64, v0
	v_mov_b32_e32 v65, v0
	v_mov_b32_e32 v66, v0
	v_mov_b32_e32 v67, v0
	v_mov_b32_e32 v68, v0
	v_mov_b32_e32 v69, v0
	v_mov_b32_e32 v70, v0
	v_mov_b32_e32 v71, v0
	v_mov_b32_e32 v80, v0
	v_mov_b32_e32 v81, v0
	v_mov_b32_e32 v82, v0
	v_mov_b32_e32 v83, v0
	v_mov_b32_e32 v84, v0
	v_mov_b32_e32 v85, v0
	v_mov_b32_e32 v86, v0
	v_mov_b32_e32 v87, v0
	v_mov_b32_e32 v96, v0
	v_mov_b32_e32 v97, v0
	v_mov_b32_e32 v98, v0
	v_mov_b32_e32 v99, v0
	v_mov_b32_e32 v100, v0
	v_mov_b32_e32 v101, v0
	v_mov_b32_e32 v102, v0
	v_mov_b32_e32 v103, v0
	v_mov_b32_e32 v112, v0
	v_mov_b32_e32 v113, v0
	v_mov_b32_e32 v114, v0
	v_mov_b32_e32 v115, v0
	v_mov_b32_e32 v116, v0
	v_mov_b32_e32 v117, v0
	v_mov_b32_e32 v118, v0
	v_mov_b32_e32 v119, v0
	v_mov_b32_e32 v72, v0
	v_mov_b32_e32 v73, v0
	v_mov_b32_e32 v74, v0
	v_mov_b32_e32 v75, v0
	v_mov_b32_e32 v76, v0
	v_mov_b32_e32 v77, v0
	v_mov_b32_e32 v78, v0
	v_mov_b32_e32 v79, v0
	v_mov_b32_e32 v88, v0
	v_mov_b32_e32 v89, v0
	v_mov_b32_e32 v90, v0
	v_mov_b32_e32 v91, v0
	v_mov_b32_e32 v92, v0
	v_mov_b32_e32 v93, v0
	v_mov_b32_e32 v94, v0
	v_mov_b32_e32 v95, v0
	v_mov_b32_e32 v104, v0
	v_mov_b32_e32 v105, v0
	v_mov_b32_e32 v106, v0
	v_mov_b32_e32 v107, v0
	v_mov_b32_e32 v108, v0
	v_mov_b32_e32 v109, v0
	v_mov_b32_e32 v110, v0
	v_mov_b32_e32 v111, v0
	v_mov_b32_e32 v120, v0
	v_mov_b32_e32 v121, v0
	v_mov_b32_e32 v122, v0
	v_mov_b32_e32 v123, v0
	v_mov_b32_e32 v124, v0
	v_mov_b32_e32 v125, v0
	v_mov_b32_e32 v126, v0
	v_mov_b32_e32 v127, v0
	s_and_b64 vcc, exec, s[22:23]
	s_cbranch_vccnz .Lsp_skip_3
	s_setprio 1
.Lsp_skip_3:
.LBB0_1056:
	ds_read_b128 v[128:131], v149
	ds_read_b128 v[132:135], v149 offset:1024
	ds_read_b128 v[172:175], v149 offset:2048
	ds_read_b128 v[188:191], v149 offset:3072
	ds_read_b128 v[192:195], v159
	ds_read_b128 v[196:199], v159 offset:1024
	ds_read_b128 v[200:203], v159 offset:2048
	ds_read_b128 v[204:207], v159 offset:3072
	s_add_u32 s40, s38, 0xfff80080
	s_addc_u32 s41, s39, -1
	s_cmp_eq_u32 s65, 28
	s_cselect_b32 s43, s27, s41
	s_cselect_b32 s42, s35, s40
	s_cselect_b32 s41, s25, s64
	s_cselect_b32 s40, s37, s63
	s_add_i32 m0, s46, 0xc000
	ds_read_b128 v[208:211], v163
	ds_read_b128 v[212:215], v163 offset:1024
	ds_read_b128 v[216:219], v163 offset:2048
	ds_read_b128 v[220:223], v163 offset:3072
	ds_read_b128 v[224:227], v163 offset:4096
	ds_read_b128 v[228:231], v163 offset:5120
	ds_read_b128 v[232:235], v163 offset:6144
	ds_read_b128 v[236:239], v163 offset:7168
	global_load_lds_dwordx4 v164, s[38:39]
	s_add_i32 m0, s46, 0xe000
	s_nop 0
	global_load_lds_dwordx4 v166, s[38:39]
	s_waitcnt vmcnt(8)
	s_waitcnt lgkmcnt(0)
	s_barrier
; #define PG8_STAGE(bufoff, gbase, voff) do { _Pragma("unroll") for (int _i = 0; _i < 2; ++_i) \
;         __builtin_amdgcn_global_load_lds((const unsigned*)((const char*)(gbase) + (voff)[_i]), (PG8_LAS unsigned*)(lds + (bufoff) + ldsw + _i * 8192), 16, 0, 0); } while (0)
; #define PG8_LDA(dst, b, h) do { _Pragma("unroll") for (int m = 0; m < 4; ++m) _Pragma("unroll") for (int k = 0; k < 2; ++k) dst[m][k] = *(const PG8_LAS bf16x8*)(lds + PG8_SA(b, h) + aoff + m * 2048 + k * 1024); } while (0)
; #define PG8_MMA(ai, bj, At, Bt) do { __builtin_amdgcn_s_setprio(1); _Pragma("unroll") for (int m = 0; m < 4; ++m) _Pragma("unroll") for (int n = 0; n < 2; ++n) _Pragma("unroll") for (int k = 0; k < 2; ++k) \
;         acc[ai][bj][m][n] = __builtin_amdgcn_mfma_f32_16x16x32_bf16(Bt[n][k], At[m][k], acc[ai][bj][m][n], 0, 0, 0); __builtin_amdgcn_s_setprio(0); } while (0)
; #define PG8_WAIT_V(n) asm volatile("s_waitcnt vmcnt(" #n ")" ::: "memory")
; #define PG8_WAIT_L(n) asm volatile("s_waitcnt lgkmcnt(" #n ")" ::: "memory")
; #define PG8_BAR __builtin_amdgcn_s_barrier()
; #define PG8_SCHED __builtin_amdgcn_sched_barrier(0)
; template <class Epi, class Sched, bool ALIGN_EPI = false, bool SP2 = false>
; __device__ __forceinline__ void gemm_phase(PG8_LAS unsigned char* lds, const Gemm g, const Sched& S, const Epi& E) {
;     ...
;             PG8_WAIT_V(8); PG8_WAIT_L(0); PG8_BAR; PG8_MMA(0, 0, At, B0); PG8_MMA(0, 1, At, B1); PG8_BAR; PG8_SCHED;
;             PG8_LDA(At, 0, 1); PG8_STAGE(PG8_SB(0, 0), b2, voffB); PG8_STAGE(PG8_SB(0, 1), b2 + hstep, voffB); PG8_STAGE(PG8_SA(0, 0), a2, voffA);
;             PG8_WAIT_V(8); PG8_WAIT_L(0); PG8_BAR; PG8_MMA(1, 0, At, B0); PG8_MMA(1, 1, At, B1); PG8_BAR; PG8_SCHED;
	s_waitcnt lgkmcnt(0)
	v_mfma_f32_16x16x32_bf16 v[124:127], v[128:131], v[208:211], v[124:127]
	v_mfma_f32_16x16x32_bf16 v[124:127], v[132:135], v[212:215], v[124:127]
	v_mfma_f32_16x16x32_bf16 v[120:123], v[188:191], v[212:215], v[120:123]
	v_mfma_f32_16x16x32_bf16 v[120:123], v[172:175], v[208:211], v[120:123]
	v_mfma_f32_16x16x32_bf16 v[104:107], v[172:175], v[216:219], v[104:107]
	v_mfma_f32_16x16x32_bf16 v[104:107], v[188:191], v[220:223], v[104:107]
	v_mfma_f32_16x16x32_bf16 v[108:111], v[132:135], v[220:223], v[108:111]
	v_mfma_f32_16x16x32_bf16 v[108:111], v[128:131], v[216:219], v[108:111]
	v_mfma_f32_16x16x32_bf16 v[92:95], v[128:131], v[224:227], v[92:95]
	v_mfma_f32_16x16x32_bf16 v[92:95], v[132:135], v[228:231], v[92:95]
	v_mfma_f32_16x16x32_bf16 v[88:91], v[188:191], v[228:231], v[88:91]
	v_mfma_f32_16x16x32_bf16 v[88:91], v[172:175], v[224:227], v[88:91]
	v_mfma_f32_16x16x32_bf16 v[72:75], v[172:175], v[232:235], v[72:75]
	v_mfma_f32_16x16x32_bf16 v[72:75], v[188:191], v[236:239], v[72:75]
	v_mfma_f32_16x16x32_bf16 v[76:79], v[132:135], v[236:239], v[76:79]
	v_mfma_f32_16x16x32_bf16 v[76:79], v[128:131], v[232:235], v[76:79]
	v_mfma_f32_16x16x32_bf16 v[116:119], v[192:195], v[208:211], v[116:119]
	v_mfma_f32_16x16x32_bf16 v[116:119], v[196:199], v[212:215], v[116:119]
	v_mfma_f32_16x16x32_bf16 v[112:115], v[204:207], v[212:215], v[112:115]
	v_mfma_f32_16x16x32_bf16 v[112:115], v[200:203], v[208:211], v[112:115]
	v_mfma_f32_16x16x32_bf16 v[96:99], v[200:203], v[216:219], v[96:99]
	v_mfma_f32_16x16x32_bf16 v[96:99], v[204:207], v[220:223], v[96:99]
	v_mfma_f32_16x16x32_bf16 v[100:103], v[196:199], v[220:223], v[100:103]
	v_mfma_f32_16x16x32_bf16 v[100:103], v[192:195], v[216:219], v[100:103]
	v_mfma_f32_16x16x32_bf16 v[84:87], v[192:195], v[224:227], v[84:87]
	v_mfma_f32_16x16x32_bf16 v[84:87], v[196:199], v[228:231], v[84:87]
	v_mfma_f32_16x16x32_bf16 v[80:83], v[204:207], v[228:231], v[80:83]
	v_mfma_f32_16x16x32_bf16 v[80:83], v[200:203], v[224:227], v[80:83]
	v_mfma_f32_16x16x32_bf16 v[64:67], v[200:203], v[232:235], v[64:67]
	v_mfma_f32_16x16x32_bf16 v[64:67], v[204:207], v[236:239], v[64:67]
	v_mfma_f32_16x16x32_bf16 v[68:71], v[196:199], v[236:239], v[68:71]
	v_mfma_f32_16x16x32_bf16 v[68:71], v[192:195], v[232:235], v[68:71]
	s_barrier
	s_add_u32 s98, s40, 0x80
	s_addc_u32 s99, s41, 0
	s_add_u32 s100, s42, 0x80
	s_addc_u32 s101, s43, 0
	s_add_i32 s66, s56, s45
	s_mov_b32 m0, s66
	ds_read_b128 v[208:211], v163 offset:16384
	ds_read_b128 v[212:215], v163 offset:17408
	ds_read_b128 v[216:219], v163 offset:18432
	ds_read_b128 v[220:223], v163 offset:19456
	ds_read_b128 v[224:227], v163 offset:20480
	ds_read_b128 v[228:231], v163 offset:21504
	ds_read_b128 v[232:235], v163 offset:22528
	ds_read_b128 v[236:239], v163 offset:23552
	global_load_lds_dwordx4 v152, s[40:41]
	s_add_i32 m0, s66, 0x2000
	s_add_u32 s66, s40, 0x80000
	s_addc_u32 s67, s41, 0
	s_add_i32 s68, s57, s45
	global_load_lds_dwordx4 v156, s[40:41]
	s_mov_b32 m0, s68
	s_nop 0
	global_load_lds_dwordx4 v152, s[66:67]
	s_add_i32 m0, s68, 0x2000
	s_nop 0
	global_load_lds_dwordx4 v156, s[66:67]
	s_mov_b32 m0, s46
	s_nop 0
	global_load_lds_dwordx4 v150, s[42:43]
	s_mov_b32 m0, s47
	s_nop 0
	global_load_lds_dwordx4 v154, s[42:43]
	s_waitcnt vmcnt(8)
	s_waitcnt lgkmcnt(0)
	s_barrier
	s_waitcnt lgkmcnt(0)
	v_mfma_f32_16x16x32_bf16 v[60:63], v[128:131], v[208:211], v[60:63]
	v_mfma_f32_16x16x32_bf16 v[60:63], v[132:135], v[212:215], v[60:63]
	v_mfma_f32_16x16x32_bf16 v[56:59], v[188:191], v[212:215], v[56:59]
	v_mfma_f32_16x16x32_bf16 v[56:59], v[172:175], v[208:211], v[56:59]
	v_mfma_f32_16x16x32_bf16 v[40:43], v[172:175], v[216:219], v[40:43]
	v_mfma_f32_16x16x32_bf16 v[40:43], v[188:191], v[220:223], v[40:43]
	v_mfma_f32_16x16x32_bf16 v[44:47], v[132:135], v[220:223], v[44:47]
	v_mfma_f32_16x16x32_bf16 v[44:47], v[128:131], v[216:219], v[44:47]
	v_mfma_f32_16x16x32_bf16 v[28:31], v[128:131], v[224:227], v[28:31]
	v_mfma_f32_16x16x32_bf16 v[28:31], v[132:135], v[228:231], v[28:31]
	v_mfma_f32_16x16x32_bf16 v[24:27], v[188:191], v[228:231], v[24:27]
	v_mfma_f32_16x16x32_bf16 v[24:27], v[172:175], v[224:227], v[24:27]
	v_mfma_f32_16x16x32_bf16 v[8:11], v[172:175], v[232:235], v[8:11]
	v_mfma_f32_16x16x32_bf16 v[8:11], v[188:191], v[236:239], v[8:11]
	v_mfma_f32_16x16x32_bf16 v[12:15], v[132:135], v[236:239], v[12:15]
	v_mfma_f32_16x16x32_bf16 v[12:15], v[128:131], v[232:235], v[12:15]
	v_mfma_f32_16x16x32_bf16 v[52:55], v[192:195], v[208:211], v[52:55]
	v_mfma_f32_16x16x32_bf16 v[52:55], v[196:199], v[212:215], v[52:55]
	v_mfma_f32_16x16x32_bf16 v[48:51], v[204:207], v[212:215], v[48:51]
	v_mfma_f32_16x16x32_bf16 v[48:51], v[200:203], v[208:211], v[48:51]
	v_mfma_f32_16x16x32_bf16 v[32:35], v[200:203], v[216:219], v[32:35]
	v_mfma_f32_16x16x32_bf16 v[32:35], v[204:207], v[220:223], v[32:35]
	v_mfma_f32_16x16x32_bf16 v[36:39], v[196:199], v[220:223], v[36:39]
	v_mfma_f32_16x16x32_bf16 v[36:39], v[192:195], v[216:219], v[36:39]
	v_mfma_f32_16x16x32_bf16 v[20:23], v[192:195], v[224:227], v[20:23]
	v_mfma_f32_16x16x32_bf16 v[20:23], v[196:199], v[228:231], v[20:23]
	v_mfma_f32_16x16x32_bf16 v[16:19], v[204:207], v[228:231], v[16:19]
	v_mfma_f32_16x16x32_bf16 v[16:19], v[200:203], v[224:227], v[16:19]
	v_mfma_f32_16x16x32_bf16 v[0:3], v[200:203], v[232:235], v[0:3]
	v_mfma_f32_16x16x32_bf16 v[0:3], v[204:207], v[236:239], v[0:3]
	v_mfma_f32_16x16x32_bf16 v[4:7], v[196:199], v[236:239], v[4:7]
	v_mfma_f32_16x16x32_bf16 v[4:7], v[192:195], v[232:235], v[4:7]
	s_barrier
; #define PG8_STAGE(bufoff, gbase, voff) do { _Pragma("unroll") for (int _i = 0; _i < 2; ++_i) \
;         __builtin_amdgcn_global_load_lds((const unsigned*)((const char*)(gbase) + (voff)[_i]), (PG8_LAS unsigned*)(lds + (bufoff) + ldsw + _i * 8192), 16, 0, 0); } while (0)
; #define PG8_LDA(dst, b, h) do { _Pragma("unroll") for (int m = 0; m < 4; ++m) _Pragma("unroll") for (int k = 0; k < 2; ++k) dst[m][k] = *(const PG8_LAS bf16x8*)(lds + PG8_SA(b, h) + aoff + m * 2048 + k * 1024); } while (0)
; #define PG8_LDB(dst, b, h) do { _Pragma("unroll") for (int n = 0; n < 2; ++n) _Pragma("unroll") for (int k = 0; k < 2; ++k) dst[n][k] = *(const PG8_LAS bf16x8*)(lds + PG8_SB(b, h) + boff + n * 2048 + k * 1024); } while (0)
; #define PG8_MMA(ai, bj, At, Bt) do { __builtin_amdgcn_s_setprio(1); _Pragma("unroll") for (int m = 0; m < 4; ++m) _Pragma("unroll") for (int n = 0; n < 2; ++n) _Pragma("unroll") for (int k = 0; k < 2; ++k) \
;         acc[ai][bj][m][n] = __builtin_amdgcn_mfma_f32_16x16x32_bf16(Bt[n][k], At[m][k], acc[ai][bj][m][n], 0, 0, 0); __builtin_amdgcn_s_setprio(0); } while (0)
; #define PG8_WAIT_V(n) asm volatile("s_waitcnt vmcnt(" #n ")" ::: "memory")
; #define PG8_WAIT_L(n) asm volatile("s_waitcnt lgkmcnt(" #n ")" ::: "memory")
; #define PG8_BAR __builtin_amdgcn_s_barrier()
; #define PG8_SCHED __builtin_amdgcn_sched_barrier(0)
; template <class Epi, class Sched, bool ALIGN_EPI = false, bool SP2 = false>
; __device__ __forceinline__ void gemm_phase(PG8_LAS unsigned char* lds, const Gemm g, const Sched& S, const Epi& E) {
;     ...
;             PG8_LDB(B0, 1, 0); PG8_LDB(B1, 1, 1); PG8_SCHED; PG8_LDA(At, 1, 0); PG8_STAGE(PG8_SA(0, 1), a2 + hstep, voffA);
;             PG8_WAIT_V(8); PG8_WAIT_L(0); PG8_BAR; PG8_MMA(0, 0, At, B0); PG8_MMA(0, 1, At, B1); PG8_BAR; PG8_SCHED;
;             PG8_LDA(At, 1, 1); PG8_STAGE(PG8_SB(1, 0), b3, voffB); PG8_STAGE(PG8_SB(1, 1), b3 + hstep, voffB); PG8_STAGE(PG8_SA(1, 0), a3, voffA);
;             PG8_WAIT_V(8); PG8_WAIT_L(0); PG8_BAR; PG8_MMA(1, 0, At, B0); PG8_MMA(1, 1, At, B1); PG8_BAR; PG8_SCHED;
;     ...
;         if constexpr (ALIGN_EPI) { if (wr == 0) PG8_BAR; }
	s_add_i32 s66, 0, 0x18000
	v_add_u32_e32 v160, s66, v145
	s_add_i32 s67, 0, 0x1c000
	ds_read_b128 v[128:131], v160
	ds_read_b128 v[132:135], v160 offset:1024
	ds_read_b128 v[172:175], v160 offset:2048
	ds_read_b128 v[188:191], v160 offset:3072
	v_add_u32_e32 v160, s67, v145
	ds_read_b128 v[192:195], v160
	ds_read_b128 v[196:199], v160 offset:1024
	ds_read_b128 v[200:203], v160 offset:2048
	ds_read_b128 v[204:207], v160 offset:3072
	s_add_u32 s42, s42, 0x80000
	s_addc_u32 s43, s43, 0
	s_mov_b32 m0, s48
	ds_read_b128 v[208:211], v163 offset:32768
	ds_read_b128 v[212:215], v163 offset:33792
	ds_read_b128 v[216:219], v163 offset:34816
	ds_read_b128 v[220:223], v163 offset:35840
	ds_read_b128 v[224:227], v163 offset:36864
	ds_read_b128 v[228:231], v163 offset:37888
	ds_read_b128 v[232:235], v163 offset:38912
	ds_read_b128 v[236:239], v163 offset:39936
	global_load_lds_dwordx4 v150, s[42:43]
	s_mov_b32 m0, s49
	s_nop 0
	global_load_lds_dwordx4 v154, s[42:43]
	s_waitcnt vmcnt(8)
	s_waitcnt lgkmcnt(0)
	s_barrier
	s_waitcnt lgkmcnt(0)
	v_mfma_f32_16x16x32_bf16 v[124:127], v[128:131], v[208:211], v[124:127]
	v_mfma_f32_16x16x32_bf16 v[124:127], v[132:135], v[212:215], v[124:127]
	v_mfma_f32_16x16x32_bf16 v[120:123], v[188:191], v[212:215], v[120:123]
	v_mfma_f32_16x16x32_bf16 v[120:123], v[172:175], v[208:211], v[120:123]
	v_mfma_f32_16x16x32_bf16 v[104:107], v[172:175], v[216:219], v[104:107]
	v_mfma_f32_16x16x32_bf16 v[104:107], v[188:191], v[220:223], v[104:107]
	v_mfma_f32_16x16x32_bf16 v[108:111], v[132:135], v[220:223], v[108:111]
	v_mfma_f32_16x16x32_bf16 v[108:111], v[128:131], v[216:219], v[108:111]
	v_mfma_f32_16x16x32_bf16 v[92:95], v[128:131], v[224:227], v[92:95]
	v_mfma_f32_16x16x32_bf16 v[92:95], v[132:135], v[228:231], v[92:95]
	v_mfma_f32_16x16x32_bf16 v[88:91], v[188:191], v[228:231], v[88:91]
	v_mfma_f32_16x16x32_bf16 v[88:91], v[172:175], v[224:227], v[88:91]
	v_mfma_f32_16x16x32_bf16 v[72:75], v[172:175], v[232:235], v[72:75]
	v_mfma_f32_16x16x32_bf16 v[72:75], v[188:191], v[236:239], v[72:75]
	v_mfma_f32_16x16x32_bf16 v[76:79], v[132:135], v[236:239], v[76:79]
	v_mfma_f32_16x16x32_bf16 v[76:79], v[128:131], v[232:235], v[76:79]
	v_mfma_f32_16x16x32_bf16 v[116:119], v[192:195], v[208:211], v[116:119]
	v_mfma_f32_16x16x32_bf16 v[116:119], v[196:199], v[212:215], v[116:119]
	v_mfma_f32_16x16x32_bf16 v[112:115], v[204:207], v[212:215], v[112:115]
	v_mfma_f32_16x16x32_bf16 v[112:115], v[200:203], v[208:211], v[112:115]
	v_mfma_f32_16x16x32_bf16 v[96:99], v[200:203], v[216:219], v[96:99]
	v_mfma_f32_16x16x32_bf16 v[96:99], v[204:207], v[220:223], v[96:99]
	v_mfma_f32_16x16x32_bf16 v[100:103], v[196:199], v[220:223], v[100:103]
	v_mfma_f32_16x16x32_bf16 v[100:103], v[192:195], v[216:219], v[100:103]
	v_mfma_f32_16x16x32_bf16 v[84:87], v[192:195], v[224:227], v[84:87]
	v_mfma_f32_16x16x32_bf16 v[84:87], v[196:199], v[228:231], v[84:87]
	v_mfma_f32_16x16x32_bf16 v[80:83], v[204:207], v[228:231], v[80:83]
	v_mfma_f32_16x16x32_bf16 v[80:83], v[200:203], v[224:227], v[80:83]
	v_mfma_f32_16x16x32_bf16 v[64:67], v[200:203], v[232:235], v[64:67]
	v_mfma_f32_16x16x32_bf16 v[64:67], v[204:207], v[236:239], v[64:67]
	v_mfma_f32_16x16x32_bf16 v[68:71], v[196:199], v[236:239], v[68:71]
	v_mfma_f32_16x16x32_bf16 v[68:71], v[192:195], v[232:235], v[68:71]
	s_barrier
	s_add_i32 s42, s66, s45
	s_mov_b32 m0, s42
	ds_read_b128 v[208:211], v163 offset:49152
	ds_read_b128 v[212:215], v163 offset:50176
	ds_read_b128 v[216:219], v163 offset:51200
	ds_read_b128 v[220:223], v163 offset:52224
	ds_read_b128 v[224:227], v163 offset:53248
	ds_read_b128 v[228:231], v163 offset:54272
	ds_read_b128 v[232:235], v163 offset:55296
	ds_read_b128 v[236:239], v163 offset:56320
	global_load_lds_dwordx4 v152, s[98:99]
	s_add_i32 m0, s42, 0x2000
	s_add_u32 s40, s40, 0x80080
	s_addc_u32 s41, s41, 0
	s_add_i32 s42, s67, s45
	global_load_lds_dwordx4 v156, s[98:99]
	s_mov_b32 m0, s42
	s_nop 0
	global_load_lds_dwordx4 v152, s[40:41]
	s_add_i32 m0, s42, 0x2000
	s_nop 0
	global_load_lds_dwordx4 v156, s[40:41]
	s_mov_b32 m0, s51
	s_nop 0
	global_load_lds_dwordx4 v150, s[100:101]
	s_mov_b32 m0, s52
	s_nop 0
	global_load_lds_dwordx4 v154, s[100:101]
	s_waitcnt vmcnt(8)
	s_waitcnt lgkmcnt(0)
	s_barrier
	s_waitcnt lgkmcnt(0)
	v_mfma_f32_16x16x32_bf16 v[60:63], v[128:131], v[208:211], v[60:63]
	v_mfma_f32_16x16x32_bf16 v[60:63], v[132:135], v[212:215], v[60:63]
	v_mfma_f32_16x16x32_bf16 v[56:59], v[188:191], v[212:215], v[56:59]
	v_mfma_f32_16x16x32_bf16 v[56:59], v[172:175], v[208:211], v[56:59]
	v_mfma_f32_16x16x32_bf16 v[40:43], v[172:175], v[216:219], v[40:43]
	v_mfma_f32_16x16x32_bf16 v[40:43], v[188:191], v[220:223], v[40:43]
	v_mfma_f32_16x16x32_bf16 v[44:47], v[132:135], v[220:223], v[44:47]
	v_mfma_f32_16x16x32_bf16 v[44:47], v[128:131], v[216:219], v[44:47]
	v_mfma_f32_16x16x32_bf16 v[28:31], v[128:131], v[224:227], v[28:31]
	v_mfma_f32_16x16x32_bf16 v[28:31], v[132:135], v[228:231], v[28:31]
	v_mfma_f32_16x16x32_bf16 v[24:27], v[188:191], v[228:231], v[24:27]
	v_mfma_f32_16x16x32_bf16 v[24:27], v[172:175], v[224:227], v[24:27]
	v_mfma_f32_16x16x32_bf16 v[8:11], v[172:175], v[232:235], v[8:11]
	v_mfma_f32_16x16x32_bf16 v[8:11], v[188:191], v[236:239], v[8:11]
	v_mfma_f32_16x16x32_bf16 v[12:15], v[132:135], v[236:239], v[12:15]
	v_mfma_f32_16x16x32_bf16 v[12:15], v[128:131], v[232:235], v[12:15]
	v_mfma_f32_16x16x32_bf16 v[52:55], v[192:195], v[208:211], v[52:55]
	v_mfma_f32_16x16x32_bf16 v[52:55], v[196:199], v[212:215], v[52:55]
	v_mfma_f32_16x16x32_bf16 v[48:51], v[204:207], v[212:215], v[48:51]
	v_mfma_f32_16x16x32_bf16 v[48:51], v[200:203], v[208:211], v[48:51]
	v_mfma_f32_16x16x32_bf16 v[32:35], v[200:203], v[216:219], v[32:35]
	v_mfma_f32_16x16x32_bf16 v[32:35], v[204:207], v[220:223], v[32:35]
	v_mfma_f32_16x16x32_bf16 v[36:39], v[196:199], v[220:223], v[36:39]
	v_mfma_f32_16x16x32_bf16 v[36:39], v[192:195], v[216:219], v[36:39]
	v_mfma_f32_16x16x32_bf16 v[20:23], v[192:195], v[224:227], v[20:23]
	v_mfma_f32_16x16x32_bf16 v[20:23], v[196:199], v[228:231], v[20:23]
	v_mfma_f32_16x16x32_bf16 v[16:19], v[204:207], v[228:231], v[16:19]
	v_mfma_f32_16x16x32_bf16 v[16:19], v[200:203], v[224:227], v[16:19]
	v_mfma_f32_16x16x32_bf16 v[0:3], v[200:203], v[232:235], v[0:3]
	v_mfma_f32_16x16x32_bf16 v[0:3], v[204:207], v[236:239], v[0:3]
	v_mfma_f32_16x16x32_bf16 v[4:7], v[196:199], v[236:239], v[4:7]
	v_mfma_f32_16x16x32_bf16 v[4:7], v[192:195], v[232:235], v[4:7]
	s_barrier
	s_add_i32 s65, s65, 2
	s_add_u32 s38, s38, 0x100
	s_addc_u32 s39, s39, 0
	s_add_u32 s63, s63, 0x100
	s_addc_u32 s64, s64, 0
	s_cmp_gt_u32 s65, 29
	s_cbranch_scc0 .LBB0_1056
	s_setprio 0
	s_and_b64 vcc, exec, s[22:23]
	s_cbranch_vccz .LBB0_1059
	s_barrier

;     __device__ __forceinline__ bool next(int i, Unit& u) const { if (i > 0 || c >= nitems) return false; u.pm = 64; u.pn = c % npn; u.k0 = (c / npn) * kslice; return true; }
; #define PG8_STAGE(bufoff, gbase, voff) do { _Pragma("unroll") for (int _i = 0; _i < 2; ++_i) \
;         __builtin_amdgcn_global_load_lds((const unsigned*)((const char*)(gbase) + (voff)[_i]), (PG8_LAS unsigned*)(lds + (bufoff) + ldsw + _i * 8192), 16, 0, 0); } while (0)
; #define PG8_LDA(dst, b, h) do { _Pragma("unroll") for (int m = 0; m < 4; ++m) _Pragma("unroll") for (int k = 0; k < 2; ++k) dst[m][k] = *(const PG8_LAS bf16x8*)(lds + PG8_SA(b, h) + aoff + m * 2048 + k * 1024); } while (0)
; #define PG8_LDB(dst, b, h) do { _Pragma("unroll") for (int n = 0; n < 2; ++n) _Pragma("unroll") for (int k = 0; k < 2; ++k) dst[n][k] = *(const PG8_LAS bf16x8*)(lds + PG8_SB(b, h) + boff + n * 2048 + k * 1024); } while (0)
; #define PG8_SCHED __builtin_amdgcn_sched_barrier(0)
; template <class Epi, class Sched, bool ALIGN_EPI = false, bool SP2 = false>
; __device__ __forceinline__ void gemm_phase(PG8_LAS unsigned char* lds, const Gemm g, const Sched& S, const Epi& E) {
;     ...
;         const bool has_next = S.next(ui + 1, nxt);
;         const char* nA = has_next ? (const char*)g.A + (size_t)nxt.pm * tstep + (size_t)nxt.k0 * 2 : cA; const char* nB = has_next ? (const char*)g.Bt + (size_t)nxt.pn * tstep + (size_t)nxt.k0 * 2 : cB;
;         for (int t = 0; t < nt; t += 2) {
;             const bool last = (t == nt - 2);
;             const char* a1 = cA + (size_t)(t + 1) * kstep;
;             const char* a2 = last ? nA : cA + (size_t)(t + 2) * kstep; const char* b2 = last ? nB : cB + (size_t)(t + 2) * kstep;
;             const char* a3 = a2 + kstep; const char* b3 = b2 + kstep;
;             if (last && has_next) S.a_ready(nxt);
;             if constexpr (SP2) {
;             PG8_LDB(B0, 0, 0); PG8_LDB(B1, 0, 1); PG8_SCHED; PG8_LDA(At, 0, 0); PG8_STAGE(PG8_SA(1, 1), a1 + hstep, voffA);
;     ...
;         for (int a = 0; a < 2; ++a)
; #pragma unroll
;             for (int b = 0; b < 2; ++b)
; #pragma unroll
;                 for (int m = 0; m < 4; ++m)
; #pragma unroll
;                     for (int n = 0; n < 2; ++n) acc[a][b][m][n] = (f32x4){0.f, 0.f, 0.f, 0.f};
.LBB0_1278:
	s_ashr_i32 s21, s20, 31
	s_lshl_b64 s[22:23], s[20:21], 20
	s_add_u32 s22, s3, s22
	s_addc_u32 s23, s33, s23
	s_and_b64 s[24:25], s[6:7], exec
	s_cselect_b32 s21, s23, s27
	s_cselect_b32 s50, s22, s26
	s_ashr_i32 s19, s18, 31
	s_lshl_b64 s[24:25], s[18:19], 20
	s_add_u32 s24, s34, s24
	s_addc_u32 s25, s35, s25
	s_and_b64 s[30:31], s[6:7], exec
	s_cselect_b32 s19, s25, s29
	s_cselect_b32 s51, s24, s28
	s_add_u32 s26, s26, 0x80080
	s_addc_u32 s27, s27, 0
	s_add_u32 s52, s28, 0x100
	v_mov_b32_e32 v0, 0
	s_addc_u32 s53, s29, 0
	s_mov_b32 s54, -2
	v_mov_b32_e32 v1, v0
	v_mov_b32_e32 v2, v0
	v_mov_b32_e32 v3, v0
	v_mov_b32_e32 v4, v0
	v_mov_b32_e32 v5, v0
	v_mov_b32_e32 v6, v0
	v_mov_b32_e32 v7, v0
	v_mov_b32_e32 v16, v0
	v_mov_b32_e32 v17, v0
	v_mov_b32_e32 v18, v0
	v_mov_b32_e32 v19, v0
	v_mov_b32_e32 v20, v0
	v_mov_b32_e32 v21, v0
	v_mov_b32_e32 v22, v0
	v_mov_b32_e32 v23, v0
	v_mov_b32_e32 v32, v0
	v_mov_b32_e32 v33, v0
	v_mov_b32_e32 v34, v0
	v_mov_b32_e32 v35, v0
	v_mov_b32_e32 v36, v0
	v_mov_b32_e32 v37, v0
	v_mov_b32_e32 v38, v0
	v_mov_b32_e32 v39, v0
	v_mov_b32_e32 v48, v0
	v_mov_b32_e32 v49, v0
	v_mov_b32_e32 v50, v0
	v_mov_b32_e32 v51, v0
	v_mov_b32_e32 v52, v0
	v_mov_b32_e32 v53, v0
	v_mov_b32_e32 v54, v0
	v_mov_b32_e32 v55, v0
	v_mov_b32_e32 v8, v0
	v_mov_b32_e32 v9, v0
	v_mov_b32_e32 v10, v0
	v_mov_b32_e32 v11, v0
	v_mov_b32_e32 v12, v0
	v_mov_b32_e32 v13, v0
	v_mov_b32_e32 v14, v0
	v_mov_b32_e32 v15, v0
	v_mov_b32_e32 v24, v0
	v_mov_b32_e32 v25, v0
	v_mov_b32_e32 v26, v0
	v_mov_b32_e32 v27, v0
	v_mov_b32_e32 v28, v0
	v_mov_b32_e32 v29, v0
	v_mov_b32_e32 v30, v0
	v_mov_b32_e32 v31, v0
	v_mov_b32_e32 v40, v0
	v_mov_b32_e32 v41, v0
	v_mov_b32_e32 v42, v0
	v_mov_b32_e32 v43, v0
	v_mov_b32_e32 v44, v0
	v_mov_b32_e32 v45, v0
	v_mov_b32_e32 v46, v0
	v_mov_b32_e32 v47, v0
	v_mov_b32_e32 v56, v0
	v_mov_b32_e32 v57, v0
	v_mov_b32_e32 v58, v0
	v_mov_b32_e32 v59, v0
	v_mov_b32_e32 v60, v0
	v_mov_b32_e32 v61, v0
	v_mov_b32_e32 v62, v0
	v_mov_b32_e32 v63, v0
	v_mov_b32_e32 v64, v0
	v_mov_b32_e32 v65, v0
	v_mov_b32_e32 v66, v0
	v_mov_b32_e32 v67, v0
	v_mov_b32_e32 v68, v0
	v_mov_b32_e32 v69, v0
	v_mov_b32_e32 v70, v0
	v_mov_b32_e32 v71, v0
	v_mov_b32_e32 v80, v0
	v_mov_b32_e32 v81, v0
	v_mov_b32_e32 v82, v0
	v_mov_b32_e32 v83, v0
	v_mov_b32_e32 v84, v0
	v_mov_b32_e32 v85, v0
	v_mov_b32_e32 v86, v0
	v_mov_b32_e32 v87, v0
	v_mov_b32_e32 v96, v0
	v_mov_b32_e32 v97, v0
	v_mov_b32_e32 v98, v0
	v_mov_b32_e32 v99, v0
	v_mov_b32_e32 v100, v0
	v_mov_b32_e32 v101, v0
	v_mov_b32_e32 v102, v0
	v_mov_b32_e32 v103, v0
	v_mov_b32_e32 v112, v0
	v_mov_b32_e32 v113, v0
	v_mov_b32_e32 v114, v0
	v_mov_b32_e32 v115, v0
	v_mov_b32_e32 v116, v0
	v_mov_b32_e32 v117, v0
	v_mov_b32_e32 v118, v0
	v_mov_b32_e32 v119, v0
	v_mov_b32_e32 v72, v0
	v_mov_b32_e32 v73, v0
	v_mov_b32_e32 v74, v0
	v_mov_b32_e32 v75, v0
	v_mov_b32_e32 v76, v0
	v_mov_b32_e32 v77, v0
	v_mov_b32_e32 v78, v0
	v_mov_b32_e32 v79, v0
	v_mov_b32_e32 v88, v0
	v_mov_b32_e32 v89, v0
	v_mov_b32_e32 v90, v0
	v_mov_b32_e32 v91, v0
	v_mov_b32_e32 v92, v0
	v_mov_b32_e32 v93, v0
	v_mov_b32_e32 v94, v0
	v_mov_b32_e32 v95, v0
	v_mov_b32_e32 v104, v0
	v_mov_b32_e32 v105, v0
	v_mov_b32_e32 v106, v0
	v_mov_b32_e32 v107, v0
	v_mov_b32_e32 v108, v0
	v_mov_b32_e32 v109, v0
	v_mov_b32_e32 v110, v0
	v_mov_b32_e32 v111, v0
	v_mov_b32_e32 v120, v0
	v_mov_b32_e32 v121, v0
	v_mov_b32_e32 v122, v0
	v_mov_b32_e32 v123, v0
	v_mov_b32_e32 v124, v0
	v_mov_b32_e32 v125, v0
	v_mov_b32_e32 v126, v0
	v_mov_b32_e32 v127, v0
	s_and_b64 vcc, exec, s[16:17]
	s_cbranch_vccnz .Lsp_skip_2
	s_setprio 1
.Lsp_skip_2:
.LBB0_1279:
	ds_read_b128 v[166:169], v149
	ds_read_b128 v[170:173], v149 offset:1024
	ds_read_b128 v[174:177], v149 offset:2048
	ds_read_b128 v[186:189], v149 offset:3072
	ds_read_b128 v[190:193], v159
	ds_read_b128 v[194:197], v159 offset:1024
	ds_read_b128 v[198:201], v159 offset:2048
	ds_read_b128 v[202:205], v159 offset:3072
	s_add_u32 s28, s26, 0xfff80080
	s_addc_u32 s29, s27, -1
	s_cmp_eq_u32 s54, 28
	s_cselect_b32 s31, s21, s29
	s_cselect_b32 s30, s50, s28
	s_cselect_b32 s29, s19, s53
	s_cselect_b32 s28, s51, s52
	s_add_i32 m0, s37, 0xc000
	ds_read_b128 v[206:209], v162
	ds_read_b128 v[210:213], v162 offset:1024
	ds_read_b128 v[214:217], v162 offset:2048
	ds_read_b128 v[218:221], v162 offset:3072
	ds_read_b128 v[222:225], v162 offset:4096
	ds_read_b128 v[226:229], v162 offset:5120
	ds_read_b128 v[230:233], v162 offset:6144
	ds_read_b128 v[234:237], v162 offset:7168
	global_load_lds_dwordx4 v128, s[26:27]
	s_add_i32 m0, s37, 0xe000
	s_nop 0
	global_load_lds_dwordx4 v130, s[26:27]
	s_waitcnt vmcnt(8)
	s_waitcnt lgkmcnt(0)
	s_barrier
; #define PG8_STAGE(bufoff, gbase, voff) do { _Pragma("unroll") for (int _i = 0; _i < 2; ++_i) \
;         __builtin_amdgcn_global_load_lds((const unsigned*)((const char*)(gbase) + (voff)[_i]), (PG8_LAS unsigned*)(lds + (bufoff) + ldsw + _i * 8192), 16, 0, 0); } while (0)
; #define PG8_LDA(dst, b, h) do { _Pragma("unroll") for (int m = 0; m < 4; ++m) _Pragma("unroll") for (int k = 0; k < 2; ++k) dst[m][k] = *(const PG8_LAS bf16x8*)(lds + PG8_SA(b, h) + aoff + m * 2048 + k * 1024); } while (0)
; #define PG8_MMA(ai, bj, At, Bt) do { __builtin_amdgcn_s_setprio(1); _Pragma("unroll") for (int m = 0; m < 4; ++m) _Pragma("unroll") for (int n = 0; n < 2; ++n) _Pragma("unroll") for (int k = 0; k < 2; ++k) \
;         acc[ai][bj][m][n] = __builtin_amdgcn_mfma_f32_16x16x32_bf16(Bt[n][k], At[m][k], acc[ai][bj][m][n], 0, 0, 0); __builtin_amdgcn_s_setprio(0); } while (0)
; #define PG8_WAIT_V(n) asm volatile("s_waitcnt vmcnt(" #n ")" ::: "memory")
; #define PG8_WAIT_L(n) asm volatile("s_waitcnt lgkmcnt(" #n ")" ::: "memory")
; #define PG8_BAR __builtin_amdgcn_s_barrier()
; #define PG8_SCHED __builtin_amdgcn_sched_barrier(0)
; template <class Epi, class Sched, bool ALIGN_EPI = false, bool SP2 = false>
; __device__ __forceinline__ void gemm_phase(PG8_LAS unsigned char* lds, const Gemm g, const Sched& S, const Epi& E) {
;     ...
;             PG8_WAIT_V(8); PG8_WAIT_L(0); PG8_BAR; PG8_MMA(0, 0, At, B0); PG8_MMA(0, 1, At, B1); PG8_BAR; PG8_SCHED;
;             PG8_LDA(At, 0, 1); PG8_STAGE(PG8_SB(0, 0), b2, voffB); PG8_STAGE(PG8_SB(0, 1), b2 + hstep, voffB); PG8_STAGE(PG8_SA(0, 0), a2, voffA);
;             PG8_WAIT_V(8); PG8_WAIT_L(0); PG8_BAR; PG8_MMA(1, 0, At, B0); PG8_MMA(1, 1, At, B1); PG8_BAR; PG8_SCHED;
	s_waitcnt lgkmcnt(0)
	v_mfma_f32_16x16x32_bf16 v[124:127], v[166:169], v[206:209], v[124:127]
	v_mfma_f32_16x16x32_bf16 v[124:127], v[170:173], v[210:213], v[124:127]
	v_mfma_f32_16x16x32_bf16 v[120:123], v[186:189], v[210:213], v[120:123]
	v_mfma_f32_16x16x32_bf16 v[120:123], v[174:177], v[206:209], v[120:123]
	v_mfma_f32_16x16x32_bf16 v[104:107], v[174:177], v[214:217], v[104:107]
	v_mfma_f32_16x16x32_bf16 v[104:107], v[186:189], v[218:221], v[104:107]
	v_mfma_f32_16x16x32_bf16 v[108:111], v[170:173], v[218:221], v[108:111]
	v_mfma_f32_16x16x32_bf16 v[108:111], v[166:169], v[214:217], v[108:111]
	v_mfma_f32_16x16x32_bf16 v[92:95], v[166:169], v[222:225], v[92:95]
	v_mfma_f32_16x16x32_bf16 v[92:95], v[170:173], v[226:229], v[92:95]
	v_mfma_f32_16x16x32_bf16 v[88:91], v[186:189], v[226:229], v[88:91]
	v_mfma_f32_16x16x32_bf16 v[88:91], v[174:177], v[222:225], v[88:91]
	v_mfma_f32_16x16x32_bf16 v[72:75], v[174:177], v[230:233], v[72:75]
	v_mfma_f32_16x16x32_bf16 v[72:75], v[186:189], v[234:237], v[72:75]
	v_mfma_f32_16x16x32_bf16 v[76:79], v[170:173], v[234:237], v[76:79]
	v_mfma_f32_16x16x32_bf16 v[76:79], v[166:169], v[230:233], v[76:79]
	v_mfma_f32_16x16x32_bf16 v[116:119], v[190:193], v[206:209], v[116:119]
	v_mfma_f32_16x16x32_bf16 v[116:119], v[194:197], v[210:213], v[116:119]
	v_mfma_f32_16x16x32_bf16 v[112:115], v[202:205], v[210:213], v[112:115]
	v_mfma_f32_16x16x32_bf16 v[112:115], v[198:201], v[206:209], v[112:115]
	v_mfma_f32_16x16x32_bf16 v[96:99], v[198:201], v[214:217], v[96:99]
	v_mfma_f32_16x16x32_bf16 v[96:99], v[202:205], v[218:221], v[96:99]
	v_mfma_f32_16x16x32_bf16 v[100:103], v[194:197], v[218:221], v[100:103]
	v_mfma_f32_16x16x32_bf16 v[100:103], v[190:193], v[214:217], v[100:103]
	v_mfma_f32_16x16x32_bf16 v[84:87], v[190:193], v[222:225], v[84:87]
	v_mfma_f32_16x16x32_bf16 v[84:87], v[194:197], v[226:229], v[84:87]
	v_mfma_f32_16x16x32_bf16 v[80:83], v[202:205], v[226:229], v[80:83]
	v_mfma_f32_16x16x32_bf16 v[80:83], v[198:201], v[222:225], v[80:83]
	v_mfma_f32_16x16x32_bf16 v[64:67], v[198:201], v[230:233], v[64:67]
	v_mfma_f32_16x16x32_bf16 v[64:67], v[202:205], v[234:237], v[64:67]
	v_mfma_f32_16x16x32_bf16 v[68:71], v[194:197], v[234:237], v[68:71]
	v_mfma_f32_16x16x32_bf16 v[68:71], v[190:193], v[230:233], v[68:71]
	s_barrier
	s_add_u32 s98, s28, 0x80
	s_addc_u32 s99, s29, 0
	s_add_u32 s100, s30, 0x80
	s_addc_u32 s101, s31, 0
	s_add_i32 s55, s46, s36
	s_mov_b32 m0, s55
	ds_read_b128 v[206:209], v162 offset:16384
	ds_read_b128 v[210:213], v162 offset:17408
	ds_read_b128 v[214:217], v162 offset:18432
	ds_read_b128 v[218:221], v162 offset:19456
	ds_read_b128 v[222:225], v162 offset:20480
	ds_read_b128 v[226:229], v162 offset:21504
	ds_read_b128 v[230:233], v162 offset:22528
	ds_read_b128 v[234:237], v162 offset:23552
	global_load_lds_dwordx4 v152, s[28:29]
	s_add_i32 m0, s55, 0x2000
	s_add_u32 s56, s28, 0x80000
	s_addc_u32 s57, s29, 0
	s_add_i32 s55, s47, s36
	global_load_lds_dwordx4 v156, s[28:29]
	s_mov_b32 m0, s55
	s_nop 0
	global_load_lds_dwordx4 v152, s[56:57]
	s_add_i32 m0, s55, 0x2000
	s_nop 0
	global_load_lds_dwordx4 v156, s[56:57]
	s_mov_b32 m0, s37
	s_nop 0
	global_load_lds_dwordx4 v150, s[30:31]
	s_mov_b32 m0, s38
	s_nop 0
	global_load_lds_dwordx4 v154, s[30:31]
	s_waitcnt vmcnt(8)
	s_waitcnt lgkmcnt(0)
	s_barrier
	s_waitcnt lgkmcnt(0)
	v_mfma_f32_16x16x32_bf16 v[60:63], v[166:169], v[206:209], v[60:63]
	v_mfma_f32_16x16x32_bf16 v[60:63], v[170:173], v[210:213], v[60:63]
	v_mfma_f32_16x16x32_bf16 v[56:59], v[186:189], v[210:213], v[56:59]
	v_mfma_f32_16x16x32_bf16 v[56:59], v[174:177], v[206:209], v[56:59]
	v_mfma_f32_16x16x32_bf16 v[40:43], v[174:177], v[214:217], v[40:43]
	v_mfma_f32_16x16x32_bf16 v[40:43], v[186:189], v[218:221], v[40:43]
	v_mfma_f32_16x16x32_bf16 v[44:47], v[170:173], v[218:221], v[44:47]
	v_mfma_f32_16x16x32_bf16 v[44:47], v[166:169], v[214:217], v[44:47]
	v_mfma_f32_16x16x32_bf16 v[28:31], v[166:169], v[222:225], v[28:31]
	v_mfma_f32_16x16x32_bf16 v[28:31], v[170:173], v[226:229], v[28:31]
	v_mfma_f32_16x16x32_bf16 v[24:27], v[186:189], v[226:229], v[24:27]
	v_mfma_f32_16x16x32_bf16 v[24:27], v[174:177], v[222:225], v[24:27]
	v_mfma_f32_16x16x32_bf16 v[8:11], v[174:177], v[230:233], v[8:11]
	v_mfma_f32_16x16x32_bf16 v[8:11], v[186:189], v[234:237], v[8:11]
	v_mfma_f32_16x16x32_bf16 v[12:15], v[170:173], v[234:237], v[12:15]
	v_mfma_f32_16x16x32_bf16 v[12:15], v[166:169], v[230:233], v[12:15]
	v_mfma_f32_16x16x32_bf16 v[52:55], v[190:193], v[206:209], v[52:55]
	v_mfma_f32_16x16x32_bf16 v[52:55], v[194:197], v[210:213], v[52:55]
	v_mfma_f32_16x16x32_bf16 v[48:51], v[202:205], v[210:213], v[48:51]
	v_mfma_f32_16x16x32_bf16 v[48:51], v[198:201], v[206:209], v[48:51]
	v_mfma_f32_16x16x32_bf16 v[32:35], v[198:201], v[214:217], v[32:35]
	v_mfma_f32_16x16x32_bf16 v[32:35], v[202:205], v[218:221], v[32:35]
	v_mfma_f32_16x16x32_bf16 v[36:39], v[194:197], v[218:221], v[36:39]
	v_mfma_f32_16x16x32_bf16 v[36:39], v[190:193], v[214:217], v[36:39]
	v_mfma_f32_16x16x32_bf16 v[20:23], v[190:193], v[222:225], v[20:23]
	v_mfma_f32_16x16x32_bf16 v[20:23], v[194:197], v[226:229], v[20:23]
	v_mfma_f32_16x16x32_bf16 v[16:19], v[202:205], v[226:229], v[16:19]
	v_mfma_f32_16x16x32_bf16 v[16:19], v[198:201], v[222:225], v[16:19]
	v_mfma_f32_16x16x32_bf16 v[0:3], v[198:201], v[230:233], v[0:3]
	v_mfma_f32_16x16x32_bf16 v[0:3], v[202:205], v[234:237], v[0:3]
	v_mfma_f32_16x16x32_bf16 v[4:7], v[194:197], v[234:237], v[4:7]
	v_mfma_f32_16x16x32_bf16 v[4:7], v[190:193], v[230:233], v[4:7]
	s_barrier
; #define PG8_STAGE(bufoff, gbase, voff) do { _Pragma("unroll") for (int _i = 0; _i < 2; ++_i) \
;         __builtin_amdgcn_global_load_lds((const unsigned*)((const char*)(gbase) + (voff)[_i]), (PG8_LAS unsigned*)(lds + (bufoff) + ldsw + _i * 8192), 16, 0, 0); } while (0)
; #define PG8_LDA(dst, b, h) do { _Pragma("unroll") for (int m = 0; m < 4; ++m) _Pragma("unroll") for (int k = 0; k < 2; ++k) dst[m][k] = *(const PG8_LAS bf16x8*)(lds + PG8_SA(b, h) + aoff + m * 2048 + k * 1024); } while (0)
; #define PG8_LDB(dst, b, h) do { _Pragma("unroll") for (int n = 0; n < 2; ++n) _Pragma("unroll") for (int k = 0; k < 2; ++k) dst[n][k] = *(const PG8_LAS bf16x8*)(lds + PG8_SB(b, h) + boff + n * 2048 + k * 1024); } while (0)
; #define PG8_MMA(ai, bj, At, Bt) do { __builtin_amdgcn_s_setprio(1); _Pragma("unroll") for (int m = 0; m < 4; ++m) _Pragma("unroll") for (int n = 0; n < 2; ++n) _Pragma("unroll") for (int k = 0; k < 2; ++k) \
;         acc[ai][bj][m][n] = __builtin_amdgcn_mfma_f32_16x16x32_bf16(Bt[n][k], At[m][k], acc[ai][bj][m][n], 0, 0, 0); __builtin_amdgcn_s_setprio(0); } while (0)
; #define PG8_WAIT_V(n) asm volatile("s_waitcnt vmcnt(" #n ")" ::: "memory")
; #define PG8_WAIT_L(n) asm volatile("s_waitcnt lgkmcnt(" #n ")" ::: "memory")
; #define PG8_BAR __builtin_amdgcn_s_barrier()
; #define PG8_SCHED __builtin_amdgcn_sched_barrier(0)
; template <class Epi, class Sched, bool ALIGN_EPI = false, bool SP2 = false>
; __device__ __forceinline__ void gemm_phase(PG8_LAS unsigned char* lds, const Gemm g, const Sched& S, const Epi& E) {
;     ...
;             PG8_LDB(B0, 1, 0); PG8_LDB(B1, 1, 1); PG8_SCHED; PG8_LDA(At, 1, 0); PG8_STAGE(PG8_SA(0, 1), a2 + hstep, voffA);
;             PG8_WAIT_V(8); PG8_WAIT_L(0); PG8_BAR; PG8_MMA(0, 0, At, B0); PG8_MMA(0, 1, At, B1); PG8_BAR; PG8_SCHED;
;             PG8_LDA(At, 1, 1); PG8_STAGE(PG8_SB(1, 0), b3, voffB); PG8_STAGE(PG8_SB(1, 1), b3 + hstep, voffB); PG8_STAGE(PG8_SA(1, 0), a3, voffA);
;             PG8_WAIT_V(8); PG8_WAIT_L(0); PG8_BAR; PG8_MMA(1, 0, At, B0); PG8_MMA(1, 1, At, B1); PG8_BAR; PG8_SCHED;
;     ...
;         if constexpr (ALIGN_EPI) { if (wr == 0) PG8_BAR; }
	s_add_i32 s55, 0, 0x18000
	v_add_u32_e32 v165, s55, v145
	s_add_i32 s56, 0, 0x1c000
	ds_read_b128 v[166:169], v165
	ds_read_b128 v[170:173], v165 offset:1024
	ds_read_b128 v[174:177], v165 offset:2048
	ds_read_b128 v[186:189], v165 offset:3072
	v_add_u32_e32 v165, s56, v145
	ds_read_b128 v[190:193], v165
	ds_read_b128 v[194:197], v165 offset:1024
	ds_read_b128 v[198:201], v165 offset:2048
	ds_read_b128 v[202:205], v165 offset:3072
	s_add_u32 s30, s30, 0x80000
	s_addc_u32 s31, s31, 0
	s_mov_b32 m0, s39
	ds_read_b128 v[206:209], v162 offset:32768
	ds_read_b128 v[210:213], v162 offset:33792
	ds_read_b128 v[214:217], v162 offset:34816
	ds_read_b128 v[218:221], v162 offset:35840
	ds_read_b128 v[222:225], v162 offset:36864
	ds_read_b128 v[226:229], v162 offset:37888
	ds_read_b128 v[230:233], v162 offset:38912
	ds_read_b128 v[234:237], v162 offset:39936
	global_load_lds_dwordx4 v150, s[30:31]
	s_mov_b32 m0, s40
	s_nop 0
	global_load_lds_dwordx4 v154, s[30:31]
	s_waitcnt vmcnt(8)
	s_waitcnt lgkmcnt(0)
	s_barrier
	s_waitcnt lgkmcnt(0)
	v_mfma_f32_16x16x32_bf16 v[124:127], v[166:169], v[206:209], v[124:127]
	v_mfma_f32_16x16x32_bf16 v[124:127], v[170:173], v[210:213], v[124:127]
	v_mfma_f32_16x16x32_bf16 v[120:123], v[186:189], v[210:213], v[120:123]
	v_mfma_f32_16x16x32_bf16 v[120:123], v[174:177], v[206:209], v[120:123]
	v_mfma_f32_16x16x32_bf16 v[104:107], v[174:177], v[214:217], v[104:107]
	v_mfma_f32_16x16x32_bf16 v[104:107], v[186:189], v[218:221], v[104:107]
	v_mfma_f32_16x16x32_bf16 v[108:111], v[170:173], v[218:221], v[108:111]
	v_mfma_f32_16x16x32_bf16 v[108:111], v[166:169], v[214:217], v[108:111]
	v_mfma_f32_16x16x32_bf16 v[92:95], v[166:169], v[222:225], v[92:95]
	v_mfma_f32_16x16x32_bf16 v[92:95], v[170:173], v[226:229], v[92:95]
	v_mfma_f32_16x16x32_bf16 v[88:91], v[186:189], v[226:229], v[88:91]
	v_mfma_f32_16x16x32_bf16 v[88:91], v[174:177], v[222:225], v[88:91]
	v_mfma_f32_16x16x32_bf16 v[72:75], v[174:177], v[230:233], v[72:75]
	v_mfma_f32_16x16x32_bf16 v[72:75], v[186:189], v[234:237], v[72:75]
	v_mfma_f32_16x16x32_bf16 v[76:79], v[170:173], v[234:237], v[76:79]
	v_mfma_f32_16x16x32_bf16 v[76:79], v[166:169], v[230:233], v[76:79]
	v_mfma_f32_16x16x32_bf16 v[116:119], v[190:193], v[206:209], v[116:119]
	v_mfma_f32_16x16x32_bf16 v[116:119], v[194:197], v[210:213], v[116:119]
	v_mfma_f32_16x16x32_bf16 v[112:115], v[202:205], v[210:213], v[112:115]
	v_mfma_f32_16x16x32_bf16 v[112:115], v[198:201], v[206:209], v[112:115]
	v_mfma_f32_16x16x32_bf16 v[96:99], v[198:201], v[214:217], v[96:99]
	v_mfma_f32_16x16x32_bf16 v[96:99], v[202:205], v[218:221], v[96:99]
	v_mfma_f32_16x16x32_bf16 v[100:103], v[194:197], v[218:221], v[100:103]
	v_mfma_f32_16x16x32_bf16 v[100:103], v[190:193], v[214:217], v[100:103]
	v_mfma_f32_16x16x32_bf16 v[84:87], v[190:193], v[222:225], v[84:87]
	v_mfma_f32_16x16x32_bf16 v[84:87], v[194:197], v[226:229], v[84:87]
	v_mfma_f32_16x16x32_bf16 v[80:83], v[202:205], v[226:229], v[80:83]
	v_mfma_f32_16x16x32_bf16 v[80:83], v[198:201], v[222:225], v[80:83]
	v_mfma_f32_16x16x32_bf16 v[64:67], v[198:201], v[230:233], v[64:67]
	v_mfma_f32_16x16x32_bf16 v[64:67], v[202:205], v[234:237], v[64:67]
	v_mfma_f32_16x16x32_bf16 v[68:71], v[194:197], v[234:237], v[68:71]
	v_mfma_f32_16x16x32_bf16 v[68:71], v[190:193], v[230:233], v[68:71]
	s_barrier
	s_add_i32 s30, s55, s36
	s_mov_b32 m0, s30
	ds_read_b128 v[206:209], v162 offset:49152
	ds_read_b128 v[210:213], v162 offset:50176
	ds_read_b128 v[214:217], v162 offset:51200
	ds_read_b128 v[218:221], v162 offset:52224
	ds_read_b128 v[222:225], v162 offset:53248
	ds_read_b128 v[226:229], v162 offset:54272
	ds_read_b128 v[230:233], v162 offset:55296
	ds_read_b128 v[234:237], v162 offset:56320
	global_load_lds_dwordx4 v152, s[98:99]
	s_add_i32 m0, s30, 0x2000
	s_add_u32 s28, s28, 0x80080
	s_addc_u32 s29, s29, 0
	s_add_i32 s30, s56, s36
	global_load_lds_dwordx4 v156, s[98:99]
	s_mov_b32 m0, s30
	s_nop 0
	global_load_lds_dwordx4 v152, s[28:29]
	s_add_i32 m0, s30, 0x2000
	s_nop 0
	global_load_lds_dwordx4 v156, s[28:29]
	s_mov_b32 m0, s42
	s_nop 0
	global_load_lds_dwordx4 v150, s[100:101]
	s_mov_b32 m0, s43
	s_nop 0
	global_load_lds_dwordx4 v154, s[100:101]
	s_waitcnt vmcnt(8)
	s_waitcnt lgkmcnt(0)
	s_barrier
	s_waitcnt lgkmcnt(0)
	v_mfma_f32_16x16x32_bf16 v[60:63], v[166:169], v[206:209], v[60:63]
	v_mfma_f32_16x16x32_bf16 v[60:63], v[170:173], v[210:213], v[60:63]
	v_mfma_f32_16x16x32_bf16 v[56:59], v[186:189], v[210:213], v[56:59]
	v_mfma_f32_16x16x32_bf16 v[56:59], v[174:177], v[206:209], v[56:59]
	v_mfma_f32_16x16x32_bf16 v[40:43], v[174:177], v[214:217], v[40:43]
	v_mfma_f32_16x16x32_bf16 v[40:43], v[186:189], v[218:221], v[40:43]
	v_mfma_f32_16x16x32_bf16 v[44:47], v[170:173], v[218:221], v[44:47]
	v_mfma_f32_16x16x32_bf16 v[44:47], v[166:169], v[214:217], v[44:47]
	v_mfma_f32_16x16x32_bf16 v[28:31], v[166:169], v[222:225], v[28:31]
	v_mfma_f32_16x16x32_bf16 v[28:31], v[170:173], v[226:229], v[28:31]
	v_mfma_f32_16x16x32_bf16 v[24:27], v[186:189], v[226:229], v[24:27]
	v_mfma_f32_16x16x32_bf16 v[24:27], v[174:177], v[222:225], v[24:27]
	v_mfma_f32_16x16x32_bf16 v[8:11], v[174:177], v[230:233], v[8:11]
	v_mfma_f32_16x16x32_bf16 v[8:11], v[186:189], v[234:237], v[8:11]
	v_mfma_f32_16x16x32_bf16 v[12:15], v[170:173], v[234:237], v[12:15]
	v_mfma_f32_16x16x32_bf16 v[12:15], v[166:169], v[230:233], v[12:15]
	v_mfma_f32_16x16x32_bf16 v[52:55], v[190:193], v[206:209], v[52:55]
	v_mfma_f32_16x16x32_bf16 v[52:55], v[194:197], v[210:213], v[52:55]
	v_mfma_f32_16x16x32_bf16 v[48:51], v[202:205], v[210:213], v[48:51]
	v_mfma_f32_16x16x32_bf16 v[48:51], v[198:201], v[206:209], v[48:51]
	v_mfma_f32_16x16x32_bf16 v[32:35], v[198:201], v[214:217], v[32:35]
	v_mfma_f32_16x16x32_bf16 v[32:35], v[202:205], v[218:221], v[32:35]
	v_mfma_f32_16x16x32_bf16 v[36:39], v[194:197], v[218:221], v[36:39]
	v_mfma_f32_16x16x32_bf16 v[36:39], v[190:193], v[214:217], v[36:39]
	v_mfma_f32_16x16x32_bf16 v[20:23], v[190:193], v[222:225], v[20:23]
	v_mfma_f32_16x16x32_bf16 v[20:23], v[194:197], v[226:229], v[20:23]
	v_mfma_f32_16x16x32_bf16 v[16:19], v[202:205], v[226:229], v[16:19]
	v_mfma_f32_16x16x32_bf16 v[16:19], v[198:201], v[222:225], v[16:19]
	v_mfma_f32_16x16x32_bf16 v[0:3], v[198:201], v[230:233], v[0:3]
	v_mfma_f32_16x16x32_bf16 v[0:3], v[202:205], v[234:237], v[0:3]
	v_mfma_f32_16x16x32_bf16 v[4:7], v[194:197], v[234:237], v[4:7]
	v_mfma_f32_16x16x32_bf16 v[4:7], v[190:193], v[230:233], v[4:7]
	s_barrier
	s_add_i32 s54, s54, 2
	s_add_u32 s26, s26, 0x100
	s_addc_u32 s27, s27, 0
	s_add_u32 s52, s52, 0x100
	s_addc_u32 s53, s53, 0
	s_cmp_gt_u32 s54, 29
	s_cbranch_scc0 .LBB0_1279
	s_setprio 0
	s_and_b64 vcc, exec, s[16:17]
	s_cbranch_vccz .LBB0_1282
	s_barrier

;     __device__ __forceinline__ bool next(int i, Unit& u) const { if (i > 0 || c >= nitems) return false; u.pm = 64; u.pn = c % npn; u.k0 = (c / npn) * kslice; return true; }
; template <class Epi, class Sched, bool ALIGN_EPI = false, bool SP2 = false>
; __device__ __forceinline__ void gemm_phase(PG8_LAS unsigned char* lds, const Gemm g, const Sched& S, const Epi& E) {
;     ...
;         const bool has_next = S.next(ui + 1, nxt);
;         const char* nA = has_next ? (const char*)g.A + (size_t)nxt.pm * tstep + (size_t)nxt.k0 * 2 : cA; const char* nB = has_next ? (const char*)g.Bt + (size_t)nxt.pn * tstep + (size_t)nxt.k0 * 2 : cB;
;         for (int t = 0; t < nt; t += 2) {
;             const bool last = (t == nt - 2);
;             const char* a1 = cA + (size_t)(t + 1) * kstep;
;             const char* a2 = last ? nA : cA + (size_t)(t + 2) * kstep; const char* b2 = last ? nB : cB + (size_t)(t + 2) * kstep;
;             const char* a3 = a2 + kstep; const char* b3 = b2 + kstep;
;             if (last && has_next) S.a_ready(nxt);
;             if constexpr (SP2) {
;             PG8_LDB(B0, 0, 0); PG8_LDB(B1, 0, 1); PG8_SCHED; PG8_LDA(At, 0, 0); PG8_STAGE(PG8_SA(1, 1), a1 + hstep, voffA);
;             PG8_WAIT_V(8); PG8_WAIT_L(0); PG8_BAR; PG8_MMA(0, 0, At, B0); PG8_MMA(0, 1, At, B1); PG8_BAR; PG8_SCHED;
;             PG8_LDA(At, 0, 1); PG8_STAGE(PG8_SB(0, 0), b2, voffB); PG8_STAGE(PG8_SB(0, 1), b2 + hstep, voffB); PG8_STAGE(PG8_SA(0, 0), a2, voffA);
;             PG8_WAIT_V(8); PG8_WAIT_L(0); PG8_BAR; PG8_MMA(1, 0, At, B0); PG8_MMA(1, 1, At, B1); PG8_BAR; PG8_SCHED;
;             PG8_LDB(B0, 1, 0); PG8_LDB(B1, 1, 1); PG8_SCHED; PG8_LDA(At, 1, 0); PG8_STAGE(PG8_SA(0, 1), a2 + hstep, voffA);
;             PG8_WAIT_V(8); PG8_WAIT_L(0); PG8_BAR; PG8_MMA(0, 0, At, B0); PG8_MMA(0, 1, At, B1); PG8_BAR; PG8_SCHED;
;             PG8_LDA(At, 1, 1); PG8_STAGE(PG8_SB(1, 0), b3, voffB); PG8_STAGE(PG8_SB(1, 1), b3 + hstep, voffB); PG8_STAGE(PG8_SA(1, 0), a3, voffA);
;             PG8_WAIT_V(8); PG8_WAIT_L(0); PG8_BAR; PG8_MMA(1, 0, At, B0); PG8_MMA(1, 1, At, B1); PG8_BAR; PG8_SCHED;
;     ...
;         for (int a = 0; a < 2; ++a)
; #pragma unroll
;             for (int b = 0; b < 2; ++b)
; #pragma unroll
;                 for (int m = 0; m < 4; ++m)
; #pragma unroll
;                     for (int n = 0; n < 2; ++n) acc[a][b][m][n] = (f32x4){0.f, 0.f, 0.f, 0.f};
.LBB0_1360:
	s_add_u32 s20, s20, 0x160080
	s_addc_u32 s21, s21, 0
	s_add_u32 s53, s22, 0x100
	v_mov_b32_e32 v0, 0
	s_addc_u32 s54, s23, 0
	s_mov_b32 s55, -2
	v_mov_b32_e32 v1, v0
	v_mov_b32_e32 v2, v0
	v_mov_b32_e32 v3, v0
	v_mov_b32_e32 v4, v0
	v_mov_b32_e32 v5, v0
	v_mov_b32_e32 v6, v0
	v_mov_b32_e32 v7, v0
	v_mov_b32_e32 v16, v0
	v_mov_b32_e32 v17, v0
	v_mov_b32_e32 v18, v0
	v_mov_b32_e32 v19, v0
	v_mov_b32_e32 v20, v0
	v_mov_b32_e32 v21, v0
	v_mov_b32_e32 v22, v0
	v_mov_b32_e32 v23, v0
	v_mov_b32_e32 v32, v0
	v_mov_b32_e32 v33, v0
	v_mov_b32_e32 v34, v0
	v_mov_b32_e32 v35, v0
	v_mov_b32_e32 v36, v0
	v_mov_b32_e32 v37, v0
	v_mov_b32_e32 v38, v0
	v_mov_b32_e32 v39, v0
	v_mov_b32_e32 v48, v0
	v_mov_b32_e32 v49, v0
	v_mov_b32_e32 v50, v0
	v_mov_b32_e32 v51, v0
	v_mov_b32_e32 v52, v0
	v_mov_b32_e32 v53, v0
	v_mov_b32_e32 v54, v0
	v_mov_b32_e32 v55, v0
	v_mov_b32_e32 v8, v0
	v_mov_b32_e32 v9, v0
	v_mov_b32_e32 v10, v0
	v_mov_b32_e32 v11, v0
	v_mov_b32_e32 v12, v0
	v_mov_b32_e32 v13, v0
	v_mov_b32_e32 v14, v0
	v_mov_b32_e32 v15, v0
	v_mov_b32_e32 v24, v0
	v_mov_b32_e32 v25, v0
	v_mov_b32_e32 v26, v0
	v_mov_b32_e32 v27, v0
	v_mov_b32_e32 v28, v0
	v_mov_b32_e32 v29, v0
	v_mov_b32_e32 v30, v0
	v_mov_b32_e32 v31, v0
	v_mov_b32_e32 v40, v0
	v_mov_b32_e32 v41, v0
	v_mov_b32_e32 v42, v0
	v_mov_b32_e32 v43, v0
	v_mov_b32_e32 v44, v0
	v_mov_b32_e32 v45, v0
	v_mov_b32_e32 v46, v0
	v_mov_b32_e32 v47, v0
	v_mov_b32_e32 v56, v0
	v_mov_b32_e32 v57, v0
	v_mov_b32_e32 v58, v0
	v_mov_b32_e32 v59, v0
	v_mov_b32_e32 v60, v0
	v_mov_b32_e32 v61, v0
	v_mov_b32_e32 v62, v0
	v_mov_b32_e32 v63, v0
	v_mov_b32_e32 v64, v0
	v_mov_b32_e32 v65, v0
	v_mov_b32_e32 v66, v0
	v_mov_b32_e32 v67, v0
	v_mov_b32_e32 v68, v0
	v_mov_b32_e32 v69, v0
	v_mov_b32_e32 v70, v0
	v_mov_b32_e32 v71, v0
	v_mov_b32_e32 v80, v0
	v_mov_b32_e32 v81, v0
	v_mov_b32_e32 v82, v0
	v_mov_b32_e32 v83, v0
	v_mov_b32_e32 v84, v0
	v_mov_b32_e32 v85, v0
	v_mov_b32_e32 v86, v0
	v_mov_b32_e32 v87, v0
	v_mov_b32_e32 v96, v0
	v_mov_b32_e32 v97, v0
	v_mov_b32_e32 v98, v0
	v_mov_b32_e32 v99, v0
	v_mov_b32_e32 v100, v0
	v_mov_b32_e32 v101, v0
	v_mov_b32_e32 v102, v0
	v_mov_b32_e32 v103, v0
	v_mov_b32_e32 v112, v0
	v_mov_b32_e32 v113, v0
	v_mov_b32_e32 v114, v0
	v_mov_b32_e32 v115, v0
	v_mov_b32_e32 v116, v0
	v_mov_b32_e32 v117, v0
	v_mov_b32_e32 v118, v0
	v_mov_b32_e32 v119, v0
	v_mov_b32_e32 v72, v0
	v_mov_b32_e32 v73, v0
	v_mov_b32_e32 v74, v0
	v_mov_b32_e32 v75, v0
	v_mov_b32_e32 v76, v0
	v_mov_b32_e32 v77, v0
	v_mov_b32_e32 v78, v0
	v_mov_b32_e32 v79, v0
	v_mov_b32_e32 v88, v0
	v_mov_b32_e32 v89, v0
	v_mov_b32_e32 v90, v0
	v_mov_b32_e32 v91, v0
	v_mov_b32_e32 v92, v0
	v_mov_b32_e32 v93, v0
	v_mov_b32_e32 v94, v0
	v_mov_b32_e32 v95, v0
	v_mov_b32_e32 v104, v0
	v_mov_b32_e32 v105, v0
	v_mov_b32_e32 v106, v0
	v_mov_b32_e32 v107, v0
	v_mov_b32_e32 v108, v0
	v_mov_b32_e32 v109, v0
	v_mov_b32_e32 v110, v0
	v_mov_b32_e32 v111, v0
	v_mov_b32_e32 v120, v0
	v_mov_b32_e32 v121, v0
	v_mov_b32_e32 v122, v0
	v_mov_b32_e32 v123, v0
	v_mov_b32_e32 v124, v0
	v_mov_b32_e32 v125, v0
	v_mov_b32_e32 v126, v0
	v_mov_b32_e32 v127, v0
	s_and_b64 vcc, exec, s[16:17]
	s_cbranch_vccnz .Lsp_skip_1
	s_setprio 1
.Lsp_skip_1:
.LBB0_1361:
	ds_read_b128 v[128:131], v166
	ds_read_b128 v[132:135], v166 offset:1024
	ds_read_b128 v[160:163], v166 offset:2048
	ds_read_b128 v[170:173], v166 offset:3072
	ds_read_b128 v[174:177], v167
	ds_read_b128 v[186:189], v167 offset:1024
	ds_read_b128 v[190:193], v167 offset:2048
	ds_read_b128 v[194:197], v167 offset:3072
	s_add_u32 s22, s20, 0xffea0080
	s_addc_u32 s23, s21, -1
	s_cmpk_eq_i32 s55, 0x54
	s_cselect_b32 s25, s7, s23
	s_cselect_b32 s24, s6, s22
	s_cselect_b32 s23, s19, s54
	s_cselect_b32 s22, s18, s53
	s_add_i32 m0, s29, 0xc000
	ds_read_b128 v[198:201], v168
	ds_read_b128 v[202:205], v168 offset:1024
	ds_read_b128 v[206:209], v168 offset:2048
	ds_read_b128 v[210:213], v168 offset:3072
	ds_read_b128 v[214:217], v168 offset:4096
	ds_read_b128 v[218:221], v168 offset:5120
	ds_read_b128 v[222:225], v168 offset:6144
	ds_read_b128 v[226:229], v168 offset:7168
	global_load_lds_dwordx4 v150, s[20:21]
	s_add_i32 m0, s29, 0xe000
	s_nop 0
	global_load_lds_dwordx4 v152, s[20:21]
	s_waitcnt vmcnt(8)
	s_waitcnt lgkmcnt(0)
	s_barrier
	s_waitcnt lgkmcnt(0)
	v_mfma_f32_16x16x32_bf16 v[124:127], v[128:131], v[198:201], v[124:127]
	v_mfma_f32_16x16x32_bf16 v[124:127], v[132:135], v[202:205], v[124:127]
	v_mfma_f32_16x16x32_bf16 v[120:123], v[170:173], v[202:205], v[120:123]
	v_mfma_f32_16x16x32_bf16 v[120:123], v[160:163], v[198:201], v[120:123]
	v_mfma_f32_16x16x32_bf16 v[104:107], v[160:163], v[206:209], v[104:107]
	v_mfma_f32_16x16x32_bf16 v[104:107], v[170:173], v[210:213], v[104:107]
	v_mfma_f32_16x16x32_bf16 v[108:111], v[132:135], v[210:213], v[108:111]
	v_mfma_f32_16x16x32_bf16 v[108:111], v[128:131], v[206:209], v[108:111]
	v_mfma_f32_16x16x32_bf16 v[92:95], v[128:131], v[214:217], v[92:95]
	v_mfma_f32_16x16x32_bf16 v[92:95], v[132:135], v[218:221], v[92:95]
	v_mfma_f32_16x16x32_bf16 v[88:91], v[170:173], v[218:221], v[88:91]
	v_mfma_f32_16x16x32_bf16 v[88:91], v[160:163], v[214:217], v[88:91]
	v_mfma_f32_16x16x32_bf16 v[72:75], v[160:163], v[222:225], v[72:75]
	v_mfma_f32_16x16x32_bf16 v[72:75], v[170:173], v[226:229], v[72:75]
	v_mfma_f32_16x16x32_bf16 v[76:79], v[132:135], v[226:229], v[76:79]
	v_mfma_f32_16x16x32_bf16 v[76:79], v[128:131], v[222:225], v[76:79]
	v_mfma_f32_16x16x32_bf16 v[116:119], v[174:177], v[198:201], v[116:119]
	v_mfma_f32_16x16x32_bf16 v[116:119], v[186:189], v[202:205], v[116:119]
	v_mfma_f32_16x16x32_bf16 v[112:115], v[194:197], v[202:205], v[112:115]
	v_mfma_f32_16x16x32_bf16 v[112:115], v[190:193], v[198:201], v[112:115]
	v_mfma_f32_16x16x32_bf16 v[96:99], v[190:193], v[206:209], v[96:99]
	v_mfma_f32_16x16x32_bf16 v[96:99], v[194:197], v[210:213], v[96:99]
	v_mfma_f32_16x16x32_bf16 v[100:103], v[186:189], v[210:213], v[100:103]
	v_mfma_f32_16x16x32_bf16 v[100:103], v[174:177], v[206:209], v[100:103]
	v_mfma_f32_16x16x32_bf16 v[84:87], v[174:177], v[214:217], v[84:87]
	v_mfma_f32_16x16x32_bf16 v[84:87], v[186:189], v[218:221], v[84:87]
	v_mfma_f32_16x16x32_bf16 v[80:83], v[194:197], v[218:221], v[80:83]
	v_mfma_f32_16x16x32_bf16 v[80:83], v[190:193], v[214:217], v[80:83]
	v_mfma_f32_16x16x32_bf16 v[64:67], v[190:193], v[222:225], v[64:67]
	v_mfma_f32_16x16x32_bf16 v[64:67], v[194:197], v[226:229], v[64:67]
	v_mfma_f32_16x16x32_bf16 v[68:71], v[186:189], v[226:229], v[68:71]
	v_mfma_f32_16x16x32_bf16 v[68:71], v[174:177], v[222:225], v[68:71]
	s_barrier
; #define PG8_STAGE(bufoff, gbase, voff) do { _Pragma("unroll") for (int _i = 0; _i < 2; ++_i) \
;         __builtin_amdgcn_global_load_lds((const unsigned*)((const char*)(gbase) + (voff)[_i]), (PG8_LAS unsigned*)(lds + (bufoff) + ldsw + _i * 8192), 16, 0, 0); } while (0)
; #define PG8_LDA(dst, b, h) do { _Pragma("unroll") for (int m = 0; m < 4; ++m) _Pragma("unroll") for (int k = 0; k < 2; ++k) dst[m][k] = *(const PG8_LAS bf16x8*)(lds + PG8_SA(b, h) + aoff + m * 2048 + k * 1024); } while (0)
; #define PG8_LDB(dst, b, h) do { _Pragma("unroll") for (int n = 0; n < 2; ++n) _Pragma("unroll") for (int k = 0; k < 2; ++k) dst[n][k] = *(const PG8_LAS bf16x8*)(lds + PG8_SB(b, h) + boff + n * 2048 + k * 1024); } while (0)
; #define PG8_MMA(ai, bj, At, Bt) do { __builtin_amdgcn_s_setprio(1); _Pragma("unroll") for (int m = 0; m < 4; ++m) _Pragma("unroll") for (int n = 0; n < 2; ++n) _Pragma("unroll") for (int k = 0; k < 2; ++k) \
;         acc[ai][bj][m][n] = __builtin_amdgcn_mfma_f32_16x16x32_bf16(Bt[n][k], At[m][k], acc[ai][bj][m][n], 0, 0, 0); __builtin_amdgcn_s_setprio(0); } while (0)
; #define PG8_WAIT_V(n) asm volatile("s_waitcnt vmcnt(" #n ")" ::: "memory")
; #define PG8_WAIT_L(n) asm volatile("s_waitcnt lgkmcnt(" #n ")" ::: "memory")
; #define PG8_BAR __builtin_amdgcn_s_barrier()
; #define PG8_SCHED __builtin_amdgcn_sched_barrier(0)
; template <class Epi, class Sched, bool ALIGN_EPI = false, bool SP2 = false>
; __device__ __forceinline__ void gemm_phase(PG8_LAS unsigned char* lds, const Gemm g, const Sched& S, const Epi& E) {
;     ...
;             PG8_LDA(At, 0, 1); PG8_STAGE(PG8_SB(0, 0), b2, voffB); PG8_STAGE(PG8_SB(0, 1), b2 + hstep, voffB); PG8_STAGE(PG8_SA(0, 0), a2, voffA);
;             PG8_WAIT_V(8); PG8_WAIT_L(0); PG8_BAR; PG8_MMA(1, 0, At, B0); PG8_MMA(1, 1, At, B1); PG8_BAR; PG8_SCHED;
;             PG8_LDB(B0, 1, 0); PG8_LDB(B1, 1, 1); PG8_SCHED; PG8_LDA(At, 1, 0); PG8_STAGE(PG8_SA(0, 1), a2 + hstep, voffA);
	s_add_u32 s98, s22, 0x80
	s_addc_u32 s99, s23, 0
	s_add_u32 s100, s24, 0x80
	s_addc_u32 s101, s25, 0
	s_add_i32 s56, s43, s28
	s_mov_b32 m0, s56
	ds_read_b128 v[198:201], v168 offset:16384
	ds_read_b128 v[202:205], v168 offset:17408
	ds_read_b128 v[206:209], v168 offset:18432
	ds_read_b128 v[210:213], v168 offset:19456
	ds_read_b128 v[214:217], v168 offset:20480
	ds_read_b128 v[218:221], v168 offset:21504
	ds_read_b128 v[222:225], v168 offset:22528
	ds_read_b128 v[226:229], v168 offset:23552
	global_load_lds_dwordx4 v144, s[22:23]
	s_add_i32 m0, s56, 0x2000
	s_add_u32 s56, s22, 0x160000
	s_addc_u32 s57, s23, 0
	s_add_i32 s58, s44, s28
	global_load_lds_dwordx4 v148, s[22:23]
	s_mov_b32 m0, s58
	s_nop 0
	global_load_lds_dwordx4 v144, s[56:57]
	s_add_i32 m0, s58, 0x2000
	s_nop 0
	global_load_lds_dwordx4 v148, s[56:57]
	s_mov_b32 m0, s29
	s_nop 0
	global_load_lds_dwordx4 v142, s[24:25]
	s_mov_b32 m0, s30
	s_nop 0
	global_load_lds_dwordx4 v146, s[24:25]
	s_waitcnt vmcnt(8)
	s_waitcnt lgkmcnt(0)
	s_barrier
	s_waitcnt lgkmcnt(0)
	v_mfma_f32_16x16x32_bf16 v[60:63], v[128:131], v[198:201], v[60:63]
	v_mfma_f32_16x16x32_bf16 v[60:63], v[132:135], v[202:205], v[60:63]
	v_mfma_f32_16x16x32_bf16 v[56:59], v[170:173], v[202:205], v[56:59]
	v_mfma_f32_16x16x32_bf16 v[56:59], v[160:163], v[198:201], v[56:59]
	v_mfma_f32_16x16x32_bf16 v[40:43], v[160:163], v[206:209], v[40:43]
	v_mfma_f32_16x16x32_bf16 v[40:43], v[170:173], v[210:213], v[40:43]
	v_mfma_f32_16x16x32_bf16 v[44:47], v[132:135], v[210:213], v[44:47]
	v_mfma_f32_16x16x32_bf16 v[44:47], v[128:131], v[206:209], v[44:47]
	v_mfma_f32_16x16x32_bf16 v[28:31], v[128:131], v[214:217], v[28:31]
	v_mfma_f32_16x16x32_bf16 v[28:31], v[132:135], v[218:221], v[28:31]
	v_mfma_f32_16x16x32_bf16 v[24:27], v[170:173], v[218:221], v[24:27]
	v_mfma_f32_16x16x32_bf16 v[24:27], v[160:163], v[214:217], v[24:27]
	v_mfma_f32_16x16x32_bf16 v[8:11], v[160:163], v[222:225], v[8:11]
	v_mfma_f32_16x16x32_bf16 v[8:11], v[170:173], v[226:229], v[8:11]
	v_mfma_f32_16x16x32_bf16 v[12:15], v[132:135], v[226:229], v[12:15]
	v_mfma_f32_16x16x32_bf16 v[12:15], v[128:131], v[222:225], v[12:15]
	v_mfma_f32_16x16x32_bf16 v[52:55], v[174:177], v[198:201], v[52:55]
	v_mfma_f32_16x16x32_bf16 v[52:55], v[186:189], v[202:205], v[52:55]
	v_mfma_f32_16x16x32_bf16 v[48:51], v[194:197], v[202:205], v[48:51]
	v_mfma_f32_16x16x32_bf16 v[48:51], v[190:193], v[198:201], v[48:51]
	v_mfma_f32_16x16x32_bf16 v[32:35], v[190:193], v[206:209], v[32:35]
	v_mfma_f32_16x16x32_bf16 v[32:35], v[194:197], v[210:213], v[32:35]
	v_mfma_f32_16x16x32_bf16 v[36:39], v[186:189], v[210:213], v[36:39]
	v_mfma_f32_16x16x32_bf16 v[36:39], v[174:177], v[206:209], v[36:39]
	v_mfma_f32_16x16x32_bf16 v[20:23], v[174:177], v[214:217], v[20:23]
	v_mfma_f32_16x16x32_bf16 v[20:23], v[186:189], v[218:221], v[20:23]
	v_mfma_f32_16x16x32_bf16 v[16:19], v[194:197], v[218:221], v[16:19]
	v_mfma_f32_16x16x32_bf16 v[16:19], v[190:193], v[214:217], v[16:19]
	v_mfma_f32_16x16x32_bf16 v[0:3], v[190:193], v[222:225], v[0:3]
	v_mfma_f32_16x16x32_bf16 v[0:3], v[194:197], v[226:229], v[0:3]
	v_mfma_f32_16x16x32_bf16 v[4:7], v[186:189], v[226:229], v[4:7]
	v_mfma_f32_16x16x32_bf16 v[4:7], v[174:177], v[222:225], v[4:7]
	s_barrier
	s_add_i32 s56, 0, 0x18000
	v_add_u32_e32 v169, s56, v164
	s_add_i32 s57, 0, 0x1c000
	ds_read_b128 v[128:131], v169
	ds_read_b128 v[132:135], v169 offset:1024
	ds_read_b128 v[160:163], v169 offset:2048
	ds_read_b128 v[170:173], v169 offset:3072
	v_add_u32_e32 v169, s57, v164
	ds_read_b128 v[174:177], v169
	ds_read_b128 v[186:189], v169 offset:1024
	ds_read_b128 v[190:193], v169 offset:2048
	ds_read_b128 v[194:197], v169 offset:3072
	s_add_u32 s24, s24, 0x160000
	s_addc_u32 s25, s25, 0
	s_mov_b32 m0, s31
	ds_read_b128 v[198:201], v168 offset:32768
	ds_read_b128 v[202:205], v168 offset:33792
	ds_read_b128 v[206:209], v168 offset:34816
	ds_read_b128 v[210:213], v168 offset:35840
	ds_read_b128 v[214:217], v168 offset:36864
	ds_read_b128 v[218:221], v168 offset:37888
	ds_read_b128 v[222:225], v168 offset:38912
	ds_read_b128 v[226:229], v168 offset:39936
	global_load_lds_dwordx4 v142, s[24:25]
	s_mov_b32 m0, s33
	s_nop 0
	global_load_lds_dwordx4 v146, s[24:25]
	s_waitcnt vmcnt(8)
	s_waitcnt lgkmcnt(0)
	s_barrier
; #define PG8_STAGE(bufoff, gbase, voff) do { _Pragma("unroll") for (int _i = 0; _i < 2; ++_i) \
;         __builtin_amdgcn_global_load_lds((const unsigned*)((const char*)(gbase) + (voff)[_i]), (PG8_LAS unsigned*)(lds + (bufoff) + ldsw + _i * 8192), 16, 0, 0); } while (0)
; #define PG8_LDA(dst, b, h) do { _Pragma("unroll") for (int m = 0; m < 4; ++m) _Pragma("unroll") for (int k = 0; k < 2; ++k) dst[m][k] = *(const PG8_LAS bf16x8*)(lds + PG8_SA(b, h) + aoff + m * 2048 + k * 1024); } while (0)
; #define PG8_LDB(dst, b, h) do { _Pragma("unroll") for (int n = 0; n < 2; ++n) _Pragma("unroll") for (int k = 0; k < 2; ++k) dst[n][k] = *(const PG8_LAS bf16x8*)(lds + PG8_SB(b, h) + boff + n * 2048 + k * 1024); } while (0)
; #define PG8_MMA(ai, bj, At, Bt) do { __builtin_amdgcn_s_setprio(1); _Pragma("unroll") for (int m = 0; m < 4; ++m) _Pragma("unroll") for (int n = 0; n < 2; ++n) _Pragma("unroll") for (int k = 0; k < 2; ++k) \
;         acc[ai][bj][m][n] = __builtin_amdgcn_mfma_f32_16x16x32_bf16(Bt[n][k], At[m][k], acc[ai][bj][m][n], 0, 0, 0); __builtin_amdgcn_s_setprio(0); } while (0)
; #define PG8_WAIT_V(n) asm volatile("s_waitcnt vmcnt(" #n ")" ::: "memory")
; #define PG8_WAIT_L(n) asm volatile("s_waitcnt lgkmcnt(" #n ")" ::: "memory")
; #define PG8_BAR __builtin_amdgcn_s_barrier()
; #define PG8_SCHED __builtin_amdgcn_sched_barrier(0)
; template <class Epi, class Sched, bool ALIGN_EPI = false, bool SP2 = false>
; __device__ __forceinline__ void gemm_phase(PG8_LAS unsigned char* lds, const Gemm g, const Sched& S, const Epi& E) {
;     ...
;             PG8_LDB(B0, 1, 0); PG8_LDB(B1, 1, 1); PG8_SCHED; PG8_LDA(At, 1, 0); PG8_STAGE(PG8_SA(0, 1), a2 + hstep, voffA);
;             PG8_WAIT_V(8); PG8_WAIT_L(0); PG8_BAR; PG8_MMA(0, 0, At, B0); PG8_MMA(0, 1, At, B1); PG8_BAR; PG8_SCHED;
;             PG8_LDA(At, 1, 1); PG8_STAGE(PG8_SB(1, 0), b3, voffB); PG8_STAGE(PG8_SB(1, 1), b3 + hstep, voffB); PG8_STAGE(PG8_SA(1, 0), a3, voffA);
;             PG8_WAIT_V(8); PG8_WAIT_L(0); PG8_BAR; PG8_MMA(1, 0, At, B0); PG8_MMA(1, 1, At, B1); PG8_BAR; PG8_SCHED;
;     ...
;         if constexpr (ALIGN_EPI) { if (wr == 0) PG8_BAR; }
	s_waitcnt lgkmcnt(0)
	v_mfma_f32_16x16x32_bf16 v[124:127], v[128:131], v[198:201], v[124:127]
	v_mfma_f32_16x16x32_bf16 v[124:127], v[132:135], v[202:205], v[124:127]
	v_mfma_f32_16x16x32_bf16 v[120:123], v[170:173], v[202:205], v[120:123]
	v_mfma_f32_16x16x32_bf16 v[120:123], v[160:163], v[198:201], v[120:123]
	v_mfma_f32_16x16x32_bf16 v[104:107], v[160:163], v[206:209], v[104:107]
	v_mfma_f32_16x16x32_bf16 v[104:107], v[170:173], v[210:213], v[104:107]
	v_mfma_f32_16x16x32_bf16 v[108:111], v[132:135], v[210:213], v[108:111]
	v_mfma_f32_16x16x32_bf16 v[108:111], v[128:131], v[206:209], v[108:111]
	v_mfma_f32_16x16x32_bf16 v[92:95], v[128:131], v[214:217], v[92:95]
	v_mfma_f32_16x16x32_bf16 v[92:95], v[132:135], v[218:221], v[92:95]
	v_mfma_f32_16x16x32_bf16 v[88:91], v[170:173], v[218:221], v[88:91]
	v_mfma_f32_16x16x32_bf16 v[88:91], v[160:163], v[214:217], v[88:91]
	v_mfma_f32_16x16x32_bf16 v[72:75], v[160:163], v[222:225], v[72:75]
	v_mfma_f32_16x16x32_bf16 v[72:75], v[170:173], v[226:229], v[72:75]
	v_mfma_f32_16x16x32_bf16 v[76:79], v[132:135], v[226:229], v[76:79]
	v_mfma_f32_16x16x32_bf16 v[76:79], v[128:131], v[222:225], v[76:79]
	v_mfma_f32_16x16x32_bf16 v[116:119], v[174:177], v[198:201], v[116:119]
	v_mfma_f32_16x16x32_bf16 v[116:119], v[186:189], v[202:205], v[116:119]
	v_mfma_f32_16x16x32_bf16 v[112:115], v[194:197], v[202:205], v[112:115]
	v_mfma_f32_16x16x32_bf16 v[112:115], v[190:193], v[198:201], v[112:115]
	v_mfma_f32_16x16x32_bf16 v[96:99], v[190:193], v[206:209], v[96:99]
	v_mfma_f32_16x16x32_bf16 v[96:99], v[194:197], v[210:213], v[96:99]
	v_mfma_f32_16x16x32_bf16 v[100:103], v[186:189], v[210:213], v[100:103]
	v_mfma_f32_16x16x32_bf16 v[100:103], v[174:177], v[206:209], v[100:103]
	v_mfma_f32_16x16x32_bf16 v[84:87], v[174:177], v[214:217], v[84:87]
	v_mfma_f32_16x16x32_bf16 v[84:87], v[186:189], v[218:221], v[84:87]
	v_mfma_f32_16x16x32_bf16 v[80:83], v[194:197], v[218:221], v[80:83]
	v_mfma_f32_16x16x32_bf16 v[80:83], v[190:193], v[214:217], v[80:83]
	v_mfma_f32_16x16x32_bf16 v[64:67], v[190:193], v[222:225], v[64:67]
	v_mfma_f32_16x16x32_bf16 v[64:67], v[194:197], v[226:229], v[64:67]
	v_mfma_f32_16x16x32_bf16 v[68:71], v[186:189], v[226:229], v[68:71]
	v_mfma_f32_16x16x32_bf16 v[68:71], v[174:177], v[222:225], v[68:71]
	s_barrier
	s_add_i32 s24, s56, s28
	s_mov_b32 m0, s24
	ds_read_b128 v[198:201], v168 offset:49152
	ds_read_b128 v[202:205], v168 offset:50176
	ds_read_b128 v[206:209], v168 offset:51200
	ds_read_b128 v[210:213], v168 offset:52224
	ds_read_b128 v[214:217], v168 offset:53248
	ds_read_b128 v[218:221], v168 offset:54272
	ds_read_b128 v[222:225], v168 offset:55296
	ds_read_b128 v[226:229], v168 offset:56320
	global_load_lds_dwordx4 v144, s[98:99]
	s_add_i32 m0, s24, 0x2000
	s_add_u32 s22, s22, 0x160080
	s_addc_u32 s23, s23, 0
	s_add_i32 s24, s57, s28
	global_load_lds_dwordx4 v148, s[98:99]
	s_mov_b32 m0, s24
	s_nop 0
	global_load_lds_dwordx4 v144, s[22:23]
	s_add_i32 m0, s24, 0x2000
	s_nop 0
	global_load_lds_dwordx4 v148, s[22:23]
	s_mov_b32 m0, s38
	s_nop 0
	global_load_lds_dwordx4 v142, s[100:101]
	s_mov_b32 m0, s39
	s_nop 0
	global_load_lds_dwordx4 v146, s[100:101]
	s_waitcnt vmcnt(8)
	s_waitcnt lgkmcnt(0)
	s_barrier
	s_waitcnt lgkmcnt(0)
	v_mfma_f32_16x16x32_bf16 v[60:63], v[128:131], v[198:201], v[60:63]
	v_mfma_f32_16x16x32_bf16 v[60:63], v[132:135], v[202:205], v[60:63]
	v_mfma_f32_16x16x32_bf16 v[56:59], v[170:173], v[202:205], v[56:59]
	v_mfma_f32_16x16x32_bf16 v[56:59], v[160:163], v[198:201], v[56:59]
	v_mfma_f32_16x16x32_bf16 v[40:43], v[160:163], v[206:209], v[40:43]
	v_mfma_f32_16x16x32_bf16 v[40:43], v[170:173], v[210:213], v[40:43]
	v_mfma_f32_16x16x32_bf16 v[44:47], v[132:135], v[210:213], v[44:47]
	v_mfma_f32_16x16x32_bf16 v[44:47], v[128:131], v[206:209], v[44:47]
	v_mfma_f32_16x16x32_bf16 v[28:31], v[128:131], v[214:217], v[28:31]
	v_mfma_f32_16x16x32_bf16 v[28:31], v[132:135], v[218:221], v[28:31]
	v_mfma_f32_16x16x32_bf16 v[24:27], v[170:173], v[218:221], v[24:27]
	v_mfma_f32_16x16x32_bf16 v[24:27], v[160:163], v[214:217], v[24:27]
	v_mfma_f32_16x16x32_bf16 v[8:11], v[160:163], v[222:225], v[8:11]
	v_mfma_f32_16x16x32_bf16 v[8:11], v[170:173], v[226:229], v[8:11]
	v_mfma_f32_16x16x32_bf16 v[12:15], v[132:135], v[226:229], v[12:15]
	v_mfma_f32_16x16x32_bf16 v[12:15], v[128:131], v[222:225], v[12:15]
	v_mfma_f32_16x16x32_bf16 v[52:55], v[174:177], v[198:201], v[52:55]
	v_mfma_f32_16x16x32_bf16 v[52:55], v[186:189], v[202:205], v[52:55]
	v_mfma_f32_16x16x32_bf16 v[48:51], v[194:197], v[202:205], v[48:51]
	v_mfma_f32_16x16x32_bf16 v[48:51], v[190:193], v[198:201], v[48:51]
	v_mfma_f32_16x16x32_bf16 v[32:35], v[190:193], v[206:209], v[32:35]
	v_mfma_f32_16x16x32_bf16 v[32:35], v[194:197], v[210:213], v[32:35]
	v_mfma_f32_16x16x32_bf16 v[36:39], v[186:189], v[210:213], v[36:39]
	v_mfma_f32_16x16x32_bf16 v[36:39], v[174:177], v[206:209], v[36:39]
	v_mfma_f32_16x16x32_bf16 v[20:23], v[174:177], v[214:217], v[20:23]
	v_mfma_f32_16x16x32_bf16 v[20:23], v[186:189], v[218:221], v[20:23]
	v_mfma_f32_16x16x32_bf16 v[16:19], v[194:197], v[218:221], v[16:19]
	v_mfma_f32_16x16x32_bf16 v[16:19], v[190:193], v[214:217], v[16:19]
	v_mfma_f32_16x16x32_bf16 v[0:3], v[190:193], v[222:225], v[0:3]
	v_mfma_f32_16x16x32_bf16 v[0:3], v[194:197], v[226:229], v[0:3]
	v_mfma_f32_16x16x32_bf16 v[4:7], v[186:189], v[226:229], v[4:7]
	v_mfma_f32_16x16x32_bf16 v[4:7], v[174:177], v[222:225], v[4:7]
	s_barrier
	s_add_i32 s55, s55, 2
	s_add_u32 s20, s20, 0x100
	s_addc_u32 s21, s21, 0
	s_add_u32 s53, s53, 0x100
	s_addc_u32 s54, s54, 0
	s_cmpk_gt_u32 s55, 0x55
	s_cbranch_scc0 .LBB0_1361
	s_setprio 0
	s_and_b64 vcc, exec, s[16:17]
	s_cbranch_vccz .LBB0_1364
	s_barrier
